# GEMM EpiRes epilogues (out-proj, MLP2 x2, b_out): residual loads issued three row-groups ahead with counted vmcnt instead of load-wait-store chain
# speedup vs baseline: 1.0189x; 1.0189x over previous
.LBB0_368:
	ds_read_b128 v[144:147], v149
	ds_read_b128 v[152:155], v149 offset:1024
	ds_read_b128 v[156:159], v149 offset:2048
	ds_read_b128 v[160:163], v149 offset:3072
	s_add_u32 s70, s68, 0x100
	s_addc_u32 s71, s69, 0
	s_cmp_eq_u32 s77, 12
	s_cselect_b32 s75, s19, s71
	s_cselect_b32 s74, s55, s70
	s_cselect_b32 s73, s17, s76
	s_cselect_b32 s72, s57, s67
	v_lshl_add_u64 v[196:197], s[68:69], 0, v[134:135]
	s_add_i32 m0, s26, 0xc000
	ds_read_b128 v[164:167], v150
	ds_read_b128 v[168:171], v150 offset:1024
	ds_read_b128 v[172:175], v150 offset:2048
	ds_read_b128 v[176:179], v150 offset:3072
	ds_read_b128 v[180:183], v150 offset:4096
	ds_read_b128 v[184:187], v150 offset:5120
	ds_read_b128 v[188:191], v150 offset:6144
	ds_read_b128 v[192:195], v150 offset:7168
	global_load_lds_dwordx4 v[196:197], off
	v_lshl_add_u64 v[196:197], s[68:69], 0, v[138:139]
	s_add_i32 m0, s26, 0xe000
	s_nop 0
	global_load_lds_dwordx4 v[196:197], off
	s_waitcnt lgkmcnt(8)
	s_barrier
	s_waitcnt lgkmcnt(0)
	s_setprio 1
	s_waitcnt lgkmcnt(0)
	v_mfma_f32_16x16x32_bf16 v[124:127], v[144:147], v[164:167], v[124:127]
	v_mfma_f32_16x16x32_bf16 v[120:123], v[156:159], v[164:167], v[120:123]
	v_mfma_f32_16x16x32_bf16 v[108:111], v[144:147], v[172:175], v[108:111]
	v_mfma_f32_16x16x32_bf16 v[104:107], v[156:159], v[172:175], v[104:107]
	v_mfma_f32_16x16x32_bf16 v[92:95], v[144:147], v[180:183], v[92:95]
	v_mfma_f32_16x16x32_bf16 v[88:91], v[156:159], v[180:183], v[88:91]
	v_mfma_f32_16x16x32_bf16 v[76:79], v[144:147], v[188:191], v[76:79]
	v_mfma_f32_16x16x32_bf16 v[72:75], v[156:159], v[188:191], v[72:75]
	v_mfma_f32_16x16x32_bf16 v[124:127], v[152:155], v[168:171], v[124:127]
	v_mfma_f32_16x16x32_bf16 v[120:123], v[160:163], v[168:171], v[120:123]
	v_mfma_f32_16x16x32_bf16 v[108:111], v[152:155], v[176:179], v[108:111]
	v_mfma_f32_16x16x32_bf16 v[104:107], v[160:163], v[176:179], v[104:107]
	v_mfma_f32_16x16x32_bf16 v[92:95], v[152:155], v[184:187], v[92:95]
	v_mfma_f32_16x16x32_bf16 v[88:91], v[160:163], v[184:187], v[88:91]
	v_mfma_f32_16x16x32_bf16 v[76:79], v[152:155], v[192:195], v[76:79]
	v_mfma_f32_16x16x32_bf16 v[72:75], v[160:163], v[192:195], v[72:75]
	s_setprio 0
	s_barrier
	s_add_i32 s68, s49, s7
	v_lshl_add_u64 v[212:213], s[72:73], 0, v[128:129]
	s_mov_b32 m0, s68
	ds_read_b128 v[196:199], v151
	ds_read_b128 v[200:203], v151 offset:1024
	ds_read_b128 v[204:207], v151 offset:2048
	ds_read_b128 v[208:211], v151 offset:3072
	global_load_lds_dwordx4 v[212:213], off
	v_lshl_add_u64 v[214:215], s[72:73], 0, v[130:131]
	s_add_i32 m0, s68, 0x2000
	s_nop 0
	global_load_lds_dwordx4 v[214:215], off
	s_barrier
	s_waitcnt lgkmcnt(0)
	s_setprio 1
	s_waitcnt lgkmcnt(0)
	v_mfma_f32_16x16x32_bf16 v[116:119], v[196:199], v[164:167], v[116:119]
	v_mfma_f32_16x16x32_bf16 v[112:115], v[204:207], v[164:167], v[112:115]
	v_mfma_f32_16x16x32_bf16 v[100:103], v[196:199], v[172:175], v[100:103]
	v_mfma_f32_16x16x32_bf16 v[96:99], v[204:207], v[172:175], v[96:99]
	v_mfma_f32_16x16x32_bf16 v[84:87], v[196:199], v[180:183], v[84:87]
	v_mfma_f32_16x16x32_bf16 v[80:83], v[204:207], v[180:183], v[80:83]
	v_mfma_f32_16x16x32_bf16 v[68:71], v[196:199], v[188:191], v[68:71]
	v_mfma_f32_16x16x32_bf16 v[64:67], v[204:207], v[188:191], v[64:67]
	v_mfma_f32_16x16x32_bf16 v[116:119], v[200:203], v[168:171], v[116:119]
	v_mfma_f32_16x16x32_bf16 v[112:115], v[208:211], v[168:171], v[112:115]
	v_mfma_f32_16x16x32_bf16 v[100:103], v[200:203], v[176:179], v[100:103]
	v_mfma_f32_16x16x32_bf16 v[96:99], v[208:211], v[176:179], v[96:99]
	v_mfma_f32_16x16x32_bf16 v[84:87], v[200:203], v[184:187], v[84:87]
	v_mfma_f32_16x16x32_bf16 v[80:83], v[208:211], v[184:187], v[80:83]
	v_mfma_f32_16x16x32_bf16 v[68:71], v[200:203], v[192:195], v[68:71]
	v_mfma_f32_16x16x32_bf16 v[64:67], v[208:211], v[192:195], v[64:67]
	s_setprio 0
	s_mov_b32 m0, s26
	v_lshl_add_u64 v[216:217], s[74:75], 0, v[128:129]
	s_barrier
	ds_read_b128 v[164:167], v150 offset:16384
	ds_read_b128 v[168:171], v150 offset:17408
	ds_read_b128 v[172:175], v150 offset:18432
	ds_read_b128 v[176:179], v150 offset:19456
	ds_read_b128 v[180:183], v150 offset:20480
	ds_read_b128 v[184:187], v150 offset:21504
	ds_read_b128 v[188:191], v150 offset:22528
	ds_read_b128 v[192:195], v150 offset:23552
	global_load_lds_dwordx4 v[216:217], off
	v_lshl_add_u64 v[218:219], s[74:75], 0, v[130:131]
	s_mov_b32 m0, s27
	s_nop 0
	global_load_lds_dwordx4 v[218:219], off
	s_barrier
	s_waitcnt lgkmcnt(0)
	s_setprio 1
	s_waitcnt lgkmcnt(0)
	v_mfma_f32_16x16x32_bf16 v[60:63], v[144:147], v[164:167], v[60:63]
	v_mfma_f32_16x16x32_bf16 v[56:59], v[156:159], v[164:167], v[56:59]
	v_mfma_f32_16x16x32_bf16 v[44:47], v[144:147], v[172:175], v[44:47]
	v_mfma_f32_16x16x32_bf16 v[40:43], v[156:159], v[172:175], v[40:43]
	v_mfma_f32_16x16x32_bf16 v[28:31], v[144:147], v[180:183], v[28:31]
	v_mfma_f32_16x16x32_bf16 v[24:27], v[156:159], v[180:183], v[24:27]
	v_mfma_f32_16x16x32_bf16 v[12:15], v[144:147], v[188:191], v[12:15]
	v_mfma_f32_16x16x32_bf16 v[8:11], v[156:159], v[188:191], v[8:11]
	v_mfma_f32_16x16x32_bf16 v[60:63], v[152:155], v[168:171], v[60:63]
	v_mfma_f32_16x16x32_bf16 v[56:59], v[160:163], v[168:171], v[56:59]
	v_mfma_f32_16x16x32_bf16 v[44:47], v[152:155], v[176:179], v[44:47]
	v_mfma_f32_16x16x32_bf16 v[40:43], v[160:163], v[176:179], v[40:43]
	v_mfma_f32_16x16x32_bf16 v[28:31], v[152:155], v[184:187], v[28:31]
	v_mfma_f32_16x16x32_bf16 v[24:27], v[160:163], v[184:187], v[24:27]
	v_mfma_f32_16x16x32_bf16 v[12:15], v[152:155], v[192:195], v[12:15]
	v_mfma_f32_16x16x32_bf16 v[8:11], v[160:163], v[192:195], v[8:11]
	s_setprio 0
	s_barrier
	s_add_u32 s68, s72, 0x40000
	s_addc_u32 s69, s73, 0
	s_add_i32 s78, s56, s7
	v_lshl_add_u64 v[144:145], s[68:69], 0, v[128:129]
	s_mov_b32 m0, s78
	s_nop 0
	global_load_lds_dwordx4 v[144:145], off
	v_lshl_add_u64 v[144:145], s[68:69], 0, v[130:131]
	s_add_i32 m0, s78, 0x2000
	s_nop 0
	global_load_lds_dwordx4 v[144:145], off
	s_waitcnt vmcnt(6)
	s_barrier
	s_setprio 1
	v_mfma_f32_16x16x32_bf16 v[52:55], v[196:199], v[164:167], v[52:55]
	v_mfma_f32_16x16x32_bf16 v[48:51], v[204:207], v[164:167], v[48:51]
	v_mfma_f32_16x16x32_bf16 v[36:39], v[196:199], v[172:175], v[36:39]
	v_mfma_f32_16x16x32_bf16 v[32:35], v[204:207], v[172:175], v[32:35]
	v_mfma_f32_16x16x32_bf16 v[20:23], v[196:199], v[180:183], v[20:23]
	v_mfma_f32_16x16x32_bf16 v[16:19], v[204:207], v[180:183], v[16:19]
	v_mfma_f32_16x16x32_bf16 v[4:7], v[196:199], v[188:191], v[4:7]
	v_mfma_f32_16x16x32_bf16 v[0:3], v[204:207], v[188:191], v[0:3]
	v_mfma_f32_16x16x32_bf16 v[52:55], v[200:203], v[168:171], v[52:55]
	v_mfma_f32_16x16x32_bf16 v[48:51], v[208:211], v[168:171], v[48:51]
	v_mfma_f32_16x16x32_bf16 v[36:39], v[200:203], v[176:179], v[36:39]
	v_mfma_f32_16x16x32_bf16 v[32:35], v[208:211], v[176:179], v[32:35]
	v_mfma_f32_16x16x32_bf16 v[20:23], v[200:203], v[184:187], v[20:23]
	v_mfma_f32_16x16x32_bf16 v[16:19], v[208:211], v[184:187], v[16:19]
	v_mfma_f32_16x16x32_bf16 v[4:7], v[200:203], v[192:195], v[4:7]
	v_mfma_f32_16x16x32_bf16 v[0:3], v[208:211], v[192:195], v[0:3]
	s_setprio 0
	s_add_i32 s78, 16, 0x18000
	v_add_u32_e32 v160, s78, v148
	s_barrier
	ds_read_b128 v[144:147], v160
	ds_read_b128 v[152:155], v160 offset:1024
	ds_read_b128 v[156:159], v160 offset:2048
	ds_read_b128 v[160:163], v160 offset:3072
	s_add_u32 s68, s74, 0x40000
	s_addc_u32 s69, s75, 0
	s_mov_b32 m0, s39
	v_lshl_add_u64 v[196:197], s[68:69], 0, v[128:129]
	ds_read_b128 v[164:167], v150 offset:32768
	ds_read_b128 v[168:171], v150 offset:33792
	ds_read_b128 v[172:175], v150 offset:34816
	ds_read_b128 v[176:179], v150 offset:35840
	ds_read_b128 v[180:183], v150 offset:36864
	ds_read_b128 v[184:187], v150 offset:37888
	ds_read_b128 v[188:191], v150 offset:38912
	ds_read_b128 v[192:195], v150 offset:39936
	global_load_lds_dwordx4 v[196:197], off
	v_lshl_add_u64 v[196:197], s[68:69], 0, v[130:131]
	s_mov_b32 m0, s44
	s_nop 0
	global_load_lds_dwordx4 v[196:197], off
	s_waitcnt lgkmcnt(8)
	s_barrier
	s_waitcnt lgkmcnt(0)
	s_setprio 1
	s_waitcnt lgkmcnt(0)
	v_mfma_f32_16x16x32_bf16 v[124:127], v[144:147], v[164:167], v[124:127]
	v_mfma_f32_16x16x32_bf16 v[120:123], v[156:159], v[164:167], v[120:123]
	v_mfma_f32_16x16x32_bf16 v[108:111], v[144:147], v[172:175], v[108:111]
	v_mfma_f32_16x16x32_bf16 v[104:107], v[156:159], v[172:175], v[104:107]
	v_mfma_f32_16x16x32_bf16 v[92:95], v[144:147], v[180:183], v[92:95]
	v_mfma_f32_16x16x32_bf16 v[88:91], v[156:159], v[180:183], v[88:91]
	v_mfma_f32_16x16x32_bf16 v[76:79], v[144:147], v[188:191], v[76:79]
	v_mfma_f32_16x16x32_bf16 v[72:75], v[156:159], v[188:191], v[72:75]
	v_mfma_f32_16x16x32_bf16 v[124:127], v[152:155], v[168:171], v[124:127]
	v_mfma_f32_16x16x32_bf16 v[120:123], v[160:163], v[168:171], v[120:123]
	v_mfma_f32_16x16x32_bf16 v[108:111], v[152:155], v[176:179], v[108:111]
	v_mfma_f32_16x16x32_bf16 v[104:107], v[160:163], v[176:179], v[104:107]
	v_mfma_f32_16x16x32_bf16 v[92:95], v[152:155], v[184:187], v[92:95]
	v_mfma_f32_16x16x32_bf16 v[88:91], v[160:163], v[184:187], v[88:91]
	v_mfma_f32_16x16x32_bf16 v[76:79], v[152:155], v[192:195], v[76:79]
	v_mfma_f32_16x16x32_bf16 v[72:75], v[160:163], v[192:195], v[72:75]
	s_setprio 0
	s_barrier
	s_add_i32 s74, 16, 0x1c000
	s_add_i32 s68, s78, s7
	v_add_u32_e32 v208, s74, v148
	v_lshl_add_u64 v[212:213], v[212:213], 0, s[14:15]
	s_mov_b32 m0, s68
	ds_read_b128 v[196:199], v208
	ds_read_b128 v[200:203], v208 offset:1024
	ds_read_b128 v[204:207], v208 offset:2048
	ds_read_b128 v[208:211], v208 offset:3072
	global_load_lds_dwordx4 v[212:213], off
	v_lshl_add_u64 v[212:213], v[214:215], 0, s[14:15]
	s_add_i32 m0, s68, 0x2000
	s_nop 0
	global_load_lds_dwordx4 v[212:213], off
	s_barrier
	s_waitcnt lgkmcnt(0)
	s_setprio 1
	s_waitcnt lgkmcnt(0)
	v_mfma_f32_16x16x32_bf16 v[116:119], v[196:199], v[164:167], v[116:119]
	v_mfma_f32_16x16x32_bf16 v[112:115], v[204:207], v[164:167], v[112:115]
	v_mfma_f32_16x16x32_bf16 v[100:103], v[196:199], v[172:175], v[100:103]
	v_mfma_f32_16x16x32_bf16 v[96:99], v[204:207], v[172:175], v[96:99]
	v_mfma_f32_16x16x32_bf16 v[84:87], v[196:199], v[180:183], v[84:87]
	v_mfma_f32_16x16x32_bf16 v[80:83], v[204:207], v[180:183], v[80:83]
	v_mfma_f32_16x16x32_bf16 v[68:71], v[196:199], v[188:191], v[68:71]
	v_mfma_f32_16x16x32_bf16 v[64:67], v[204:207], v[188:191], v[64:67]
	v_mfma_f32_16x16x32_bf16 v[116:119], v[200:203], v[168:171], v[116:119]
	v_mfma_f32_16x16x32_bf16 v[112:115], v[208:211], v[168:171], v[112:115]
	v_mfma_f32_16x16x32_bf16 v[100:103], v[200:203], v[176:179], v[100:103]
	v_mfma_f32_16x16x32_bf16 v[96:99], v[208:211], v[176:179], v[96:99]
	v_mfma_f32_16x16x32_bf16 v[84:87], v[200:203], v[184:187], v[84:87]
	v_mfma_f32_16x16x32_bf16 v[80:83], v[208:211], v[184:187], v[80:83]
	v_mfma_f32_16x16x32_bf16 v[68:71], v[200:203], v[192:195], v[68:71]
	v_mfma_f32_16x16x32_bf16 v[64:67], v[208:211], v[192:195], v[64:67]
	s_setprio 0
	s_mov_b32 m0, s45
	v_lshl_add_u64 v[212:213], v[216:217], 0, s[14:15]
	s_barrier
	ds_read_b128 v[164:167], v150 offset:49152
	ds_read_b128 v[168:171], v150 offset:50176
	ds_read_b128 v[172:175], v150 offset:51200
	ds_read_b128 v[176:179], v150 offset:52224
	ds_read_b128 v[180:183], v150 offset:53248
	ds_read_b128 v[184:187], v150 offset:54272
	ds_read_b128 v[188:191], v150 offset:55296
	ds_read_b128 v[192:195], v150 offset:56320
	global_load_lds_dwordx4 v[212:213], off
	v_lshl_add_u64 v[212:213], v[218:219], 0, s[14:15]
	s_mov_b32 m0, s46
	s_nop 0
	global_load_lds_dwordx4 v[212:213], off
	s_barrier
	s_waitcnt lgkmcnt(0)
	s_setprio 1
	s_waitcnt lgkmcnt(0)
	v_mfma_f32_16x16x32_bf16 v[60:63], v[144:147], v[164:167], v[60:63]
	v_mfma_f32_16x16x32_bf16 v[56:59], v[156:159], v[164:167], v[56:59]
	v_mfma_f32_16x16x32_bf16 v[44:47], v[144:147], v[172:175], v[44:47]
	v_mfma_f32_16x16x32_bf16 v[40:43], v[156:159], v[172:175], v[40:43]
	v_mfma_f32_16x16x32_bf16 v[28:31], v[144:147], v[180:183], v[28:31]
	v_mfma_f32_16x16x32_bf16 v[24:27], v[156:159], v[180:183], v[24:27]
	v_mfma_f32_16x16x32_bf16 v[12:15], v[144:147], v[188:191], v[12:15]
	v_mfma_f32_16x16x32_bf16 v[8:11], v[156:159], v[188:191], v[8:11]
	v_mfma_f32_16x16x32_bf16 v[60:63], v[152:155], v[168:171], v[60:63]
	v_mfma_f32_16x16x32_bf16 v[56:59], v[160:163], v[168:171], v[56:59]
	v_mfma_f32_16x16x32_bf16 v[44:47], v[152:155], v[176:179], v[44:47]
	v_mfma_f32_16x16x32_bf16 v[40:43], v[160:163], v[176:179], v[40:43]
	v_mfma_f32_16x16x32_bf16 v[28:31], v[152:155], v[184:187], v[28:31]
	v_mfma_f32_16x16x32_bf16 v[24:27], v[160:163], v[184:187], v[24:27]
	v_mfma_f32_16x16x32_bf16 v[12:15], v[152:155], v[192:195], v[12:15]
	v_mfma_f32_16x16x32_bf16 v[8:11], v[160:163], v[192:195], v[8:11]
	s_setprio 0
	s_barrier
	s_add_u32 s68, s72, 0x40080
	s_addc_u32 s69, s73, 0
	s_add_i32 s72, s74, s7
	v_lshl_add_u64 v[144:145], s[68:69], 0, v[128:129]
	s_mov_b32 m0, s72
	s_nop 0
	global_load_lds_dwordx4 v[144:145], off
	v_lshl_add_u64 v[144:145], s[68:69], 0, v[130:131]
	s_add_i32 m0, s72, 0x2000
	s_nop 0
	global_load_lds_dwordx4 v[144:145], off
	s_waitcnt vmcnt(6)
	s_barrier
	s_setprio 1
	v_mfma_f32_16x16x32_bf16 v[52:55], v[196:199], v[164:167], v[52:55]
	v_mfma_f32_16x16x32_bf16 v[48:51], v[204:207], v[164:167], v[48:51]
	v_mfma_f32_16x16x32_bf16 v[36:39], v[196:199], v[172:175], v[36:39]
	v_mfma_f32_16x16x32_bf16 v[32:35], v[204:207], v[172:175], v[32:35]
	v_mfma_f32_16x16x32_bf16 v[20:23], v[196:199], v[180:183], v[20:23]
	v_mfma_f32_16x16x32_bf16 v[16:19], v[204:207], v[180:183], v[16:19]
	v_mfma_f32_16x16x32_bf16 v[4:7], v[196:199], v[188:191], v[4:7]
	v_mfma_f32_16x16x32_bf16 v[0:3], v[204:207], v[188:191], v[0:3]
	v_mfma_f32_16x16x32_bf16 v[52:55], v[200:203], v[168:171], v[52:55]
	v_mfma_f32_16x16x32_bf16 v[48:51], v[208:211], v[168:171], v[48:51]
	v_mfma_f32_16x16x32_bf16 v[36:39], v[200:203], v[176:179], v[36:39]
	v_mfma_f32_16x16x32_bf16 v[32:35], v[208:211], v[176:179], v[32:35]
	v_mfma_f32_16x16x32_bf16 v[20:23], v[200:203], v[184:187], v[20:23]
	v_mfma_f32_16x16x32_bf16 v[16:19], v[208:211], v[184:187], v[16:19]
	v_mfma_f32_16x16x32_bf16 v[4:7], v[200:203], v[192:195], v[4:7]
	v_mfma_f32_16x16x32_bf16 v[0:3], v[208:211], v[192:195], v[0:3]
	s_setprio 0
	s_add_i32 s77, s77, 2
	s_add_u32 s67, s67, 0x100
	s_addc_u32 s76, s76, 0
	s_cmp_gt_u32 s77, 13
	s_mov_b64 s[68:69], s[70:71]
	s_barrier
	s_cbranch_scc0 .LBB0_368
	v_lshl_add_u32 v146, s54, 8, v133
	s_lshl_b32 s17, s66, 8
	s_ashr_i32 s19, s17, 31
	v_ashrrev_i32_e32 v147, 31, v146
	v_mov_b32_e32 v145, s19
	v_or_b32_e32 v144, s17, v132
	v_mov_b32_e32 v212, v146
	v_mov_b32_e32 v213, v147
	v_lshlrev_b64 v[214:215], 11, v[212:213]
	v_lshl_add_u64 v[214:215], v[214:215], 0, v[144:145]
	v_lshl_add_u64 v[152:153], v[214:215], 2, s[20:21]
	global_load_dwordx4 v[164:167], v[152:153], off
	global_load_dwordx4 v[168:171], v[152:153], off offset:64
	global_load_dwordx4 v[172:175], v[152:153], off offset:512
	global_load_dwordx4 v[176:179], v[152:153], off offset:576
	v_add_u32_e32 v212, 0x10, v146
	v_mov_b32_e32 v213, v147
	v_lshlrev_b64 v[214:215], 11, v[212:213]
	v_lshl_add_u64 v[214:215], v[214:215], 0, v[144:145]
	v_lshl_add_u64 v[152:153], v[214:215], 2, s[20:21]
	global_load_dwordx4 v[180:183], v[152:153], off
	global_load_dwordx4 v[184:187], v[152:153], off offset:64
	global_load_dwordx4 v[188:191], v[152:153], off offset:512
	global_load_dwordx4 v[192:195], v[152:153], off offset:576
	v_add_u32_e32 v212, 0x20, v146
	v_mov_b32_e32 v213, v147
	v_lshlrev_b64 v[214:215], 11, v[212:213]
	v_lshl_add_u64 v[214:215], v[214:215], 0, v[144:145]
	v_lshl_add_u64 v[152:153], v[214:215], 2, s[20:21]
	global_load_dwordx4 v[196:199], v[152:153], off
	global_load_dwordx4 v[200:203], v[152:153], off offset:64
	global_load_dwordx4 v[204:207], v[152:153], off offset:512
	global_load_dwordx4 v[208:211], v[152:153], off offset:576
	s_waitcnt vmcnt(8)
	v_mov_b32_e32 v212, v146
	v_mov_b32_e32 v213, v147
	v_lshlrev_b64 v[214:215], 11, v[212:213]
	v_lshl_add_u64 v[214:215], v[214:215], 0, v[144:145]
	v_lshl_add_u64 v[154:155], v[214:215], 2, s[28:29]
	v_lshl_add_u64 v[156:157], v[214:215], 1, s[40:41]
	v_pk_add_f32 v[126:127], v[126:127], v[166:167]
	v_pk_add_f32 v[124:125], v[124:125], v[164:165]
	v_cvt_pk_bf16_f32 v159, v126, v127
	v_cvt_pk_bf16_f32 v158, v124, v125
	global_store_dwordx4 v[154:155], v[124:127], off
	global_store_dwordx2 v[156:157], v[158:159], off
	s_nop 0
	v_mul_f32_e32 v125, v125, v125
	v_mul_f32_e32 v127, v127, v127
	v_fmac_f32_e32 v125, v124, v124
	v_fmac_f32_e32 v127, v126, v126
	v_add_f32_e32 v160, v125, v127
	v_pk_add_f32 v[122:123], v[122:123], v[170:171]
	v_pk_add_f32 v[120:121], v[120:121], v[168:169]
	v_cvt_pk_bf16_f32 v159, v122, v123
	v_cvt_pk_bf16_f32 v158, v120, v121
	global_store_dwordx4 v[154:155], v[120:123], off offset:64
	global_store_dwordx2 v[156:157], v[158:159], off offset:32
	s_nop 0
	v_mul_f32_e32 v121, v121, v121
	v_mul_f32_e32 v123, v123, v123
	v_fmac_f32_e32 v121, v120, v120
	v_fmac_f32_e32 v123, v122, v122
	v_add_f32_e32 v120, v121, v123
	v_add_f32_e32 v160, v160, v120
	v_pk_add_f32 v[118:119], v[118:119], v[174:175]
	v_pk_add_f32 v[116:117], v[116:117], v[172:173]
	v_cvt_pk_bf16_f32 v159, v118, v119
	v_cvt_pk_bf16_f32 v158, v116, v117
	global_store_dwordx4 v[154:155], v[116:119], off offset:512
	global_store_dwordx2 v[156:157], v[158:159], off offset:256
	s_nop 0
	v_mul_f32_e32 v117, v117, v117
	v_mul_f32_e32 v119, v119, v119
	v_fmac_f32_e32 v117, v116, v116
	v_fmac_f32_e32 v119, v118, v118
	v_add_f32_e32 v116, v117, v119
	v_add_f32_e32 v160, v160, v116
	v_pk_add_f32 v[114:115], v[114:115], v[178:179]
	v_pk_add_f32 v[112:113], v[112:113], v[176:177]
	v_cvt_pk_bf16_f32 v159, v114, v115
	v_cvt_pk_bf16_f32 v158, v112, v113
	global_store_dwordx4 v[154:155], v[112:115], off offset:576
	global_store_dwordx2 v[156:157], v[158:159], off offset:288
	s_nop 0
	v_mul_f32_e32 v113, v113, v113
	v_mul_f32_e32 v115, v115, v115
	v_fmac_f32_e32 v113, v112, v112
	v_fmac_f32_e32 v115, v114, v114
	v_add_f32_e32 v112, v113, v115
	v_add_f32_e32 v160, v160, v112
	v_mov_b32_e32 v161, v160
	s_nop 1
	v_permlane16_swap_b32_e32 v160, v161
	v_add_f32_e32 v160, v160, v161
	v_mov_b32_e32 v161, v160
	s_nop 1
	v_permlane32_swap_b32_e32 v160, v161
	s_and_saveexec_b64 s[54:55], s[8:9]
	v_lshl_add_u64 v[162:163], v[212:213], 2, s[64:65]
	v_add_f32_e32 v160, v160, v161
	global_atomic_add_f32 v[162:163], v160, off
	s_or_b64 exec, exec, s[54:55]
	v_add_u32_e32 v212, 0x30, v146
	v_mov_b32_e32 v213, v147
	v_lshlrev_b64 v[214:215], 11, v[212:213]
	v_lshl_add_u64 v[214:215], v[214:215], 0, v[144:145]
	v_lshl_add_u64 v[152:153], v[214:215], 2, s[20:21]
	global_load_dwordx4 v[164:167], v[152:153], off
	global_load_dwordx4 v[168:171], v[152:153], off offset:64
	global_load_dwordx4 v[172:175], v[152:153], off offset:512
	global_load_dwordx4 v[176:179], v[152:153], off offset:576
	s_waitcnt vmcnt(17)
	v_add_u32_e32 v212, 0x10, v146
	v_mov_b32_e32 v213, v147
	v_lshlrev_b64 v[214:215], 11, v[212:213]
	v_lshl_add_u64 v[214:215], v[214:215], 0, v[144:145]
	v_lshl_add_u64 v[154:155], v[214:215], 2, s[28:29]
	v_lshl_add_u64 v[156:157], v[214:215], 1, s[40:41]
	v_pk_add_f32 v[110:111], v[110:111], v[182:183]
	v_pk_add_f32 v[108:109], v[108:109], v[180:181]
	v_cvt_pk_bf16_f32 v159, v110, v111
	v_cvt_pk_bf16_f32 v158, v108, v109
	global_store_dwordx4 v[154:155], v[108:111], off
	global_store_dwordx2 v[156:157], v[158:159], off
	s_nop 0
	v_mul_f32_e32 v109, v109, v109
	v_mul_f32_e32 v111, v111, v111
	v_fmac_f32_e32 v109, v108, v108
	v_fmac_f32_e32 v111, v110, v110
	v_add_f32_e32 v160, v109, v111
	v_pk_add_f32 v[106:107], v[106:107], v[186:187]
	v_pk_add_f32 v[104:105], v[104:105], v[184:185]
	v_cvt_pk_bf16_f32 v159, v106, v107
	v_cvt_pk_bf16_f32 v158, v104, v105
	global_store_dwordx4 v[154:155], v[104:107], off offset:64
	global_store_dwordx2 v[156:157], v[158:159], off offset:32
	s_nop 0
	v_mul_f32_e32 v105, v105, v105
	v_mul_f32_e32 v107, v107, v107
	v_fmac_f32_e32 v105, v104, v104
	v_fmac_f32_e32 v107, v106, v106
	v_add_f32_e32 v104, v105, v107
	v_add_f32_e32 v160, v160, v104
	v_pk_add_f32 v[102:103], v[102:103], v[190:191]
	v_pk_add_f32 v[100:101], v[100:101], v[188:189]
	v_cvt_pk_bf16_f32 v159, v102, v103
	v_cvt_pk_bf16_f32 v158, v100, v101
	global_store_dwordx4 v[154:155], v[100:103], off offset:512
	global_store_dwordx2 v[156:157], v[158:159], off offset:256
	s_nop 0
	v_mul_f32_e32 v101, v101, v101
	v_mul_f32_e32 v103, v103, v103
	v_fmac_f32_e32 v101, v100, v100
	v_fmac_f32_e32 v103, v102, v102
	v_add_f32_e32 v100, v101, v103
	v_add_f32_e32 v160, v160, v100
	v_pk_add_f32 v[98:99], v[98:99], v[194:195]
	v_pk_add_f32 v[96:97], v[96:97], v[192:193]
	v_cvt_pk_bf16_f32 v159, v98, v99
	v_cvt_pk_bf16_f32 v158, v96, v97
	global_store_dwordx4 v[154:155], v[96:99], off offset:576
	global_store_dwordx2 v[156:157], v[158:159], off offset:288
	s_nop 0
	v_mul_f32_e32 v97, v97, v97
	v_mul_f32_e32 v99, v99, v99
	v_fmac_f32_e32 v97, v96, v96
	v_fmac_f32_e32 v99, v98, v98
	v_add_f32_e32 v96, v97, v99
	v_add_f32_e32 v160, v160, v96
	v_mov_b32_e32 v161, v160
	s_nop 1
	v_permlane16_swap_b32_e32 v160, v161
	v_add_f32_e32 v160, v160, v161
	v_mov_b32_e32 v161, v160
	s_nop 1
	v_permlane32_swap_b32_e32 v160, v161
	s_and_saveexec_b64 s[54:55], s[8:9]
	v_lshl_add_u64 v[162:163], v[212:213], 2, s[64:65]
	v_add_f32_e32 v160, v160, v161
	global_atomic_add_f32 v[162:163], v160, off
	s_or_b64 exec, exec, s[54:55]
	v_add_u32_e32 v212, 0x80, v146
	v_mov_b32_e32 v213, v147
	v_lshlrev_b64 v[214:215], 11, v[212:213]
	v_lshl_add_u64 v[214:215], v[214:215], 0, v[144:145]
	v_lshl_add_u64 v[152:153], v[214:215], 2, s[20:21]
	global_load_dwordx4 v[180:183], v[152:153], off
	global_load_dwordx4 v[184:187], v[152:153], off offset:64
	global_load_dwordx4 v[188:191], v[152:153], off offset:512
	global_load_dwordx4 v[192:195], v[152:153], off offset:576
	s_waitcnt vmcnt(26)
	v_add_u32_e32 v212, 0x20, v146
	v_mov_b32_e32 v213, v147
	v_lshlrev_b64 v[214:215], 11, v[212:213]
	v_lshl_add_u64 v[214:215], v[214:215], 0, v[144:145]
	v_lshl_add_u64 v[154:155], v[214:215], 2, s[28:29]
	v_lshl_add_u64 v[156:157], v[214:215], 1, s[40:41]
	v_pk_add_f32 v[94:95], v[94:95], v[198:199]
	v_pk_add_f32 v[92:93], v[92:93], v[196:197]
	v_cvt_pk_bf16_f32 v159, v94, v95
	v_cvt_pk_bf16_f32 v158, v92, v93
	global_store_dwordx4 v[154:155], v[92:95], off
	global_store_dwordx2 v[156:157], v[158:159], off
	s_nop 0
	v_mul_f32_e32 v93, v93, v93
	v_mul_f32_e32 v95, v95, v95
	v_fmac_f32_e32 v93, v92, v92
	v_fmac_f32_e32 v95, v94, v94
	v_add_f32_e32 v160, v93, v95
	v_pk_add_f32 v[90:91], v[90:91], v[202:203]
	v_pk_add_f32 v[88:89], v[88:89], v[200:201]
	v_cvt_pk_bf16_f32 v159, v90, v91
	v_cvt_pk_bf16_f32 v158, v88, v89
	global_store_dwordx4 v[154:155], v[88:91], off offset:64
	global_store_dwordx2 v[156:157], v[158:159], off offset:32
	s_nop 0
	v_mul_f32_e32 v89, v89, v89
	v_mul_f32_e32 v91, v91, v91
	v_fmac_f32_e32 v89, v88, v88
	v_fmac_f32_e32 v91, v90, v90
	v_add_f32_e32 v88, v89, v91
	v_add_f32_e32 v160, v160, v88
	v_pk_add_f32 v[86:87], v[86:87], v[206:207]
	v_pk_add_f32 v[84:85], v[84:85], v[204:205]
	v_cvt_pk_bf16_f32 v159, v86, v87
	v_cvt_pk_bf16_f32 v158, v84, v85
	global_store_dwordx4 v[154:155], v[84:87], off offset:512
	global_store_dwordx2 v[156:157], v[158:159], off offset:256
	s_nop 0
	v_mul_f32_e32 v85, v85, v85
	v_mul_f32_e32 v87, v87, v87
	v_fmac_f32_e32 v85, v84, v84
	v_fmac_f32_e32 v87, v86, v86
	v_add_f32_e32 v84, v85, v87
	v_add_f32_e32 v160, v160, v84
	v_pk_add_f32 v[82:83], v[82:83], v[210:211]
	v_pk_add_f32 v[80:81], v[80:81], v[208:209]
	v_cvt_pk_bf16_f32 v159, v82, v83
	v_cvt_pk_bf16_f32 v158, v80, v81
	global_store_dwordx4 v[154:155], v[80:83], off offset:576
	global_store_dwordx2 v[156:157], v[158:159], off offset:288
	s_nop 0
	v_mul_f32_e32 v81, v81, v81
	v_mul_f32_e32 v83, v83, v83
	v_fmac_f32_e32 v81, v80, v80
	v_fmac_f32_e32 v83, v82, v82
	v_add_f32_e32 v80, v81, v83
	v_add_f32_e32 v160, v160, v80
	v_mov_b32_e32 v161, v160
	s_nop 1
	v_permlane16_swap_b32_e32 v160, v161
	v_add_f32_e32 v160, v160, v161
	v_mov_b32_e32 v161, v160
	s_nop 1
	v_permlane32_swap_b32_e32 v160, v161
	s_and_saveexec_b64 s[54:55], s[8:9]
	v_lshl_add_u64 v[162:163], v[212:213], 2, s[64:65]
	v_add_f32_e32 v160, v160, v161
	global_atomic_add_f32 v[162:163], v160, off
	s_or_b64 exec, exec, s[54:55]
	v_add_u32_e32 v212, 0x90, v146
	v_mov_b32_e32 v213, v147
	v_lshlrev_b64 v[214:215], 11, v[212:213]
	v_lshl_add_u64 v[214:215], v[214:215], 0, v[144:145]
	v_lshl_add_u64 v[152:153], v[214:215], 2, s[20:21]
	global_load_dwordx4 v[196:199], v[152:153], off
	global_load_dwordx4 v[200:203], v[152:153], off offset:64
	global_load_dwordx4 v[204:207], v[152:153], off offset:512
	global_load_dwordx4 v[208:211], v[152:153], off offset:576
	s_waitcnt vmcnt(26)
	v_add_u32_e32 v212, 0x30, v146
	v_mov_b32_e32 v213, v147
	v_lshlrev_b64 v[214:215], 11, v[212:213]
	v_lshl_add_u64 v[214:215], v[214:215], 0, v[144:145]
	v_lshl_add_u64 v[154:155], v[214:215], 2, s[28:29]
	v_lshl_add_u64 v[156:157], v[214:215], 1, s[40:41]
	v_pk_add_f32 v[78:79], v[78:79], v[166:167]
	v_pk_add_f32 v[76:77], v[76:77], v[164:165]
	v_cvt_pk_bf16_f32 v159, v78, v79
	v_cvt_pk_bf16_f32 v158, v76, v77
	global_store_dwordx4 v[154:155], v[76:79], off
	global_store_dwordx2 v[156:157], v[158:159], off
	s_nop 0
	v_mul_f32_e32 v77, v77, v77
	v_mul_f32_e32 v79, v79, v79
	v_fmac_f32_e32 v77, v76, v76
	v_fmac_f32_e32 v79, v78, v78
	v_add_f32_e32 v160, v77, v79
	v_pk_add_f32 v[74:75], v[74:75], v[170:171]
	v_pk_add_f32 v[72:73], v[72:73], v[168:169]
	v_cvt_pk_bf16_f32 v159, v74, v75
	v_cvt_pk_bf16_f32 v158, v72, v73
	global_store_dwordx4 v[154:155], v[72:75], off offset:64
	global_store_dwordx2 v[156:157], v[158:159], off offset:32
	s_nop 0
	v_mul_f32_e32 v73, v73, v73
	v_mul_f32_e32 v75, v75, v75
	v_fmac_f32_e32 v73, v72, v72
	v_fmac_f32_e32 v75, v74, v74
	v_add_f32_e32 v72, v73, v75
	v_add_f32_e32 v160, v160, v72
	v_pk_add_f32 v[70:71], v[70:71], v[174:175]
	v_pk_add_f32 v[68:69], v[68:69], v[172:173]
	v_cvt_pk_bf16_f32 v159, v70, v71
	v_cvt_pk_bf16_f32 v158, v68, v69
	global_store_dwordx4 v[154:155], v[68:71], off offset:512
	global_store_dwordx2 v[156:157], v[158:159], off offset:256
	s_nop 0
	v_mul_f32_e32 v69, v69, v69
	v_mul_f32_e32 v71, v71, v71
	v_fmac_f32_e32 v69, v68, v68
	v_fmac_f32_e32 v71, v70, v70
	v_add_f32_e32 v68, v69, v71
	v_add_f32_e32 v160, v160, v68
	v_pk_add_f32 v[66:67], v[66:67], v[178:179]
	v_pk_add_f32 v[64:65], v[64:65], v[176:177]
	v_cvt_pk_bf16_f32 v159, v66, v67
	v_cvt_pk_bf16_f32 v158, v64, v65
	global_store_dwordx4 v[154:155], v[64:67], off offset:576
	global_store_dwordx2 v[156:157], v[158:159], off offset:288
	s_nop 0
	v_mul_f32_e32 v65, v65, v65
	v_mul_f32_e32 v67, v67, v67
	v_fmac_f32_e32 v65, v64, v64
	v_fmac_f32_e32 v67, v66, v66
	v_add_f32_e32 v64, v65, v67
	v_add_f32_e32 v160, v160, v64
	v_mov_b32_e32 v161, v160
	s_nop 1
	v_permlane16_swap_b32_e32 v160, v161
	v_add_f32_e32 v160, v160, v161
	v_mov_b32_e32 v161, v160
	s_nop 1
	v_permlane32_swap_b32_e32 v160, v161
	s_and_saveexec_b64 s[54:55], s[8:9]
	v_lshl_add_u64 v[162:163], v[212:213], 2, s[64:65]
	v_add_f32_e32 v160, v160, v161
	global_atomic_add_f32 v[162:163], v160, off
	s_or_b64 exec, exec, s[54:55]
	v_add_u32_e32 v212, 0xa0, v146
	v_mov_b32_e32 v213, v147
	v_lshlrev_b64 v[214:215], 11, v[212:213]
	v_lshl_add_u64 v[214:215], v[214:215], 0, v[144:145]
	v_lshl_add_u64 v[152:153], v[214:215], 2, s[20:21]
	global_load_dwordx4 v[164:167], v[152:153], off
	global_load_dwordx4 v[168:171], v[152:153], off offset:64
	global_load_dwordx4 v[172:175], v[152:153], off offset:512
	global_load_dwordx4 v[176:179], v[152:153], off offset:576
	s_waitcnt vmcnt(26)
	v_add_u32_e32 v212, 0x80, v146
	v_mov_b32_e32 v213, v147
	v_lshlrev_b64 v[214:215], 11, v[212:213]
	v_lshl_add_u64 v[214:215], v[214:215], 0, v[144:145]
	v_lshl_add_u64 v[154:155], v[214:215], 2, s[28:29]
	v_lshl_add_u64 v[156:157], v[214:215], 1, s[40:41]
	v_pk_add_f32 v[62:63], v[62:63], v[182:183]
	v_pk_add_f32 v[60:61], v[60:61], v[180:181]
	v_cvt_pk_bf16_f32 v159, v62, v63
	v_cvt_pk_bf16_f32 v158, v60, v61
	global_store_dwordx4 v[154:155], v[60:63], off
	global_store_dwordx2 v[156:157], v[158:159], off
	s_nop 0
	v_mul_f32_e32 v61, v61, v61
	v_mul_f32_e32 v63, v63, v63
	v_fmac_f32_e32 v61, v60, v60
	v_fmac_f32_e32 v63, v62, v62
	v_add_f32_e32 v160, v61, v63
	v_pk_add_f32 v[58:59], v[58:59], v[186:187]
	v_pk_add_f32 v[56:57], v[56:57], v[184:185]
	v_cvt_pk_bf16_f32 v159, v58, v59
	v_cvt_pk_bf16_f32 v158, v56, v57
	global_store_dwordx4 v[154:155], v[56:59], off offset:64
	global_store_dwordx2 v[156:157], v[158:159], off offset:32
	s_nop 0
	v_mul_f32_e32 v57, v57, v57
	v_mul_f32_e32 v59, v59, v59
	v_fmac_f32_e32 v57, v56, v56
	v_fmac_f32_e32 v59, v58, v58
	v_add_f32_e32 v56, v57, v59
	v_add_f32_e32 v160, v160, v56
	v_pk_add_f32 v[54:55], v[54:55], v[190:191]
	v_pk_add_f32 v[52:53], v[52:53], v[188:189]
	v_cvt_pk_bf16_f32 v159, v54, v55
	v_cvt_pk_bf16_f32 v158, v52, v53
	global_store_dwordx4 v[154:155], v[52:55], off offset:512
	global_store_dwordx2 v[156:157], v[158:159], off offset:256
	s_nop 0
	v_mul_f32_e32 v53, v53, v53
	v_mul_f32_e32 v55, v55, v55
	v_fmac_f32_e32 v53, v52, v52
	v_fmac_f32_e32 v55, v54, v54
	v_add_f32_e32 v52, v53, v55
	v_add_f32_e32 v160, v160, v52
	v_pk_add_f32 v[50:51], v[50:51], v[194:195]
	v_pk_add_f32 v[48:49], v[48:49], v[192:193]
	v_cvt_pk_bf16_f32 v159, v50, v51
	v_cvt_pk_bf16_f32 v158, v48, v49
	global_store_dwordx4 v[154:155], v[48:51], off offset:576
	global_store_dwordx2 v[156:157], v[158:159], off offset:288
	s_nop 0
	v_mul_f32_e32 v49, v49, v49
	v_mul_f32_e32 v51, v51, v51
	v_fmac_f32_e32 v49, v48, v48
	v_fmac_f32_e32 v51, v50, v50
	v_add_f32_e32 v48, v49, v51
	v_add_f32_e32 v160, v160, v48
	v_mov_b32_e32 v161, v160
	s_nop 1
	v_permlane16_swap_b32_e32 v160, v161
	v_add_f32_e32 v160, v160, v161
	v_mov_b32_e32 v161, v160
	s_nop 1
	v_permlane32_swap_b32_e32 v160, v161
	s_and_saveexec_b64 s[54:55], s[8:9]
	v_lshl_add_u64 v[162:163], v[212:213], 2, s[64:65]
	v_add_f32_e32 v160, v160, v161
	global_atomic_add_f32 v[162:163], v160, off
	s_or_b64 exec, exec, s[54:55]
	v_add_u32_e32 v212, 0xb0, v146
	v_mov_b32_e32 v213, v147
	v_lshlrev_b64 v[214:215], 11, v[212:213]
	v_lshl_add_u64 v[214:215], v[214:215], 0, v[144:145]
	v_lshl_add_u64 v[152:153], v[214:215], 2, s[20:21]
	global_load_dwordx4 v[180:183], v[152:153], off
	global_load_dwordx4 v[184:187], v[152:153], off offset:64
	global_load_dwordx4 v[188:191], v[152:153], off offset:512
	global_load_dwordx4 v[192:195], v[152:153], off offset:576
	s_waitcnt vmcnt(26)
	v_add_u32_e32 v212, 0x90, v146
	v_mov_b32_e32 v213, v147
	v_lshlrev_b64 v[214:215], 11, v[212:213]
	v_lshl_add_u64 v[214:215], v[214:215], 0, v[144:145]
	v_lshl_add_u64 v[154:155], v[214:215], 2, s[28:29]
	v_lshl_add_u64 v[156:157], v[214:215], 1, s[40:41]
	v_pk_add_f32 v[46:47], v[46:47], v[198:199]
	v_pk_add_f32 v[44:45], v[44:45], v[196:197]
	v_cvt_pk_bf16_f32 v159, v46, v47
	v_cvt_pk_bf16_f32 v158, v44, v45
	global_store_dwordx4 v[154:155], v[44:47], off
	global_store_dwordx2 v[156:157], v[158:159], off
	s_nop 0
	v_mul_f32_e32 v45, v45, v45
	v_mul_f32_e32 v47, v47, v47
	v_fmac_f32_e32 v45, v44, v44
	v_fmac_f32_e32 v47, v46, v46
	v_add_f32_e32 v160, v45, v47
	v_pk_add_f32 v[42:43], v[42:43], v[202:203]
	v_pk_add_f32 v[40:41], v[40:41], v[200:201]
	v_cvt_pk_bf16_f32 v159, v42, v43
	v_cvt_pk_bf16_f32 v158, v40, v41
	global_store_dwordx4 v[154:155], v[40:43], off offset:64
	global_store_dwordx2 v[156:157], v[158:159], off offset:32
	s_nop 0
	v_mul_f32_e32 v41, v41, v41
	v_mul_f32_e32 v43, v43, v43
	v_fmac_f32_e32 v41, v40, v40
	v_fmac_f32_e32 v43, v42, v42
	v_add_f32_e32 v40, v41, v43
	v_add_f32_e32 v160, v160, v40
	v_pk_add_f32 v[38:39], v[38:39], v[206:207]
	v_pk_add_f32 v[36:37], v[36:37], v[204:205]
	v_cvt_pk_bf16_f32 v159, v38, v39
	v_cvt_pk_bf16_f32 v158, v36, v37
	global_store_dwordx4 v[154:155], v[36:39], off offset:512
	global_store_dwordx2 v[156:157], v[158:159], off offset:256
	s_nop 0
	v_mul_f32_e32 v37, v37, v37
	v_mul_f32_e32 v39, v39, v39
	v_fmac_f32_e32 v37, v36, v36
	v_fmac_f32_e32 v39, v38, v38
	v_add_f32_e32 v36, v37, v39
	v_add_f32_e32 v160, v160, v36
	v_pk_add_f32 v[34:35], v[34:35], v[210:211]
	v_pk_add_f32 v[32:33], v[32:33], v[208:209]
	v_cvt_pk_bf16_f32 v159, v34, v35
	v_cvt_pk_bf16_f32 v158, v32, v33
	global_store_dwordx4 v[154:155], v[32:35], off offset:576
	global_store_dwordx2 v[156:157], v[158:159], off offset:288
	s_nop 0
	v_mul_f32_e32 v33, v33, v33
	v_mul_f32_e32 v35, v35, v35
	v_fmac_f32_e32 v33, v32, v32
	v_fmac_f32_e32 v35, v34, v34
	v_add_f32_e32 v32, v33, v35
	v_add_f32_e32 v160, v160, v32
	v_mov_b32_e32 v161, v160
	s_nop 1
	v_permlane16_swap_b32_e32 v160, v161
	v_add_f32_e32 v160, v160, v161
	v_mov_b32_e32 v161, v160
	s_nop 1
	v_permlane32_swap_b32_e32 v160, v161
	s_and_saveexec_b64 s[54:55], s[8:9]
	v_lshl_add_u64 v[162:163], v[212:213], 2, s[64:65]
	v_add_f32_e32 v160, v160, v161
	global_atomic_add_f32 v[162:163], v160, off
	s_or_b64 exec, exec, s[54:55]
	s_waitcnt vmcnt(22)
	v_add_u32_e32 v212, 0xa0, v146
	v_mov_b32_e32 v213, v147
	v_lshlrev_b64 v[214:215], 11, v[212:213]
	v_lshl_add_u64 v[214:215], v[214:215], 0, v[144:145]
	v_lshl_add_u64 v[154:155], v[214:215], 2, s[28:29]
	v_lshl_add_u64 v[156:157], v[214:215], 1, s[40:41]
	v_pk_add_f32 v[30:31], v[30:31], v[166:167]
	v_pk_add_f32 v[28:29], v[28:29], v[164:165]
	v_cvt_pk_bf16_f32 v159, v30, v31
	v_cvt_pk_bf16_f32 v158, v28, v29
	global_store_dwordx4 v[154:155], v[28:31], off
	global_store_dwordx2 v[156:157], v[158:159], off
	s_nop 0
	v_mul_f32_e32 v29, v29, v29
	v_mul_f32_e32 v31, v31, v31
	v_fmac_f32_e32 v29, v28, v28
	v_fmac_f32_e32 v31, v30, v30
	v_add_f32_e32 v160, v29, v31
	v_pk_add_f32 v[26:27], v[26:27], v[170:171]
	v_pk_add_f32 v[24:25], v[24:25], v[168:169]
	v_cvt_pk_bf16_f32 v159, v26, v27
	v_cvt_pk_bf16_f32 v158, v24, v25
	global_store_dwordx4 v[154:155], v[24:27], off offset:64
	global_store_dwordx2 v[156:157], v[158:159], off offset:32
	s_nop 0
	v_mul_f32_e32 v25, v25, v25
	v_mul_f32_e32 v27, v27, v27
	v_fmac_f32_e32 v25, v24, v24
	v_fmac_f32_e32 v27, v26, v26
	v_add_f32_e32 v24, v25, v27
	v_add_f32_e32 v160, v160, v24
	v_pk_add_f32 v[22:23], v[22:23], v[174:175]
	v_pk_add_f32 v[20:21], v[20:21], v[172:173]
	v_cvt_pk_bf16_f32 v159, v22, v23
	v_cvt_pk_bf16_f32 v158, v20, v21
	global_store_dwordx4 v[154:155], v[20:23], off offset:512
	global_store_dwordx2 v[156:157], v[158:159], off offset:256
	s_nop 0
	v_mul_f32_e32 v21, v21, v21
	v_mul_f32_e32 v23, v23, v23
	v_fmac_f32_e32 v21, v20, v20
	v_fmac_f32_e32 v23, v22, v22
	v_add_f32_e32 v20, v21, v23
	v_add_f32_e32 v160, v160, v20
	v_pk_add_f32 v[18:19], v[18:19], v[178:179]
	v_pk_add_f32 v[16:17], v[16:17], v[176:177]
	v_cvt_pk_bf16_f32 v159, v18, v19
	v_cvt_pk_bf16_f32 v158, v16, v17
	global_store_dwordx4 v[154:155], v[16:19], off offset:576
	global_store_dwordx2 v[156:157], v[158:159], off offset:288
	s_nop 0
	v_mul_f32_e32 v17, v17, v17
	v_mul_f32_e32 v19, v19, v19
	v_fmac_f32_e32 v17, v16, v16
	v_fmac_f32_e32 v19, v18, v18
	v_add_f32_e32 v16, v17, v19
	v_add_f32_e32 v160, v160, v16
	v_mov_b32_e32 v161, v160
	s_nop 1
	v_permlane16_swap_b32_e32 v160, v161
	v_add_f32_e32 v160, v160, v161
	v_mov_b32_e32 v161, v160
	s_nop 1
	v_permlane32_swap_b32_e32 v160, v161
	s_and_saveexec_b64 s[54:55], s[8:9]
	v_lshl_add_u64 v[162:163], v[212:213], 2, s[64:65]
	v_add_f32_e32 v160, v160, v161
	global_atomic_add_f32 v[162:163], v160, off
	s_or_b64 exec, exec, s[54:55]
	s_waitcnt vmcnt(18)
	v_add_u32_e32 v212, 0xb0, v146
	v_mov_b32_e32 v213, v147
	v_lshlrev_b64 v[214:215], 11, v[212:213]
	v_lshl_add_u64 v[214:215], v[214:215], 0, v[144:145]
	v_lshl_add_u64 v[154:155], v[214:215], 2, s[28:29]
	v_lshl_add_u64 v[156:157], v[214:215], 1, s[40:41]
	v_pk_add_f32 v[14:15], v[14:15], v[182:183]
	v_pk_add_f32 v[12:13], v[12:13], v[180:181]
	v_cvt_pk_bf16_f32 v159, v14, v15
	v_cvt_pk_bf16_f32 v158, v12, v13
	global_store_dwordx4 v[154:155], v[12:15], off
	global_store_dwordx2 v[156:157], v[158:159], off
	s_nop 0
	v_mul_f32_e32 v13, v13, v13
	v_mul_f32_e32 v15, v15, v15
	v_fmac_f32_e32 v13, v12, v12
	v_fmac_f32_e32 v15, v14, v14
	v_add_f32_e32 v160, v13, v15
	v_pk_add_f32 v[10:11], v[10:11], v[186:187]
	v_pk_add_f32 v[8:9], v[8:9], v[184:185]
	v_cvt_pk_bf16_f32 v159, v10, v11
	v_cvt_pk_bf16_f32 v158, v8, v9
	global_store_dwordx4 v[154:155], v[8:11], off offset:64
	global_store_dwordx2 v[156:157], v[158:159], off offset:32
	s_nop 0
	v_mul_f32_e32 v9, v9, v9
	v_mul_f32_e32 v11, v11, v11
	v_fmac_f32_e32 v9, v8, v8
	v_fmac_f32_e32 v11, v10, v10
	v_add_f32_e32 v8, v9, v11
	v_add_f32_e32 v160, v160, v8
	v_pk_add_f32 v[6:7], v[6:7], v[190:191]
	v_pk_add_f32 v[4:5], v[4:5], v[188:189]
	v_cvt_pk_bf16_f32 v159, v6, v7
	v_cvt_pk_bf16_f32 v158, v4, v5
	global_store_dwordx4 v[154:155], v[4:7], off offset:512
	global_store_dwordx2 v[156:157], v[158:159], off offset:256
	s_nop 0
	v_mul_f32_e32 v5, v5, v5
	v_mul_f32_e32 v7, v7, v7
	v_fmac_f32_e32 v5, v4, v4
	v_fmac_f32_e32 v7, v6, v6
	v_add_f32_e32 v4, v5, v7
	v_add_f32_e32 v160, v160, v4
	v_pk_add_f32 v[2:3], v[2:3], v[194:195]
	v_pk_add_f32 v[0:1], v[0:1], v[192:193]
	v_cvt_pk_bf16_f32 v159, v2, v3
	v_cvt_pk_bf16_f32 v158, v0, v1
	global_store_dwordx4 v[154:155], v[0:3], off offset:576
	global_store_dwordx2 v[156:157], v[158:159], off offset:288
	s_nop 0
	v_mul_f32_e32 v1, v1, v1
	v_mul_f32_e32 v3, v3, v3
	v_fmac_f32_e32 v1, v0, v0
	v_fmac_f32_e32 v3, v2, v2
	v_add_f32_e32 v0, v1, v3
	v_add_f32_e32 v160, v160, v0
	v_mov_b32_e32 v161, v160
	s_nop 1
	v_permlane16_swap_b32_e32 v160, v161
	v_add_f32_e32 v160, v160, v161
	v_mov_b32_e32 v161, v160
	s_nop 1
	v_permlane32_swap_b32_e32 v160, v161
	s_and_saveexec_b64 s[54:55], s[8:9]
	v_lshl_add_u64 v[162:163], v[212:213], 2, s[64:65]
	v_add_f32_e32 v160, v160, v161
	global_atomic_add_f32 v[162:163], v160, off
	s_or_b64 exec, exec, s[54:55]
	s_branch .LBB0_360

.LBB0_530:
	ds_read_b128 v[144:147], v149
	ds_read_b128 v[152:155], v149 offset:1024
	ds_read_b128 v[156:159], v149 offset:2048
	ds_read_b128 v[160:163], v149 offset:3072
	s_add_u32 s70, s68, 0x100
	s_addc_u32 s71, s69, 0
	s_cmpk_eq_i32 s56, 0x7c
	s_cselect_b32 s75, s19, s71
	s_cselect_b32 s74, s25, s70
	s_cselect_b32 s73, s17, s55
	s_cselect_b32 s72, s49, s54
	v_lshl_add_u64 v[196:197], s[68:69], 0, v[134:135]
	s_add_i32 m0, s6, 0xc000
	ds_read_b128 v[164:167], v150
	ds_read_b128 v[168:171], v150 offset:1024
	ds_read_b128 v[172:175], v150 offset:2048
	ds_read_b128 v[176:179], v150 offset:3072
	ds_read_b128 v[180:183], v150 offset:4096
	ds_read_b128 v[184:187], v150 offset:5120
	ds_read_b128 v[188:191], v150 offset:6144
	ds_read_b128 v[192:195], v150 offset:7168
	global_load_lds_dwordx4 v[196:197], off
	v_lshl_add_u64 v[196:197], s[68:69], 0, v[138:139]
	s_add_i32 m0, s6, 0xe000
	s_nop 0
	global_load_lds_dwordx4 v[196:197], off
	s_waitcnt lgkmcnt(8)
	s_barrier
	s_waitcnt lgkmcnt(0)
	s_setprio 1
	s_waitcnt lgkmcnt(0)
	v_mfma_f32_16x16x32_bf16 v[124:127], v[144:147], v[164:167], v[124:127]
	v_mfma_f32_16x16x32_bf16 v[120:123], v[156:159], v[164:167], v[120:123]
	v_mfma_f32_16x16x32_bf16 v[108:111], v[144:147], v[172:175], v[108:111]
	v_mfma_f32_16x16x32_bf16 v[104:107], v[156:159], v[172:175], v[104:107]
	v_mfma_f32_16x16x32_bf16 v[92:95], v[144:147], v[180:183], v[92:95]
	v_mfma_f32_16x16x32_bf16 v[88:91], v[156:159], v[180:183], v[88:91]
	v_mfma_f32_16x16x32_bf16 v[76:79], v[144:147], v[188:191], v[76:79]
	v_mfma_f32_16x16x32_bf16 v[72:75], v[156:159], v[188:191], v[72:75]
	v_mfma_f32_16x16x32_bf16 v[124:127], v[152:155], v[168:171], v[124:127]
	v_mfma_f32_16x16x32_bf16 v[120:123], v[160:163], v[168:171], v[120:123]
	v_mfma_f32_16x16x32_bf16 v[108:111], v[152:155], v[176:179], v[108:111]
	v_mfma_f32_16x16x32_bf16 v[104:107], v[160:163], v[176:179], v[104:107]
	v_mfma_f32_16x16x32_bf16 v[92:95], v[152:155], v[184:187], v[92:95]
	v_mfma_f32_16x16x32_bf16 v[88:91], v[160:163], v[184:187], v[88:91]
	v_mfma_f32_16x16x32_bf16 v[76:79], v[152:155], v[192:195], v[76:79]
	v_mfma_f32_16x16x32_bf16 v[72:75], v[160:163], v[192:195], v[72:75]
	s_setprio 0
	s_barrier
	s_add_i32 s57, s47, s5
	v_lshl_add_u64 v[212:213], s[72:73], 0, v[128:129]
	s_mov_b32 m0, s57
	ds_read_b128 v[196:199], v151
	ds_read_b128 v[200:203], v151 offset:1024
	ds_read_b128 v[204:207], v151 offset:2048
	ds_read_b128 v[208:211], v151 offset:3072
	global_load_lds_dwordx4 v[212:213], off
	v_lshl_add_u64 v[214:215], s[72:73], 0, v[130:131]
	s_add_i32 m0, s57, 0x2000
	s_nop 0
	global_load_lds_dwordx4 v[214:215], off
	s_barrier
	s_waitcnt lgkmcnt(0)
	s_setprio 1
	s_waitcnt lgkmcnt(0)
	v_mfma_f32_16x16x32_bf16 v[116:119], v[196:199], v[164:167], v[116:119]
	v_mfma_f32_16x16x32_bf16 v[112:115], v[204:207], v[164:167], v[112:115]
	v_mfma_f32_16x16x32_bf16 v[100:103], v[196:199], v[172:175], v[100:103]
	v_mfma_f32_16x16x32_bf16 v[96:99], v[204:207], v[172:175], v[96:99]
	v_mfma_f32_16x16x32_bf16 v[84:87], v[196:199], v[180:183], v[84:87]
	v_mfma_f32_16x16x32_bf16 v[80:83], v[204:207], v[180:183], v[80:83]
	v_mfma_f32_16x16x32_bf16 v[68:71], v[196:199], v[188:191], v[68:71]
	v_mfma_f32_16x16x32_bf16 v[64:67], v[204:207], v[188:191], v[64:67]
	v_mfma_f32_16x16x32_bf16 v[116:119], v[200:203], v[168:171], v[116:119]
	v_mfma_f32_16x16x32_bf16 v[112:115], v[208:211], v[168:171], v[112:115]
	v_mfma_f32_16x16x32_bf16 v[100:103], v[200:203], v[176:179], v[100:103]
	v_mfma_f32_16x16x32_bf16 v[96:99], v[208:211], v[176:179], v[96:99]
	v_mfma_f32_16x16x32_bf16 v[84:87], v[200:203], v[184:187], v[84:87]
	v_mfma_f32_16x16x32_bf16 v[80:83], v[208:211], v[184:187], v[80:83]
	v_mfma_f32_16x16x32_bf16 v[68:71], v[200:203], v[192:195], v[68:71]
	v_mfma_f32_16x16x32_bf16 v[64:67], v[208:211], v[192:195], v[64:67]
	s_setprio 0
	s_mov_b32 m0, s6
	v_lshl_add_u64 v[216:217], s[74:75], 0, v[128:129]
	s_barrier
	ds_read_b128 v[164:167], v150 offset:16384
	ds_read_b128 v[168:171], v150 offset:17408
	ds_read_b128 v[172:175], v150 offset:18432
	ds_read_b128 v[176:179], v150 offset:19456
	ds_read_b128 v[180:183], v150 offset:20480
	ds_read_b128 v[184:187], v150 offset:21504
	ds_read_b128 v[188:191], v150 offset:22528
	ds_read_b128 v[192:195], v150 offset:23552
	global_load_lds_dwordx4 v[216:217], off
	v_lshl_add_u64 v[218:219], s[74:75], 0, v[130:131]
	s_mov_b32 m0, s7
	s_nop 0
	global_load_lds_dwordx4 v[218:219], off
	s_barrier
	s_waitcnt lgkmcnt(0)
	s_setprio 1
	s_waitcnt lgkmcnt(0)
	v_mfma_f32_16x16x32_bf16 v[60:63], v[144:147], v[164:167], v[60:63]
	v_mfma_f32_16x16x32_bf16 v[56:59], v[156:159], v[164:167], v[56:59]
	v_mfma_f32_16x16x32_bf16 v[44:47], v[144:147], v[172:175], v[44:47]
	v_mfma_f32_16x16x32_bf16 v[40:43], v[156:159], v[172:175], v[40:43]
	v_mfma_f32_16x16x32_bf16 v[28:31], v[144:147], v[180:183], v[28:31]
	v_mfma_f32_16x16x32_bf16 v[24:27], v[156:159], v[180:183], v[24:27]
	v_mfma_f32_16x16x32_bf16 v[12:15], v[144:147], v[188:191], v[12:15]
	v_mfma_f32_16x16x32_bf16 v[8:11], v[156:159], v[188:191], v[8:11]
	v_mfma_f32_16x16x32_bf16 v[60:63], v[152:155], v[168:171], v[60:63]
	v_mfma_f32_16x16x32_bf16 v[56:59], v[160:163], v[168:171], v[56:59]
	v_mfma_f32_16x16x32_bf16 v[44:47], v[152:155], v[176:179], v[44:47]
	v_mfma_f32_16x16x32_bf16 v[40:43], v[160:163], v[176:179], v[40:43]
	v_mfma_f32_16x16x32_bf16 v[28:31], v[152:155], v[184:187], v[28:31]
	v_mfma_f32_16x16x32_bf16 v[24:27], v[160:163], v[184:187], v[24:27]
	v_mfma_f32_16x16x32_bf16 v[12:15], v[152:155], v[192:195], v[12:15]
	v_mfma_f32_16x16x32_bf16 v[8:11], v[160:163], v[192:195], v[8:11]
	s_setprio 0
	s_barrier
	s_add_u32 s68, s72, 0x200000
	s_addc_u32 s69, s73, 0
	s_add_i32 s57, s48, s5
	v_lshl_add_u64 v[144:145], s[68:69], 0, v[128:129]
	s_mov_b32 m0, s57
	s_nop 0
	global_load_lds_dwordx4 v[144:145], off
	v_lshl_add_u64 v[144:145], s[68:69], 0, v[130:131]
	s_add_i32 m0, s57, 0x2000
	s_nop 0
	global_load_lds_dwordx4 v[144:145], off
	s_waitcnt vmcnt(6)
	s_barrier
	s_setprio 1
	v_mfma_f32_16x16x32_bf16 v[52:55], v[196:199], v[164:167], v[52:55]
	v_mfma_f32_16x16x32_bf16 v[48:51], v[204:207], v[164:167], v[48:51]
	v_mfma_f32_16x16x32_bf16 v[36:39], v[196:199], v[172:175], v[36:39]
	v_mfma_f32_16x16x32_bf16 v[32:35], v[204:207], v[172:175], v[32:35]
	v_mfma_f32_16x16x32_bf16 v[20:23], v[196:199], v[180:183], v[20:23]
	v_mfma_f32_16x16x32_bf16 v[16:19], v[204:207], v[180:183], v[16:19]
	v_mfma_f32_16x16x32_bf16 v[4:7], v[196:199], v[188:191], v[4:7]
	v_mfma_f32_16x16x32_bf16 v[0:3], v[204:207], v[188:191], v[0:3]
	v_mfma_f32_16x16x32_bf16 v[52:55], v[200:203], v[168:171], v[52:55]
	v_mfma_f32_16x16x32_bf16 v[48:51], v[208:211], v[168:171], v[48:51]
	v_mfma_f32_16x16x32_bf16 v[36:39], v[200:203], v[176:179], v[36:39]
	v_mfma_f32_16x16x32_bf16 v[32:35], v[208:211], v[176:179], v[32:35]
	v_mfma_f32_16x16x32_bf16 v[20:23], v[200:203], v[184:187], v[20:23]
	v_mfma_f32_16x16x32_bf16 v[16:19], v[208:211], v[184:187], v[16:19]
	v_mfma_f32_16x16x32_bf16 v[4:7], v[200:203], v[192:195], v[4:7]
	v_mfma_f32_16x16x32_bf16 v[0:3], v[208:211], v[192:195], v[0:3]
	s_setprio 0
	s_add_i32 s57, 16, 0x18000
	v_add_u32_e32 v160, s57, v148
	s_barrier
	ds_read_b128 v[144:147], v160
	ds_read_b128 v[152:155], v160 offset:1024
	ds_read_b128 v[156:159], v160 offset:2048
	ds_read_b128 v[160:163], v160 offset:3072
	s_add_u32 s68, s74, 0x200000
	s_addc_u32 s69, s75, 0
	s_mov_b32 m0, s26
	v_lshl_add_u64 v[196:197], s[68:69], 0, v[128:129]
	ds_read_b128 v[164:167], v150 offset:32768
	ds_read_b128 v[168:171], v150 offset:33792
	ds_read_b128 v[172:175], v150 offset:34816
	ds_read_b128 v[176:179], v150 offset:35840
	ds_read_b128 v[180:183], v150 offset:36864
	ds_read_b128 v[184:187], v150 offset:37888
	ds_read_b128 v[188:191], v150 offset:38912
	ds_read_b128 v[192:195], v150 offset:39936
	global_load_lds_dwordx4 v[196:197], off
	v_lshl_add_u64 v[196:197], s[68:69], 0, v[130:131]
	s_mov_b32 m0, s27
	s_nop 0
	global_load_lds_dwordx4 v[196:197], off
	s_waitcnt lgkmcnt(8)
	s_barrier
	s_waitcnt lgkmcnt(0)
	s_setprio 1
	s_waitcnt lgkmcnt(0)
	v_mfma_f32_16x16x32_bf16 v[124:127], v[144:147], v[164:167], v[124:127]
	v_mfma_f32_16x16x32_bf16 v[120:123], v[156:159], v[164:167], v[120:123]
	v_mfma_f32_16x16x32_bf16 v[108:111], v[144:147], v[172:175], v[108:111]
	v_mfma_f32_16x16x32_bf16 v[104:107], v[156:159], v[172:175], v[104:107]
	v_mfma_f32_16x16x32_bf16 v[92:95], v[144:147], v[180:183], v[92:95]
	v_mfma_f32_16x16x32_bf16 v[88:91], v[156:159], v[180:183], v[88:91]
	v_mfma_f32_16x16x32_bf16 v[76:79], v[144:147], v[188:191], v[76:79]
	v_mfma_f32_16x16x32_bf16 v[72:75], v[156:159], v[188:191], v[72:75]
	v_mfma_f32_16x16x32_bf16 v[124:127], v[152:155], v[168:171], v[124:127]
	v_mfma_f32_16x16x32_bf16 v[120:123], v[160:163], v[168:171], v[120:123]
	v_mfma_f32_16x16x32_bf16 v[108:111], v[152:155], v[176:179], v[108:111]
	v_mfma_f32_16x16x32_bf16 v[104:107], v[160:163], v[176:179], v[104:107]
	v_mfma_f32_16x16x32_bf16 v[92:95], v[152:155], v[184:187], v[92:95]
	v_mfma_f32_16x16x32_bf16 v[88:91], v[160:163], v[184:187], v[88:91]
	v_mfma_f32_16x16x32_bf16 v[76:79], v[152:155], v[192:195], v[76:79]
	v_mfma_f32_16x16x32_bf16 v[72:75], v[160:163], v[192:195], v[72:75]
	s_setprio 0
	s_barrier
	s_add_i32 s67, 16, 0x1c000
	s_add_i32 s57, s57, s5
	v_add_u32_e32 v208, s67, v148
	v_lshl_add_u64 v[212:213], v[212:213], 0, s[14:15]
	s_mov_b32 m0, s57
	ds_read_b128 v[196:199], v208
	ds_read_b128 v[200:203], v208 offset:1024
	ds_read_b128 v[204:207], v208 offset:2048
	ds_read_b128 v[208:211], v208 offset:3072
	global_load_lds_dwordx4 v[212:213], off
	v_lshl_add_u64 v[212:213], v[214:215], 0, s[14:15]
	s_add_i32 m0, s57, 0x2000
	s_nop 0
	global_load_lds_dwordx4 v[212:213], off
	s_barrier
	s_waitcnt lgkmcnt(0)
	s_setprio 1
	s_waitcnt lgkmcnt(0)
	v_mfma_f32_16x16x32_bf16 v[116:119], v[196:199], v[164:167], v[116:119]
	v_mfma_f32_16x16x32_bf16 v[112:115], v[204:207], v[164:167], v[112:115]
	v_mfma_f32_16x16x32_bf16 v[100:103], v[196:199], v[172:175], v[100:103]
	v_mfma_f32_16x16x32_bf16 v[96:99], v[204:207], v[172:175], v[96:99]
	v_mfma_f32_16x16x32_bf16 v[84:87], v[196:199], v[180:183], v[84:87]
	v_mfma_f32_16x16x32_bf16 v[80:83], v[204:207], v[180:183], v[80:83]
	v_mfma_f32_16x16x32_bf16 v[68:71], v[196:199], v[188:191], v[68:71]
	v_mfma_f32_16x16x32_bf16 v[64:67], v[204:207], v[188:191], v[64:67]
	v_mfma_f32_16x16x32_bf16 v[116:119], v[200:203], v[168:171], v[116:119]
	v_mfma_f32_16x16x32_bf16 v[112:115], v[208:211], v[168:171], v[112:115]
	v_mfma_f32_16x16x32_bf16 v[100:103], v[200:203], v[176:179], v[100:103]
	v_mfma_f32_16x16x32_bf16 v[96:99], v[208:211], v[176:179], v[96:99]
	v_mfma_f32_16x16x32_bf16 v[84:87], v[200:203], v[184:187], v[84:87]
	v_mfma_f32_16x16x32_bf16 v[80:83], v[208:211], v[184:187], v[80:83]
	v_mfma_f32_16x16x32_bf16 v[68:71], v[200:203], v[192:195], v[68:71]
	v_mfma_f32_16x16x32_bf16 v[64:67], v[208:211], v[192:195], v[64:67]
	s_setprio 0
	s_mov_b32 m0, s39
	v_lshl_add_u64 v[212:213], v[216:217], 0, s[14:15]
	s_barrier
	ds_read_b128 v[164:167], v150 offset:49152
	ds_read_b128 v[168:171], v150 offset:50176
	ds_read_b128 v[172:175], v150 offset:51200
	ds_read_b128 v[176:179], v150 offset:52224
	ds_read_b128 v[180:183], v150 offset:53248
	ds_read_b128 v[184:187], v150 offset:54272
	ds_read_b128 v[188:191], v150 offset:55296
	ds_read_b128 v[192:195], v150 offset:56320
	global_load_lds_dwordx4 v[212:213], off
	v_lshl_add_u64 v[212:213], v[218:219], 0, s[14:15]
	s_mov_b32 m0, s44
	s_nop 0
	global_load_lds_dwordx4 v[212:213], off
	s_barrier
	s_waitcnt lgkmcnt(0)
	s_setprio 1
	s_waitcnt lgkmcnt(0)
	v_mfma_f32_16x16x32_bf16 v[60:63], v[144:147], v[164:167], v[60:63]
	v_mfma_f32_16x16x32_bf16 v[56:59], v[156:159], v[164:167], v[56:59]
	v_mfma_f32_16x16x32_bf16 v[44:47], v[144:147], v[172:175], v[44:47]
	v_mfma_f32_16x16x32_bf16 v[40:43], v[156:159], v[172:175], v[40:43]
	v_mfma_f32_16x16x32_bf16 v[28:31], v[144:147], v[180:183], v[28:31]
	v_mfma_f32_16x16x32_bf16 v[24:27], v[156:159], v[180:183], v[24:27]
	v_mfma_f32_16x16x32_bf16 v[12:15], v[144:147], v[188:191], v[12:15]
	v_mfma_f32_16x16x32_bf16 v[8:11], v[156:159], v[188:191], v[8:11]
	v_mfma_f32_16x16x32_bf16 v[60:63], v[152:155], v[168:171], v[60:63]
	v_mfma_f32_16x16x32_bf16 v[56:59], v[160:163], v[168:171], v[56:59]
	v_mfma_f32_16x16x32_bf16 v[44:47], v[152:155], v[176:179], v[44:47]
	v_mfma_f32_16x16x32_bf16 v[40:43], v[160:163], v[176:179], v[40:43]
	v_mfma_f32_16x16x32_bf16 v[28:31], v[152:155], v[184:187], v[28:31]
	v_mfma_f32_16x16x32_bf16 v[24:27], v[160:163], v[184:187], v[24:27]
	v_mfma_f32_16x16x32_bf16 v[12:15], v[152:155], v[192:195], v[12:15]
	v_mfma_f32_16x16x32_bf16 v[8:11], v[160:163], v[192:195], v[8:11]
	s_setprio 0
	s_barrier
	s_add_u32 s68, s72, 0x200080
	s_addc_u32 s69, s73, 0
	s_add_i32 s57, s67, s5
	v_lshl_add_u64 v[144:145], s[68:69], 0, v[128:129]
	s_mov_b32 m0, s57
	s_nop 0
	global_load_lds_dwordx4 v[144:145], off
	v_lshl_add_u64 v[144:145], s[68:69], 0, v[130:131]
	s_add_i32 m0, s57, 0x2000
	s_nop 0
	global_load_lds_dwordx4 v[144:145], off
	s_waitcnt vmcnt(6)
	s_barrier
	s_setprio 1
	v_mfma_f32_16x16x32_bf16 v[52:55], v[196:199], v[164:167], v[52:55]
	v_mfma_f32_16x16x32_bf16 v[48:51], v[204:207], v[164:167], v[48:51]
	v_mfma_f32_16x16x32_bf16 v[36:39], v[196:199], v[172:175], v[36:39]
	v_mfma_f32_16x16x32_bf16 v[32:35], v[204:207], v[172:175], v[32:35]
	v_mfma_f32_16x16x32_bf16 v[20:23], v[196:199], v[180:183], v[20:23]
	v_mfma_f32_16x16x32_bf16 v[16:19], v[204:207], v[180:183], v[16:19]
	v_mfma_f32_16x16x32_bf16 v[4:7], v[196:199], v[188:191], v[4:7]
	v_mfma_f32_16x16x32_bf16 v[0:3], v[204:207], v[188:191], v[0:3]
	v_mfma_f32_16x16x32_bf16 v[52:55], v[200:203], v[168:171], v[52:55]
	v_mfma_f32_16x16x32_bf16 v[48:51], v[208:211], v[168:171], v[48:51]
	v_mfma_f32_16x16x32_bf16 v[36:39], v[200:203], v[176:179], v[36:39]
	v_mfma_f32_16x16x32_bf16 v[32:35], v[208:211], v[176:179], v[32:35]
	v_mfma_f32_16x16x32_bf16 v[20:23], v[200:203], v[184:187], v[20:23]
	v_mfma_f32_16x16x32_bf16 v[16:19], v[208:211], v[184:187], v[16:19]
	v_mfma_f32_16x16x32_bf16 v[4:7], v[200:203], v[192:195], v[4:7]
	v_mfma_f32_16x16x32_bf16 v[0:3], v[208:211], v[192:195], v[0:3]
	s_setprio 0
	s_add_i32 s56, s56, 2
	s_add_u32 s54, s54, 0x100
	s_addc_u32 s55, s55, 0
	s_cmpk_gt_u32 s56, 0x7d
	s_mov_b64 s[68:69], s[70:71]
	s_barrier
	s_cbranch_scc0 .LBB0_530
	v_lshl_add_u32 v146, s24, 8, v133
	s_lshl_b32 s17, s66, 8
	s_ashr_i32 s19, s17, 31
	v_ashrrev_i32_e32 v147, 31, v146
	v_mov_b32_e32 v145, s19
	v_or_b32_e32 v144, s17, v132
	v_mov_b32_e32 v212, v146
	v_mov_b32_e32 v213, v147
	v_lshlrev_b64 v[214:215], 11, v[212:213]
	v_lshl_add_u64 v[214:215], v[214:215], 0, v[144:145]
	v_lshl_add_u64 v[152:153], v[214:215], 2, s[28:29]
	global_load_dwordx4 v[164:167], v[152:153], off
	global_load_dwordx4 v[168:171], v[152:153], off offset:64
	global_load_dwordx4 v[172:175], v[152:153], off offset:512
	global_load_dwordx4 v[176:179], v[152:153], off offset:576
	v_add_u32_e32 v212, 0x10, v146
	v_mov_b32_e32 v213, v147
	v_lshlrev_b64 v[214:215], 11, v[212:213]
	v_lshl_add_u64 v[214:215], v[214:215], 0, v[144:145]
	v_lshl_add_u64 v[152:153], v[214:215], 2, s[28:29]
	global_load_dwordx4 v[180:183], v[152:153], off
	global_load_dwordx4 v[184:187], v[152:153], off offset:64
	global_load_dwordx4 v[188:191], v[152:153], off offset:512
	global_load_dwordx4 v[192:195], v[152:153], off offset:576
	v_add_u32_e32 v212, 0x20, v146
	v_mov_b32_e32 v213, v147
	v_lshlrev_b64 v[214:215], 11, v[212:213]
	v_lshl_add_u64 v[214:215], v[214:215], 0, v[144:145]
	v_lshl_add_u64 v[152:153], v[214:215], 2, s[28:29]
	global_load_dwordx4 v[196:199], v[152:153], off
	global_load_dwordx4 v[200:203], v[152:153], off offset:64
	global_load_dwordx4 v[204:207], v[152:153], off offset:512
	global_load_dwordx4 v[208:211], v[152:153], off offset:576
	s_waitcnt vmcnt(8)
	v_mov_b32_e32 v212, v146
	v_mov_b32_e32 v213, v147
	v_lshlrev_b64 v[214:215], 11, v[212:213]
	v_lshl_add_u64 v[214:215], v[214:215], 0, v[144:145]
	v_lshl_add_u64 v[154:155], v[214:215], 2, s[28:29]
	v_lshl_add_u64 v[156:157], v[214:215], 1, s[40:41]
	v_pk_add_f32 v[126:127], v[126:127], v[166:167]
	v_pk_add_f32 v[124:125], v[124:125], v[164:165]
	v_cvt_pk_bf16_f32 v159, v126, v127
	v_cvt_pk_bf16_f32 v158, v124, v125
	global_store_dwordx4 v[154:155], v[124:127], off
	global_store_dwordx2 v[156:157], v[158:159], off
	s_nop 0
	v_mul_f32_e32 v125, v125, v125
	v_mul_f32_e32 v127, v127, v127
	v_fmac_f32_e32 v125, v124, v124
	v_fmac_f32_e32 v127, v126, v126
	v_add_f32_e32 v160, v125, v127
	v_pk_add_f32 v[122:123], v[122:123], v[170:171]
	v_pk_add_f32 v[120:121], v[120:121], v[168:169]
	v_cvt_pk_bf16_f32 v159, v122, v123
	v_cvt_pk_bf16_f32 v158, v120, v121
	global_store_dwordx4 v[154:155], v[120:123], off offset:64
	global_store_dwordx2 v[156:157], v[158:159], off offset:32
	s_nop 0
	v_mul_f32_e32 v121, v121, v121
	v_mul_f32_e32 v123, v123, v123
	v_fmac_f32_e32 v121, v120, v120
	v_fmac_f32_e32 v123, v122, v122
	v_add_f32_e32 v120, v121, v123
	v_add_f32_e32 v160, v160, v120
	v_pk_add_f32 v[118:119], v[118:119], v[174:175]
	v_pk_add_f32 v[116:117], v[116:117], v[172:173]
	v_cvt_pk_bf16_f32 v159, v118, v119
	v_cvt_pk_bf16_f32 v158, v116, v117
	global_store_dwordx4 v[154:155], v[116:119], off offset:512
	global_store_dwordx2 v[156:157], v[158:159], off offset:256
	s_nop 0
	v_mul_f32_e32 v117, v117, v117
	v_mul_f32_e32 v119, v119, v119
	v_fmac_f32_e32 v117, v116, v116
	v_fmac_f32_e32 v119, v118, v118
	v_add_f32_e32 v116, v117, v119
	v_add_f32_e32 v160, v160, v116
	v_pk_add_f32 v[114:115], v[114:115], v[178:179]
	v_pk_add_f32 v[112:113], v[112:113], v[176:177]
	v_cvt_pk_bf16_f32 v159, v114, v115
	v_cvt_pk_bf16_f32 v158, v112, v113
	global_store_dwordx4 v[154:155], v[112:115], off offset:576
	global_store_dwordx2 v[156:157], v[158:159], off offset:288
	s_nop 0
	v_mul_f32_e32 v113, v113, v113
	v_mul_f32_e32 v115, v115, v115
	v_fmac_f32_e32 v113, v112, v112
	v_fmac_f32_e32 v115, v114, v114
	v_add_f32_e32 v112, v113, v115
	v_add_f32_e32 v160, v160, v112
	v_mov_b32_e32 v161, v160
	s_nop 1
	v_permlane16_swap_b32_e32 v160, v161
	v_add_f32_e32 v160, v160, v161
	v_mov_b32_e32 v161, v160
	s_nop 1
	v_permlane32_swap_b32_e32 v160, v161
	s_and_saveexec_b64 s[24:25], s[8:9]
	v_lshl_add_u64 v[162:163], v[212:213], 2, s[64:65]
	v_add_f32_e32 v160, v160, v161
	global_atomic_add_f32 v[162:163], v160, off
	s_or_b64 exec, exec, s[24:25]
	v_add_u32_e32 v212, 0x30, v146
	v_mov_b32_e32 v213, v147
	v_lshlrev_b64 v[214:215], 11, v[212:213]
	v_lshl_add_u64 v[214:215], v[214:215], 0, v[144:145]
	v_lshl_add_u64 v[152:153], v[214:215], 2, s[28:29]
	global_load_dwordx4 v[164:167], v[152:153], off
	global_load_dwordx4 v[168:171], v[152:153], off offset:64
	global_load_dwordx4 v[172:175], v[152:153], off offset:512
	global_load_dwordx4 v[176:179], v[152:153], off offset:576
	s_waitcnt vmcnt(17)
	v_add_u32_e32 v212, 0x10, v146
	v_mov_b32_e32 v213, v147
	v_lshlrev_b64 v[214:215], 11, v[212:213]
	v_lshl_add_u64 v[214:215], v[214:215], 0, v[144:145]
	v_lshl_add_u64 v[154:155], v[214:215], 2, s[28:29]
	v_lshl_add_u64 v[156:157], v[214:215], 1, s[40:41]
	v_pk_add_f32 v[110:111], v[110:111], v[182:183]
	v_pk_add_f32 v[108:109], v[108:109], v[180:181]
	v_cvt_pk_bf16_f32 v159, v110, v111
	v_cvt_pk_bf16_f32 v158, v108, v109
	global_store_dwordx4 v[154:155], v[108:111], off
	global_store_dwordx2 v[156:157], v[158:159], off
	s_nop 0
	v_mul_f32_e32 v109, v109, v109
	v_mul_f32_e32 v111, v111, v111
	v_fmac_f32_e32 v109, v108, v108
	v_fmac_f32_e32 v111, v110, v110
	v_add_f32_e32 v160, v109, v111
	v_pk_add_f32 v[106:107], v[106:107], v[186:187]
	v_pk_add_f32 v[104:105], v[104:105], v[184:185]
	v_cvt_pk_bf16_f32 v159, v106, v107
	v_cvt_pk_bf16_f32 v158, v104, v105
	global_store_dwordx4 v[154:155], v[104:107], off offset:64
	global_store_dwordx2 v[156:157], v[158:159], off offset:32
	s_nop 0
	v_mul_f32_e32 v105, v105, v105
	v_mul_f32_e32 v107, v107, v107
	v_fmac_f32_e32 v105, v104, v104
	v_fmac_f32_e32 v107, v106, v106
	v_add_f32_e32 v104, v105, v107
	v_add_f32_e32 v160, v160, v104
	v_pk_add_f32 v[102:103], v[102:103], v[190:191]
	v_pk_add_f32 v[100:101], v[100:101], v[188:189]
	v_cvt_pk_bf16_f32 v159, v102, v103
	v_cvt_pk_bf16_f32 v158, v100, v101
	global_store_dwordx4 v[154:155], v[100:103], off offset:512
	global_store_dwordx2 v[156:157], v[158:159], off offset:256
	s_nop 0
	v_mul_f32_e32 v101, v101, v101
	v_mul_f32_e32 v103, v103, v103
	v_fmac_f32_e32 v101, v100, v100
	v_fmac_f32_e32 v103, v102, v102
	v_add_f32_e32 v100, v101, v103
	v_add_f32_e32 v160, v160, v100
	v_pk_add_f32 v[98:99], v[98:99], v[194:195]
	v_pk_add_f32 v[96:97], v[96:97], v[192:193]
	v_cvt_pk_bf16_f32 v159, v98, v99
	v_cvt_pk_bf16_f32 v158, v96, v97
	global_store_dwordx4 v[154:155], v[96:99], off offset:576
	global_store_dwordx2 v[156:157], v[158:159], off offset:288
	s_nop 0
	v_mul_f32_e32 v97, v97, v97
	v_mul_f32_e32 v99, v99, v99
	v_fmac_f32_e32 v97, v96, v96
	v_fmac_f32_e32 v99, v98, v98
	v_add_f32_e32 v96, v97, v99
	v_add_f32_e32 v160, v160, v96
	v_mov_b32_e32 v161, v160
	s_nop 1
	v_permlane16_swap_b32_e32 v160, v161
	v_add_f32_e32 v160, v160, v161
	v_mov_b32_e32 v161, v160
	s_nop 1
	v_permlane32_swap_b32_e32 v160, v161
	s_and_saveexec_b64 s[24:25], s[8:9]
	v_lshl_add_u64 v[162:163], v[212:213], 2, s[64:65]
	v_add_f32_e32 v160, v160, v161
	global_atomic_add_f32 v[162:163], v160, off
	s_or_b64 exec, exec, s[24:25]
	v_add_u32_e32 v212, 0x80, v146
	v_mov_b32_e32 v213, v147
	v_lshlrev_b64 v[214:215], 11, v[212:213]
	v_lshl_add_u64 v[214:215], v[214:215], 0, v[144:145]
	v_lshl_add_u64 v[152:153], v[214:215], 2, s[28:29]
	global_load_dwordx4 v[180:183], v[152:153], off
	global_load_dwordx4 v[184:187], v[152:153], off offset:64
	global_load_dwordx4 v[188:191], v[152:153], off offset:512
	global_load_dwordx4 v[192:195], v[152:153], off offset:576
	s_waitcnt vmcnt(26)
	v_add_u32_e32 v212, 0x20, v146
	v_mov_b32_e32 v213, v147
	v_lshlrev_b64 v[214:215], 11, v[212:213]
	v_lshl_add_u64 v[214:215], v[214:215], 0, v[144:145]
	v_lshl_add_u64 v[154:155], v[214:215], 2, s[28:29]
	v_lshl_add_u64 v[156:157], v[214:215], 1, s[40:41]
	v_pk_add_f32 v[94:95], v[94:95], v[198:199]
	v_pk_add_f32 v[92:93], v[92:93], v[196:197]
	v_cvt_pk_bf16_f32 v159, v94, v95
	v_cvt_pk_bf16_f32 v158, v92, v93
	global_store_dwordx4 v[154:155], v[92:95], off
	global_store_dwordx2 v[156:157], v[158:159], off
	s_nop 0
	v_mul_f32_e32 v93, v93, v93
	v_mul_f32_e32 v95, v95, v95
	v_fmac_f32_e32 v93, v92, v92
	v_fmac_f32_e32 v95, v94, v94
	v_add_f32_e32 v160, v93, v95
	v_pk_add_f32 v[90:91], v[90:91], v[202:203]
	v_pk_add_f32 v[88:89], v[88:89], v[200:201]
	v_cvt_pk_bf16_f32 v159, v90, v91
	v_cvt_pk_bf16_f32 v158, v88, v89
	global_store_dwordx4 v[154:155], v[88:91], off offset:64
	global_store_dwordx2 v[156:157], v[158:159], off offset:32
	s_nop 0
	v_mul_f32_e32 v89, v89, v89
	v_mul_f32_e32 v91, v91, v91
	v_fmac_f32_e32 v89, v88, v88
	v_fmac_f32_e32 v91, v90, v90
	v_add_f32_e32 v88, v89, v91
	v_add_f32_e32 v160, v160, v88
	v_pk_add_f32 v[86:87], v[86:87], v[206:207]
	v_pk_add_f32 v[84:85], v[84:85], v[204:205]
	v_cvt_pk_bf16_f32 v159, v86, v87
	v_cvt_pk_bf16_f32 v158, v84, v85
	global_store_dwordx4 v[154:155], v[84:87], off offset:512
	global_store_dwordx2 v[156:157], v[158:159], off offset:256
	s_nop 0
	v_mul_f32_e32 v85, v85, v85
	v_mul_f32_e32 v87, v87, v87
	v_fmac_f32_e32 v85, v84, v84
	v_fmac_f32_e32 v87, v86, v86
	v_add_f32_e32 v84, v85, v87
	v_add_f32_e32 v160, v160, v84
	v_pk_add_f32 v[82:83], v[82:83], v[210:211]
	v_pk_add_f32 v[80:81], v[80:81], v[208:209]
	v_cvt_pk_bf16_f32 v159, v82, v83
	v_cvt_pk_bf16_f32 v158, v80, v81
	global_store_dwordx4 v[154:155], v[80:83], off offset:576
	global_store_dwordx2 v[156:157], v[158:159], off offset:288
	s_nop 0
	v_mul_f32_e32 v81, v81, v81
	v_mul_f32_e32 v83, v83, v83
	v_fmac_f32_e32 v81, v80, v80
	v_fmac_f32_e32 v83, v82, v82
	v_add_f32_e32 v80, v81, v83
	v_add_f32_e32 v160, v160, v80
	v_mov_b32_e32 v161, v160
	s_nop 1
	v_permlane16_swap_b32_e32 v160, v161
	v_add_f32_e32 v160, v160, v161
	v_mov_b32_e32 v161, v160
	s_nop 1
	v_permlane32_swap_b32_e32 v160, v161
	s_and_saveexec_b64 s[24:25], s[8:9]
	v_lshl_add_u64 v[162:163], v[212:213], 2, s[64:65]
	v_add_f32_e32 v160, v160, v161
	global_atomic_add_f32 v[162:163], v160, off
	s_or_b64 exec, exec, s[24:25]
	v_add_u32_e32 v212, 0x90, v146
	v_mov_b32_e32 v213, v147
	v_lshlrev_b64 v[214:215], 11, v[212:213]
	v_lshl_add_u64 v[214:215], v[214:215], 0, v[144:145]
	v_lshl_add_u64 v[152:153], v[214:215], 2, s[28:29]
	global_load_dwordx4 v[196:199], v[152:153], off
	global_load_dwordx4 v[200:203], v[152:153], off offset:64
	global_load_dwordx4 v[204:207], v[152:153], off offset:512
	global_load_dwordx4 v[208:211], v[152:153], off offset:576
	s_waitcnt vmcnt(26)
	v_add_u32_e32 v212, 0x30, v146
	v_mov_b32_e32 v213, v147
	v_lshlrev_b64 v[214:215], 11, v[212:213]
	v_lshl_add_u64 v[214:215], v[214:215], 0, v[144:145]
	v_lshl_add_u64 v[154:155], v[214:215], 2, s[28:29]
	v_lshl_add_u64 v[156:157], v[214:215], 1, s[40:41]
	v_pk_add_f32 v[78:79], v[78:79], v[166:167]
	v_pk_add_f32 v[76:77], v[76:77], v[164:165]
	v_cvt_pk_bf16_f32 v159, v78, v79
	v_cvt_pk_bf16_f32 v158, v76, v77
	global_store_dwordx4 v[154:155], v[76:79], off
	global_store_dwordx2 v[156:157], v[158:159], off
	s_nop 0
	v_mul_f32_e32 v77, v77, v77
	v_mul_f32_e32 v79, v79, v79
	v_fmac_f32_e32 v77, v76, v76
	v_fmac_f32_e32 v79, v78, v78
	v_add_f32_e32 v160, v77, v79
	v_pk_add_f32 v[74:75], v[74:75], v[170:171]
	v_pk_add_f32 v[72:73], v[72:73], v[168:169]
	v_cvt_pk_bf16_f32 v159, v74, v75
	v_cvt_pk_bf16_f32 v158, v72, v73
	global_store_dwordx4 v[154:155], v[72:75], off offset:64
	global_store_dwordx2 v[156:157], v[158:159], off offset:32
	s_nop 0
	v_mul_f32_e32 v73, v73, v73
	v_mul_f32_e32 v75, v75, v75
	v_fmac_f32_e32 v73, v72, v72
	v_fmac_f32_e32 v75, v74, v74
	v_add_f32_e32 v72, v73, v75
	v_add_f32_e32 v160, v160, v72
	v_pk_add_f32 v[70:71], v[70:71], v[174:175]
	v_pk_add_f32 v[68:69], v[68:69], v[172:173]
	v_cvt_pk_bf16_f32 v159, v70, v71
	v_cvt_pk_bf16_f32 v158, v68, v69
	global_store_dwordx4 v[154:155], v[68:71], off offset:512
	global_store_dwordx2 v[156:157], v[158:159], off offset:256
	s_nop 0
	v_mul_f32_e32 v69, v69, v69
	v_mul_f32_e32 v71, v71, v71
	v_fmac_f32_e32 v69, v68, v68
	v_fmac_f32_e32 v71, v70, v70
	v_add_f32_e32 v68, v69, v71
	v_add_f32_e32 v160, v160, v68
	v_pk_add_f32 v[66:67], v[66:67], v[178:179]
	v_pk_add_f32 v[64:65], v[64:65], v[176:177]
	v_cvt_pk_bf16_f32 v159, v66, v67
	v_cvt_pk_bf16_f32 v158, v64, v65
	global_store_dwordx4 v[154:155], v[64:67], off offset:576
	global_store_dwordx2 v[156:157], v[158:159], off offset:288
	s_nop 0
	v_mul_f32_e32 v65, v65, v65
	v_mul_f32_e32 v67, v67, v67
	v_fmac_f32_e32 v65, v64, v64
	v_fmac_f32_e32 v67, v66, v66
	v_add_f32_e32 v64, v65, v67
	v_add_f32_e32 v160, v160, v64
	v_mov_b32_e32 v161, v160
	s_nop 1
	v_permlane16_swap_b32_e32 v160, v161
	v_add_f32_e32 v160, v160, v161
	v_mov_b32_e32 v161, v160
	s_nop 1
	v_permlane32_swap_b32_e32 v160, v161
	s_and_saveexec_b64 s[24:25], s[8:9]
	v_lshl_add_u64 v[162:163], v[212:213], 2, s[64:65]
	v_add_f32_e32 v160, v160, v161
	global_atomic_add_f32 v[162:163], v160, off
	s_or_b64 exec, exec, s[24:25]
	v_add_u32_e32 v212, 0xa0, v146
	v_mov_b32_e32 v213, v147
	v_lshlrev_b64 v[214:215], 11, v[212:213]
	v_lshl_add_u64 v[214:215], v[214:215], 0, v[144:145]
	v_lshl_add_u64 v[152:153], v[214:215], 2, s[28:29]
	global_load_dwordx4 v[164:167], v[152:153], off
	global_load_dwordx4 v[168:171], v[152:153], off offset:64
	global_load_dwordx4 v[172:175], v[152:153], off offset:512
	global_load_dwordx4 v[176:179], v[152:153], off offset:576
	s_waitcnt vmcnt(26)
	v_add_u32_e32 v212, 0x80, v146
	v_mov_b32_e32 v213, v147
	v_lshlrev_b64 v[214:215], 11, v[212:213]
	v_lshl_add_u64 v[214:215], v[214:215], 0, v[144:145]
	v_lshl_add_u64 v[154:155], v[214:215], 2, s[28:29]
	v_lshl_add_u64 v[156:157], v[214:215], 1, s[40:41]
	v_pk_add_f32 v[62:63], v[62:63], v[182:183]
	v_pk_add_f32 v[60:61], v[60:61], v[180:181]
	v_cvt_pk_bf16_f32 v159, v62, v63
	v_cvt_pk_bf16_f32 v158, v60, v61
	global_store_dwordx4 v[154:155], v[60:63], off
	global_store_dwordx2 v[156:157], v[158:159], off
	s_nop 0
	v_mul_f32_e32 v61, v61, v61
	v_mul_f32_e32 v63, v63, v63
	v_fmac_f32_e32 v61, v60, v60
	v_fmac_f32_e32 v63, v62, v62
	v_add_f32_e32 v160, v61, v63
	v_pk_add_f32 v[58:59], v[58:59], v[186:187]
	v_pk_add_f32 v[56:57], v[56:57], v[184:185]
	v_cvt_pk_bf16_f32 v159, v58, v59
	v_cvt_pk_bf16_f32 v158, v56, v57
	global_store_dwordx4 v[154:155], v[56:59], off offset:64
	global_store_dwordx2 v[156:157], v[158:159], off offset:32
	s_nop 0
	v_mul_f32_e32 v57, v57, v57
	v_mul_f32_e32 v59, v59, v59
	v_fmac_f32_e32 v57, v56, v56
	v_fmac_f32_e32 v59, v58, v58
	v_add_f32_e32 v56, v57, v59
	v_add_f32_e32 v160, v160, v56
	v_pk_add_f32 v[54:55], v[54:55], v[190:191]
	v_pk_add_f32 v[52:53], v[52:53], v[188:189]
	v_cvt_pk_bf16_f32 v159, v54, v55
	v_cvt_pk_bf16_f32 v158, v52, v53
	global_store_dwordx4 v[154:155], v[52:55], off offset:512
	global_store_dwordx2 v[156:157], v[158:159], off offset:256
	s_nop 0
	v_mul_f32_e32 v53, v53, v53
	v_mul_f32_e32 v55, v55, v55
	v_fmac_f32_e32 v53, v52, v52
	v_fmac_f32_e32 v55, v54, v54
	v_add_f32_e32 v52, v53, v55
	v_add_f32_e32 v160, v160, v52
	v_pk_add_f32 v[50:51], v[50:51], v[194:195]
	v_pk_add_f32 v[48:49], v[48:49], v[192:193]
	v_cvt_pk_bf16_f32 v159, v50, v51
	v_cvt_pk_bf16_f32 v158, v48, v49
	global_store_dwordx4 v[154:155], v[48:51], off offset:576
	global_store_dwordx2 v[156:157], v[158:159], off offset:288
	s_nop 0
	v_mul_f32_e32 v49, v49, v49
	v_mul_f32_e32 v51, v51, v51
	v_fmac_f32_e32 v49, v48, v48
	v_fmac_f32_e32 v51, v50, v50
	v_add_f32_e32 v48, v49, v51
	v_add_f32_e32 v160, v160, v48
	v_mov_b32_e32 v161, v160
	s_nop 1
	v_permlane16_swap_b32_e32 v160, v161
	v_add_f32_e32 v160, v160, v161
	v_mov_b32_e32 v161, v160
	s_nop 1
	v_permlane32_swap_b32_e32 v160, v161
	s_and_saveexec_b64 s[24:25], s[8:9]
	v_lshl_add_u64 v[162:163], v[212:213], 2, s[64:65]
	v_add_f32_e32 v160, v160, v161
	global_atomic_add_f32 v[162:163], v160, off
	s_or_b64 exec, exec, s[24:25]
	v_add_u32_e32 v212, 0xb0, v146
	v_mov_b32_e32 v213, v147
	v_lshlrev_b64 v[214:215], 11, v[212:213]
	v_lshl_add_u64 v[214:215], v[214:215], 0, v[144:145]
	v_lshl_add_u64 v[152:153], v[214:215], 2, s[28:29]
	global_load_dwordx4 v[180:183], v[152:153], off
	global_load_dwordx4 v[184:187], v[152:153], off offset:64
	global_load_dwordx4 v[188:191], v[152:153], off offset:512
	global_load_dwordx4 v[192:195], v[152:153], off offset:576
	s_waitcnt vmcnt(26)
	v_add_u32_e32 v212, 0x90, v146
	v_mov_b32_e32 v213, v147
	v_lshlrev_b64 v[214:215], 11, v[212:213]
	v_lshl_add_u64 v[214:215], v[214:215], 0, v[144:145]
	v_lshl_add_u64 v[154:155], v[214:215], 2, s[28:29]
	v_lshl_add_u64 v[156:157], v[214:215], 1, s[40:41]
	v_pk_add_f32 v[46:47], v[46:47], v[198:199]
	v_pk_add_f32 v[44:45], v[44:45], v[196:197]
	v_cvt_pk_bf16_f32 v159, v46, v47
	v_cvt_pk_bf16_f32 v158, v44, v45
	global_store_dwordx4 v[154:155], v[44:47], off
	global_store_dwordx2 v[156:157], v[158:159], off
	s_nop 0
	v_mul_f32_e32 v45, v45, v45
	v_mul_f32_e32 v47, v47, v47
	v_fmac_f32_e32 v45, v44, v44
	v_fmac_f32_e32 v47, v46, v46
	v_add_f32_e32 v160, v45, v47
	v_pk_add_f32 v[42:43], v[42:43], v[202:203]
	v_pk_add_f32 v[40:41], v[40:41], v[200:201]
	v_cvt_pk_bf16_f32 v159, v42, v43
	v_cvt_pk_bf16_f32 v158, v40, v41
	global_store_dwordx4 v[154:155], v[40:43], off offset:64
	global_store_dwordx2 v[156:157], v[158:159], off offset:32
	s_nop 0
	v_mul_f32_e32 v41, v41, v41
	v_mul_f32_e32 v43, v43, v43
	v_fmac_f32_e32 v41, v40, v40
	v_fmac_f32_e32 v43, v42, v42
	v_add_f32_e32 v40, v41, v43
	v_add_f32_e32 v160, v160, v40
	v_pk_add_f32 v[38:39], v[38:39], v[206:207]
	v_pk_add_f32 v[36:37], v[36:37], v[204:205]
	v_cvt_pk_bf16_f32 v159, v38, v39
	v_cvt_pk_bf16_f32 v158, v36, v37
	global_store_dwordx4 v[154:155], v[36:39], off offset:512
	global_store_dwordx2 v[156:157], v[158:159], off offset:256
	s_nop 0
	v_mul_f32_e32 v37, v37, v37
	v_mul_f32_e32 v39, v39, v39
	v_fmac_f32_e32 v37, v36, v36
	v_fmac_f32_e32 v39, v38, v38
	v_add_f32_e32 v36, v37, v39
	v_add_f32_e32 v160, v160, v36
	v_pk_add_f32 v[34:35], v[34:35], v[210:211]
	v_pk_add_f32 v[32:33], v[32:33], v[208:209]
	v_cvt_pk_bf16_f32 v159, v34, v35
	v_cvt_pk_bf16_f32 v158, v32, v33
	global_store_dwordx4 v[154:155], v[32:35], off offset:576
	global_store_dwordx2 v[156:157], v[158:159], off offset:288
	s_nop 0
	v_mul_f32_e32 v33, v33, v33
	v_mul_f32_e32 v35, v35, v35
	v_fmac_f32_e32 v33, v32, v32
	v_fmac_f32_e32 v35, v34, v34
	v_add_f32_e32 v32, v33, v35
	v_add_f32_e32 v160, v160, v32
	v_mov_b32_e32 v161, v160
	s_nop 1
	v_permlane16_swap_b32_e32 v160, v161
	v_add_f32_e32 v160, v160, v161
	v_mov_b32_e32 v161, v160
	s_nop 1
	v_permlane32_swap_b32_e32 v160, v161
	s_and_saveexec_b64 s[24:25], s[8:9]
	v_lshl_add_u64 v[162:163], v[212:213], 2, s[64:65]
	v_add_f32_e32 v160, v160, v161
	global_atomic_add_f32 v[162:163], v160, off
	s_or_b64 exec, exec, s[24:25]
	s_waitcnt vmcnt(22)
	v_add_u32_e32 v212, 0xa0, v146
	v_mov_b32_e32 v213, v147
	v_lshlrev_b64 v[214:215], 11, v[212:213]
	v_lshl_add_u64 v[214:215], v[214:215], 0, v[144:145]
	v_lshl_add_u64 v[154:155], v[214:215], 2, s[28:29]
	v_lshl_add_u64 v[156:157], v[214:215], 1, s[40:41]
	v_pk_add_f32 v[30:31], v[30:31], v[166:167]
	v_pk_add_f32 v[28:29], v[28:29], v[164:165]
	v_cvt_pk_bf16_f32 v159, v30, v31
	v_cvt_pk_bf16_f32 v158, v28, v29
	global_store_dwordx4 v[154:155], v[28:31], off
	global_store_dwordx2 v[156:157], v[158:159], off
	s_nop 0
	v_mul_f32_e32 v29, v29, v29
	v_mul_f32_e32 v31, v31, v31
	v_fmac_f32_e32 v29, v28, v28
	v_fmac_f32_e32 v31, v30, v30
	v_add_f32_e32 v160, v29, v31
	v_pk_add_f32 v[26:27], v[26:27], v[170:171]
	v_pk_add_f32 v[24:25], v[24:25], v[168:169]
	v_cvt_pk_bf16_f32 v159, v26, v27
	v_cvt_pk_bf16_f32 v158, v24, v25
	global_store_dwordx4 v[154:155], v[24:27], off offset:64
	global_store_dwordx2 v[156:157], v[158:159], off offset:32
	s_nop 0
	v_mul_f32_e32 v25, v25, v25
	v_mul_f32_e32 v27, v27, v27
	v_fmac_f32_e32 v25, v24, v24
	v_fmac_f32_e32 v27, v26, v26
	v_add_f32_e32 v24, v25, v27
	v_add_f32_e32 v160, v160, v24
	v_pk_add_f32 v[22:23], v[22:23], v[174:175]
	v_pk_add_f32 v[20:21], v[20:21], v[172:173]
	v_cvt_pk_bf16_f32 v159, v22, v23
	v_cvt_pk_bf16_f32 v158, v20, v21
	global_store_dwordx4 v[154:155], v[20:23], off offset:512
	global_store_dwordx2 v[156:157], v[158:159], off offset:256
	s_nop 0
	v_mul_f32_e32 v21, v21, v21
	v_mul_f32_e32 v23, v23, v23
	v_fmac_f32_e32 v21, v20, v20
	v_fmac_f32_e32 v23, v22, v22
	v_add_f32_e32 v20, v21, v23
	v_add_f32_e32 v160, v160, v20
	v_pk_add_f32 v[18:19], v[18:19], v[178:179]
	v_pk_add_f32 v[16:17], v[16:17], v[176:177]
	v_cvt_pk_bf16_f32 v159, v18, v19
	v_cvt_pk_bf16_f32 v158, v16, v17
	global_store_dwordx4 v[154:155], v[16:19], off offset:576
	global_store_dwordx2 v[156:157], v[158:159], off offset:288
	s_nop 0
	v_mul_f32_e32 v17, v17, v17
	v_mul_f32_e32 v19, v19, v19
	v_fmac_f32_e32 v17, v16, v16
	v_fmac_f32_e32 v19, v18, v18
	v_add_f32_e32 v16, v17, v19
	v_add_f32_e32 v160, v160, v16
	v_mov_b32_e32 v161, v160
	s_nop 1
	v_permlane16_swap_b32_e32 v160, v161
	v_add_f32_e32 v160, v160, v161
	v_mov_b32_e32 v161, v160
	s_nop 1
	v_permlane32_swap_b32_e32 v160, v161
	s_and_saveexec_b64 s[24:25], s[8:9]
	v_lshl_add_u64 v[162:163], v[212:213], 2, s[64:65]
	v_add_f32_e32 v160, v160, v161
	global_atomic_add_f32 v[162:163], v160, off
	s_or_b64 exec, exec, s[24:25]
	s_waitcnt vmcnt(18)
	v_add_u32_e32 v212, 0xb0, v146
	v_mov_b32_e32 v213, v147
	v_lshlrev_b64 v[214:215], 11, v[212:213]
	v_lshl_add_u64 v[214:215], v[214:215], 0, v[144:145]
	v_lshl_add_u64 v[154:155], v[214:215], 2, s[28:29]
	v_lshl_add_u64 v[156:157], v[214:215], 1, s[40:41]
	v_pk_add_f32 v[14:15], v[14:15], v[182:183]
	v_pk_add_f32 v[12:13], v[12:13], v[180:181]
	v_cvt_pk_bf16_f32 v159, v14, v15
	v_cvt_pk_bf16_f32 v158, v12, v13
	global_store_dwordx4 v[154:155], v[12:15], off
	global_store_dwordx2 v[156:157], v[158:159], off
	s_nop 0
	v_mul_f32_e32 v13, v13, v13
	v_mul_f32_e32 v15, v15, v15
	v_fmac_f32_e32 v13, v12, v12
	v_fmac_f32_e32 v15, v14, v14
	v_add_f32_e32 v160, v13, v15
	v_pk_add_f32 v[10:11], v[10:11], v[186:187]
	v_pk_add_f32 v[8:9], v[8:9], v[184:185]
	v_cvt_pk_bf16_f32 v159, v10, v11
	v_cvt_pk_bf16_f32 v158, v8, v9
	global_store_dwordx4 v[154:155], v[8:11], off offset:64
	global_store_dwordx2 v[156:157], v[158:159], off offset:32
	s_nop 0
	v_mul_f32_e32 v9, v9, v9
	v_mul_f32_e32 v11, v11, v11
	v_fmac_f32_e32 v9, v8, v8
	v_fmac_f32_e32 v11, v10, v10
	v_add_f32_e32 v8, v9, v11
	v_add_f32_e32 v160, v160, v8
	v_pk_add_f32 v[6:7], v[6:7], v[190:191]
	v_pk_add_f32 v[4:5], v[4:5], v[188:189]
	v_cvt_pk_bf16_f32 v159, v6, v7
	v_cvt_pk_bf16_f32 v158, v4, v5
	global_store_dwordx4 v[154:155], v[4:7], off offset:512
	global_store_dwordx2 v[156:157], v[158:159], off offset:256
	s_nop 0
	v_mul_f32_e32 v5, v5, v5
	v_mul_f32_e32 v7, v7, v7
	v_fmac_f32_e32 v5, v4, v4
	v_fmac_f32_e32 v7, v6, v6
	v_add_f32_e32 v4, v5, v7
	v_add_f32_e32 v160, v160, v4
	v_pk_add_f32 v[2:3], v[2:3], v[194:195]
	v_pk_add_f32 v[0:1], v[0:1], v[192:193]
	v_cvt_pk_bf16_f32 v159, v2, v3
	v_cvt_pk_bf16_f32 v158, v0, v1
	global_store_dwordx4 v[154:155], v[0:3], off offset:576
	global_store_dwordx2 v[156:157], v[158:159], off offset:288
	s_nop 0
	v_mul_f32_e32 v1, v1, v1
	v_mul_f32_e32 v3, v3, v3
	v_fmac_f32_e32 v1, v0, v0
	v_fmac_f32_e32 v3, v2, v2
	v_add_f32_e32 v0, v1, v3
	v_add_f32_e32 v160, v160, v0
	v_mov_b32_e32 v161, v160
	s_nop 1
	v_permlane16_swap_b32_e32 v160, v161
	v_add_f32_e32 v160, v160, v161
	v_mov_b32_e32 v161, v160
	s_nop 1
	v_permlane32_swap_b32_e32 v160, v161
	s_and_saveexec_b64 s[24:25], s[8:9]
	v_lshl_add_u64 v[162:163], v[212:213], 2, s[64:65]
	v_add_f32_e32 v160, v160, v161
	global_atomic_add_f32 v[162:163], v160, off
	s_or_b64 exec, exec, s[24:25]
	s_branch .LBB0_522

.Las_pre:
	s_mov_b32 s74, 0
	s_mov_b32 s75, 0x9000
	v_mov_b32_e32 v231, 0x1b100
	v_mov_b32_e32 v230, 1
	s_mov_b32 s84, 0
	s_mov_b32 s85, 0
	s_cmp_lt_u32 0, s46
	s_cbranch_scc0 .Las_loop
	v_lshl_add_u64 v[102:103], v[152:153], 0, v[134:135]
	v_add_co_u32_e32 v104, vcc, 0xe104000, v102
	v_lshl_add_u64 v[110:111], v[154:155], 0, v[134:135]
	v_addc_co_u32_e32 v105, vcc, 0, v103, vcc
	v_add_co_u32_e32 v106, vcc, 0xf104000, v102
	s_nop 1
	v_addc_co_u32_e32 v107, vcc, 0, v103, vcc
	v_add_co_u32_e32 v112, vcc, 0xe104000, v110
	global_load_dwordx4 v[102:105], v[104:105], off
	s_nop 1
	global_load_dwordx4 v[106:109], v[106:107], off
	v_addc_co_u32_e32 v113, vcc, 0, v111, vcc
	v_add_co_u32_e32 v114, vcc, 0xf104000, v110
	s_nop 1
	v_addc_co_u32_e32 v115, vcc, 0, v111, vcc
	global_load_dwordx4 v[110:113], v[112:113], off
	s_nop 0
	global_load_dwordx4 v[114:117], v[114:115], off
.Las_loop:
	s_cmp_lt_u32 s54, s46
	s_cselect_b64 s[22:23], -1, 0
	s_cbranch_scc0 .Las_nostage
	s_cmp_lt_u32 s54, 2
	s_cbranch_scc1 .Las_s1_go
	s_cmp_ge_u32 s84, 8
	s_cbranch_scc1 .Las_s1_go
	s_cmp_lg_u32 s77, 0
	s_cbranch_scc1 .Lpoll_done_s1
	s_mov_b32 s78, 0

.Las_nostage:
	ds_read2_b32 v[238:239], v231 offset0:127 offset1:1
	s_add_i32 s55, s74, 16
	s_cmp_eq_u32 s54, 0
	s_cbranch_scc1 .LBB0_1535
	s_cmp_lt_u32 s54, s46
	s_cbranch_scc1 .Las_fast
	s_cmp_ge_u32 s85, 8
	s_cbranch_scc1 .LBB0_1535
	s_cmp_lg_u32 s77, 0
	s_cbranch_scc1 .Lpoll_done_slow
	s_mov_b32 s78, 0

.Las_fast:
	s_lshl_b64 s[56:57], 1, s54
	s_cmp_gt_u32 s54, 63
	s_cselect_b64 s[8:9], -1, 0
	s_cselect_b64 s[68:69], s[62:63], s[60:61]
	s_cselect_b64 s[70:71], s[66:67], s[64:65]
	s_and_b64 s[68:69], s[68:69], s[56:57]
	s_and_b64 s[70:71], s[70:71], s[56:57]
	s_or_b64 s[82:83], s[68:69], s[70:71]
	s_cbranch_scc0 .Las_s3
	s_cmp_ge_u32 s85, 8
	s_cbranch_scc1 .Lpoll_done_fast
	s_cmp_lg_u32 s77, 0
	s_cbranch_scc1 .Lpoll_done_fast
	s_mov_b32 s78, 0

.Las_s3:
	s_waitcnt lgkmcnt(0)
	v_readfirstlane_b32 s84, v238
	v_readfirstlane_b32 s85, v239
	s_mov_b64 exec, 1
	ds_add_u32 v231, v230 offset:512
	s_mov_b64 exec, -1
	s_add_i32 s54, s54, 1
	s_add_i32 s18, s18, 64
	v_lshl_add_u64 v[152:153], v[152:153], 0, s[20:21]
	v_lshl_add_u64 v[154:155], v[154:155], 0, s[20:21]
	v_add_u32_e32 v231, 4, v231
	s_mov_b32 s74, s75
	s_add_i32 s75, s75, 0x9000
	s_cmp_eq_u32 s75, 0x1b000
	s_cselect_b32 s75, 0, s75
	s_cmp_le_u32 s54, s46
	s_cbranch_scc1 .Las_loop
	s_waitcnt lgkmcnt(0)
	s_barrier
	s_branch .LBB0_1530

.LBB0_1623:
	ds_read_b128 v[144:147], v148
	ds_read_b128 v[152:155], v148 offset:1024
	ds_read_b128 v[156:159], v148 offset:2048
	ds_read_b128 v[160:163], v148 offset:3072
	s_add_u32 s60, s58, 0x100
	s_addc_u32 s61, s59, 0
	s_cmp_eq_u32 s69, 28
	s_cselect_b32 s65, s17, s61
	s_cselect_b32 s64, s23, s60
	s_cselect_b32 s63, s15, s68
	s_cselect_b32 s62, s66, s67
	v_lshl_add_u64 v[196:197], s[58:59], 0, v[134:135]
	s_add_i32 m0, s26, 0xc000
	ds_read_b128 v[164:167], v149
	ds_read_b128 v[168:171], v149 offset:1024
	ds_read_b128 v[172:175], v149 offset:2048
	ds_read_b128 v[176:179], v149 offset:3072
	ds_read_b128 v[180:183], v149 offset:4096
	ds_read_b128 v[184:187], v149 offset:5120
	ds_read_b128 v[188:191], v149 offset:6144
	ds_read_b128 v[192:195], v149 offset:7168
	global_load_lds_dwordx4 v[196:197], off
	v_lshl_add_u64 v[196:197], s[58:59], 0, v[138:139]
	s_add_i32 m0, s26, 0xe000
	s_nop 0
	global_load_lds_dwordx4 v[196:197], off
	s_waitcnt lgkmcnt(8)
	s_barrier
	s_waitcnt lgkmcnt(0)
	s_setprio 1
	s_waitcnt lgkmcnt(0)
	v_mfma_f32_16x16x32_bf16 v[124:127], v[144:147], v[164:167], v[124:127]
	v_mfma_f32_16x16x32_bf16 v[120:123], v[156:159], v[164:167], v[120:123]
	v_mfma_f32_16x16x32_bf16 v[108:111], v[144:147], v[172:175], v[108:111]
	v_mfma_f32_16x16x32_bf16 v[104:107], v[156:159], v[172:175], v[104:107]
	v_mfma_f32_16x16x32_bf16 v[92:95], v[144:147], v[180:183], v[92:95]
	v_mfma_f32_16x16x32_bf16 v[88:91], v[156:159], v[180:183], v[88:91]
	v_mfma_f32_16x16x32_bf16 v[76:79], v[144:147], v[188:191], v[76:79]
	v_mfma_f32_16x16x32_bf16 v[72:75], v[156:159], v[188:191], v[72:75]
	v_mfma_f32_16x16x32_bf16 v[124:127], v[152:155], v[168:171], v[124:127]
	v_mfma_f32_16x16x32_bf16 v[120:123], v[160:163], v[168:171], v[120:123]
	v_mfma_f32_16x16x32_bf16 v[108:111], v[152:155], v[176:179], v[108:111]
	v_mfma_f32_16x16x32_bf16 v[104:107], v[160:163], v[176:179], v[104:107]
	v_mfma_f32_16x16x32_bf16 v[92:95], v[152:155], v[184:187], v[92:95]
	v_mfma_f32_16x16x32_bf16 v[88:91], v[160:163], v[184:187], v[88:91]
	v_mfma_f32_16x16x32_bf16 v[76:79], v[152:155], v[192:195], v[76:79]
	v_mfma_f32_16x16x32_bf16 v[72:75], v[160:163], v[192:195], v[72:75]
	s_setprio 0
	s_barrier
	s_add_i32 s58, s55, s7
	v_lshl_add_u64 v[212:213], s[62:63], 0, v[128:129]
	s_mov_b32 m0, s58
	ds_read_b128 v[196:199], v150
	ds_read_b128 v[200:203], v150 offset:1024
	ds_read_b128 v[204:207], v150 offset:2048
	ds_read_b128 v[208:211], v150 offset:3072
	global_load_lds_dwordx4 v[212:213], off
	v_lshl_add_u64 v[214:215], s[62:63], 0, v[130:131]
	s_add_i32 m0, s58, 0x2000
	s_nop 0
	global_load_lds_dwordx4 v[214:215], off
	s_barrier
	s_waitcnt lgkmcnt(0)
	s_setprio 1
	s_waitcnt lgkmcnt(0)
	v_mfma_f32_16x16x32_bf16 v[116:119], v[196:199], v[164:167], v[116:119]
	v_mfma_f32_16x16x32_bf16 v[112:115], v[204:207], v[164:167], v[112:115]
	v_mfma_f32_16x16x32_bf16 v[100:103], v[196:199], v[172:175], v[100:103]
	v_mfma_f32_16x16x32_bf16 v[96:99], v[204:207], v[172:175], v[96:99]
	v_mfma_f32_16x16x32_bf16 v[84:87], v[196:199], v[180:183], v[84:87]
	v_mfma_f32_16x16x32_bf16 v[80:83], v[204:207], v[180:183], v[80:83]
	v_mfma_f32_16x16x32_bf16 v[68:71], v[196:199], v[188:191], v[68:71]
	v_mfma_f32_16x16x32_bf16 v[64:67], v[204:207], v[188:191], v[64:67]
	v_mfma_f32_16x16x32_bf16 v[116:119], v[200:203], v[168:171], v[116:119]
	v_mfma_f32_16x16x32_bf16 v[112:115], v[208:211], v[168:171], v[112:115]
	v_mfma_f32_16x16x32_bf16 v[100:103], v[200:203], v[176:179], v[100:103]
	v_mfma_f32_16x16x32_bf16 v[96:99], v[208:211], v[176:179], v[96:99]
	v_mfma_f32_16x16x32_bf16 v[84:87], v[200:203], v[184:187], v[84:87]
	v_mfma_f32_16x16x32_bf16 v[80:83], v[208:211], v[184:187], v[80:83]
	v_mfma_f32_16x16x32_bf16 v[68:71], v[200:203], v[192:195], v[68:71]
	v_mfma_f32_16x16x32_bf16 v[64:67], v[208:211], v[192:195], v[64:67]
	s_setprio 0
	s_mov_b32 m0, s26
	v_lshl_add_u64 v[216:217], s[64:65], 0, v[128:129]
	s_barrier
	ds_read_b128 v[164:167], v149 offset:16384
	ds_read_b128 v[168:171], v149 offset:17408
	ds_read_b128 v[172:175], v149 offset:18432
	ds_read_b128 v[176:179], v149 offset:19456
	ds_read_b128 v[180:183], v149 offset:20480
	ds_read_b128 v[184:187], v149 offset:21504
	ds_read_b128 v[188:191], v149 offset:22528
	ds_read_b128 v[192:195], v149 offset:23552
	global_load_lds_dwordx4 v[216:217], off
	v_lshl_add_u64 v[218:219], s[64:65], 0, v[130:131]
	s_mov_b32 m0, s27
	s_nop 0
	global_load_lds_dwordx4 v[218:219], off
	s_barrier
	s_waitcnt lgkmcnt(0)
	s_setprio 1
	s_waitcnt lgkmcnt(0)
	v_mfma_f32_16x16x32_bf16 v[60:63], v[144:147], v[164:167], v[60:63]
	v_mfma_f32_16x16x32_bf16 v[56:59], v[156:159], v[164:167], v[56:59]
	v_mfma_f32_16x16x32_bf16 v[44:47], v[144:147], v[172:175], v[44:47]
	v_mfma_f32_16x16x32_bf16 v[40:43], v[156:159], v[172:175], v[40:43]
	v_mfma_f32_16x16x32_bf16 v[28:31], v[144:147], v[180:183], v[28:31]
	v_mfma_f32_16x16x32_bf16 v[24:27], v[156:159], v[180:183], v[24:27]
	v_mfma_f32_16x16x32_bf16 v[12:15], v[144:147], v[188:191], v[12:15]
	v_mfma_f32_16x16x32_bf16 v[8:11], v[156:159], v[188:191], v[8:11]
	v_mfma_f32_16x16x32_bf16 v[60:63], v[152:155], v[168:171], v[60:63]
	v_mfma_f32_16x16x32_bf16 v[56:59], v[160:163], v[168:171], v[56:59]
	v_mfma_f32_16x16x32_bf16 v[44:47], v[152:155], v[176:179], v[44:47]
	v_mfma_f32_16x16x32_bf16 v[40:43], v[160:163], v[176:179], v[40:43]
	v_mfma_f32_16x16x32_bf16 v[28:31], v[152:155], v[184:187], v[28:31]
	v_mfma_f32_16x16x32_bf16 v[24:27], v[160:163], v[184:187], v[24:27]
	v_mfma_f32_16x16x32_bf16 v[12:15], v[152:155], v[192:195], v[12:15]
	v_mfma_f32_16x16x32_bf16 v[8:11], v[160:163], v[192:195], v[8:11]
	s_setprio 0
	s_barrier
	s_add_u32 s58, s62, 0x80000
	s_addc_u32 s59, s63, 0
	s_add_i32 s70, s57, s7
	v_lshl_add_u64 v[144:145], s[58:59], 0, v[128:129]
	s_mov_b32 m0, s70
	s_nop 0
	global_load_lds_dwordx4 v[144:145], off
	v_lshl_add_u64 v[144:145], s[58:59], 0, v[130:131]
	s_add_i32 m0, s70, 0x2000
	s_nop 0
	global_load_lds_dwordx4 v[144:145], off
	s_waitcnt vmcnt(6)
	s_barrier
	s_setprio 1
	v_mfma_f32_16x16x32_bf16 v[52:55], v[196:199], v[164:167], v[52:55]
	v_mfma_f32_16x16x32_bf16 v[48:51], v[204:207], v[164:167], v[48:51]
	v_mfma_f32_16x16x32_bf16 v[36:39], v[196:199], v[172:175], v[36:39]
	v_mfma_f32_16x16x32_bf16 v[32:35], v[204:207], v[172:175], v[32:35]
	v_mfma_f32_16x16x32_bf16 v[20:23], v[196:199], v[180:183], v[20:23]
	v_mfma_f32_16x16x32_bf16 v[16:19], v[204:207], v[180:183], v[16:19]
	v_mfma_f32_16x16x32_bf16 v[4:7], v[196:199], v[188:191], v[4:7]
	v_mfma_f32_16x16x32_bf16 v[0:3], v[204:207], v[188:191], v[0:3]
	v_mfma_f32_16x16x32_bf16 v[52:55], v[200:203], v[168:171], v[52:55]
	v_mfma_f32_16x16x32_bf16 v[48:51], v[208:211], v[168:171], v[48:51]
	v_mfma_f32_16x16x32_bf16 v[36:39], v[200:203], v[176:179], v[36:39]
	v_mfma_f32_16x16x32_bf16 v[32:35], v[208:211], v[176:179], v[32:35]
	v_mfma_f32_16x16x32_bf16 v[20:23], v[200:203], v[184:187], v[20:23]
	v_mfma_f32_16x16x32_bf16 v[16:19], v[208:211], v[184:187], v[16:19]
	v_mfma_f32_16x16x32_bf16 v[4:7], v[200:203], v[192:195], v[4:7]
	v_mfma_f32_16x16x32_bf16 v[0:3], v[208:211], v[192:195], v[0:3]
	s_setprio 0
	s_add_i32 s70, 16, 0x18000
	v_add_u32_e32 v151, s70, v137
	s_barrier
	ds_read_b128 v[144:147], v151
	ds_read_b128 v[152:155], v151 offset:1024
	ds_read_b128 v[156:159], v151 offset:2048
	ds_read_b128 v[160:163], v151 offset:3072
	s_add_u32 s58, s64, 0x80000
	s_addc_u32 s59, s65, 0
	s_mov_b32 m0, s39
	v_lshl_add_u64 v[196:197], s[58:59], 0, v[128:129]
	ds_read_b128 v[164:167], v149 offset:32768
	ds_read_b128 v[168:171], v149 offset:33792
	ds_read_b128 v[172:175], v149 offset:34816
	ds_read_b128 v[176:179], v149 offset:35840
	ds_read_b128 v[180:183], v149 offset:36864
	ds_read_b128 v[184:187], v149 offset:37888
	ds_read_b128 v[188:191], v149 offset:38912
	ds_read_b128 v[192:195], v149 offset:39936
	global_load_lds_dwordx4 v[196:197], off
	v_lshl_add_u64 v[196:197], s[58:59], 0, v[130:131]
	s_mov_b32 m0, s44
	s_nop 0
	global_load_lds_dwordx4 v[196:197], off
	s_waitcnt lgkmcnt(8)
	s_barrier
	s_waitcnt lgkmcnt(0)
	s_setprio 1
	s_waitcnt lgkmcnt(0)
	v_mfma_f32_16x16x32_bf16 v[124:127], v[144:147], v[164:167], v[124:127]
	v_mfma_f32_16x16x32_bf16 v[120:123], v[156:159], v[164:167], v[120:123]
	v_mfma_f32_16x16x32_bf16 v[108:111], v[144:147], v[172:175], v[108:111]
	v_mfma_f32_16x16x32_bf16 v[104:107], v[156:159], v[172:175], v[104:107]
	v_mfma_f32_16x16x32_bf16 v[92:95], v[144:147], v[180:183], v[92:95]
	v_mfma_f32_16x16x32_bf16 v[88:91], v[156:159], v[180:183], v[88:91]
	v_mfma_f32_16x16x32_bf16 v[76:79], v[144:147], v[188:191], v[76:79]
	v_mfma_f32_16x16x32_bf16 v[72:75], v[156:159], v[188:191], v[72:75]
	v_mfma_f32_16x16x32_bf16 v[124:127], v[152:155], v[168:171], v[124:127]
	v_mfma_f32_16x16x32_bf16 v[120:123], v[160:163], v[168:171], v[120:123]
	v_mfma_f32_16x16x32_bf16 v[108:111], v[152:155], v[176:179], v[108:111]
	v_mfma_f32_16x16x32_bf16 v[104:107], v[160:163], v[176:179], v[104:107]
	v_mfma_f32_16x16x32_bf16 v[92:95], v[152:155], v[184:187], v[92:95]
	v_mfma_f32_16x16x32_bf16 v[88:91], v[160:163], v[184:187], v[88:91]
	v_mfma_f32_16x16x32_bf16 v[76:79], v[152:155], v[192:195], v[76:79]
	v_mfma_f32_16x16x32_bf16 v[72:75], v[160:163], v[192:195], v[72:75]
	s_setprio 0
	s_barrier
	s_add_i32 s64, 16, 0x1c000
	s_add_i32 s58, s70, s7
	v_add_u32_e32 v151, s64, v137
	v_lshl_add_u64 v[212:213], v[212:213], 0, s[12:13]
	s_mov_b32 m0, s58
	ds_read_b128 v[196:199], v151
	ds_read_b128 v[200:203], v151 offset:1024
	ds_read_b128 v[204:207], v151 offset:2048
	ds_read_b128 v[208:211], v151 offset:3072
	global_load_lds_dwordx4 v[212:213], off
	v_lshl_add_u64 v[212:213], v[214:215], 0, s[12:13]
	s_add_i32 m0, s58, 0x2000
	s_nop 0
	global_load_lds_dwordx4 v[212:213], off
	s_barrier
	s_waitcnt lgkmcnt(0)
	s_setprio 1
	s_waitcnt lgkmcnt(0)
	v_mfma_f32_16x16x32_bf16 v[116:119], v[196:199], v[164:167], v[116:119]
	v_mfma_f32_16x16x32_bf16 v[112:115], v[204:207], v[164:167], v[112:115]
	v_mfma_f32_16x16x32_bf16 v[100:103], v[196:199], v[172:175], v[100:103]
	v_mfma_f32_16x16x32_bf16 v[96:99], v[204:207], v[172:175], v[96:99]
	v_mfma_f32_16x16x32_bf16 v[84:87], v[196:199], v[180:183], v[84:87]
	v_mfma_f32_16x16x32_bf16 v[80:83], v[204:207], v[180:183], v[80:83]
	v_mfma_f32_16x16x32_bf16 v[68:71], v[196:199], v[188:191], v[68:71]
	v_mfma_f32_16x16x32_bf16 v[64:67], v[204:207], v[188:191], v[64:67]
	v_mfma_f32_16x16x32_bf16 v[116:119], v[200:203], v[168:171], v[116:119]
	v_mfma_f32_16x16x32_bf16 v[112:115], v[208:211], v[168:171], v[112:115]
	v_mfma_f32_16x16x32_bf16 v[100:103], v[200:203], v[176:179], v[100:103]
	v_mfma_f32_16x16x32_bf16 v[96:99], v[208:211], v[176:179], v[96:99]
	v_mfma_f32_16x16x32_bf16 v[84:87], v[200:203], v[184:187], v[84:87]
	v_mfma_f32_16x16x32_bf16 v[80:83], v[208:211], v[184:187], v[80:83]
	v_mfma_f32_16x16x32_bf16 v[68:71], v[200:203], v[192:195], v[68:71]
	v_mfma_f32_16x16x32_bf16 v[64:67], v[208:211], v[192:195], v[64:67]
	s_setprio 0
	s_mov_b32 m0, s45
	v_lshl_add_u64 v[212:213], v[216:217], 0, s[12:13]
	s_barrier
	ds_read_b128 v[164:167], v149 offset:49152
	ds_read_b128 v[168:171], v149 offset:50176
	ds_read_b128 v[172:175], v149 offset:51200
	ds_read_b128 v[176:179], v149 offset:52224
	ds_read_b128 v[180:183], v149 offset:53248
	ds_read_b128 v[184:187], v149 offset:54272
	ds_read_b128 v[188:191], v149 offset:55296
	ds_read_b128 v[192:195], v149 offset:56320
	global_load_lds_dwordx4 v[212:213], off
	v_lshl_add_u64 v[212:213], v[218:219], 0, s[12:13]
	s_mov_b32 m0, s46
	s_nop 0
	global_load_lds_dwordx4 v[212:213], off
	s_barrier
	s_waitcnt lgkmcnt(0)
	s_setprio 1
	s_waitcnt lgkmcnt(0)
	v_mfma_f32_16x16x32_bf16 v[60:63], v[144:147], v[164:167], v[60:63]
	v_mfma_f32_16x16x32_bf16 v[56:59], v[156:159], v[164:167], v[56:59]
	v_mfma_f32_16x16x32_bf16 v[44:47], v[144:147], v[172:175], v[44:47]
	v_mfma_f32_16x16x32_bf16 v[40:43], v[156:159], v[172:175], v[40:43]
	v_mfma_f32_16x16x32_bf16 v[28:31], v[144:147], v[180:183], v[28:31]
	v_mfma_f32_16x16x32_bf16 v[24:27], v[156:159], v[180:183], v[24:27]
	v_mfma_f32_16x16x32_bf16 v[12:15], v[144:147], v[188:191], v[12:15]
	v_mfma_f32_16x16x32_bf16 v[8:11], v[156:159], v[188:191], v[8:11]
	v_mfma_f32_16x16x32_bf16 v[60:63], v[152:155], v[168:171], v[60:63]
	v_mfma_f32_16x16x32_bf16 v[56:59], v[160:163], v[168:171], v[56:59]
	v_mfma_f32_16x16x32_bf16 v[44:47], v[152:155], v[176:179], v[44:47]
	v_mfma_f32_16x16x32_bf16 v[40:43], v[160:163], v[176:179], v[40:43]
	v_mfma_f32_16x16x32_bf16 v[28:31], v[152:155], v[184:187], v[28:31]
	v_mfma_f32_16x16x32_bf16 v[24:27], v[160:163], v[184:187], v[24:27]
	v_mfma_f32_16x16x32_bf16 v[12:15], v[152:155], v[192:195], v[12:15]
	v_mfma_f32_16x16x32_bf16 v[8:11], v[160:163], v[192:195], v[8:11]
	s_setprio 0
	s_barrier
	s_add_u32 s58, s62, 0x80080
	s_addc_u32 s59, s63, 0
	s_add_i32 s62, s64, s7
	v_lshl_add_u64 v[144:145], s[58:59], 0, v[128:129]
	s_mov_b32 m0, s62
	s_nop 0
	global_load_lds_dwordx4 v[144:145], off
	v_lshl_add_u64 v[144:145], s[58:59], 0, v[130:131]
	s_add_i32 m0, s62, 0x2000
	s_nop 0
	global_load_lds_dwordx4 v[144:145], off
	s_waitcnt vmcnt(6)
	s_barrier
	s_setprio 1
	v_mfma_f32_16x16x32_bf16 v[52:55], v[196:199], v[164:167], v[52:55]
	v_mfma_f32_16x16x32_bf16 v[48:51], v[204:207], v[164:167], v[48:51]
	v_mfma_f32_16x16x32_bf16 v[36:39], v[196:199], v[172:175], v[36:39]
	v_mfma_f32_16x16x32_bf16 v[32:35], v[204:207], v[172:175], v[32:35]
	v_mfma_f32_16x16x32_bf16 v[20:23], v[196:199], v[180:183], v[20:23]
	v_mfma_f32_16x16x32_bf16 v[16:19], v[204:207], v[180:183], v[16:19]
	v_mfma_f32_16x16x32_bf16 v[4:7], v[196:199], v[188:191], v[4:7]
	v_mfma_f32_16x16x32_bf16 v[0:3], v[204:207], v[188:191], v[0:3]
	v_mfma_f32_16x16x32_bf16 v[52:55], v[200:203], v[168:171], v[52:55]
	v_mfma_f32_16x16x32_bf16 v[48:51], v[208:211], v[168:171], v[48:51]
	v_mfma_f32_16x16x32_bf16 v[36:39], v[200:203], v[176:179], v[36:39]
	v_mfma_f32_16x16x32_bf16 v[32:35], v[208:211], v[176:179], v[32:35]
	v_mfma_f32_16x16x32_bf16 v[20:23], v[200:203], v[184:187], v[20:23]
	v_mfma_f32_16x16x32_bf16 v[16:19], v[208:211], v[184:187], v[16:19]
	v_mfma_f32_16x16x32_bf16 v[4:7], v[200:203], v[192:195], v[4:7]
	v_mfma_f32_16x16x32_bf16 v[0:3], v[208:211], v[192:195], v[0:3]
	s_setprio 0
	s_add_i32 s69, s69, 2
	s_add_u32 s67, s67, 0x100
	s_addc_u32 s68, s68, 0
	s_cmp_gt_u32 s69, 29
	s_mov_b64 s[58:59], s[60:61]
	s_barrier
	s_cbranch_scc0 .LBB0_1623
	v_lshl_add_u32 v146, s22, 8, v133
	s_lshl_b32 s15, s56, 8
	s_ashr_i32 s17, s15, 31
	v_ashrrev_i32_e32 v147, 31, v146
	v_mov_b32_e32 v145, s17
	v_or_b32_e32 v144, s15, v132
	v_mov_b32_e32 v212, v146
	v_mov_b32_e32 v213, v147
	v_lshlrev_b64 v[214:215], 11, v[212:213]
	v_lshl_add_u64 v[214:215], v[214:215], 0, v[144:145]
	v_lshl_add_u64 v[152:153], v[214:215], 2, s[28:29]
	global_load_dwordx4 v[164:167], v[152:153], off
	global_load_dwordx4 v[168:171], v[152:153], off offset:64
	global_load_dwordx4 v[172:175], v[152:153], off offset:512
	global_load_dwordx4 v[176:179], v[152:153], off offset:576
	v_add_u32_e32 v212, 0x10, v146
	v_mov_b32_e32 v213, v147
	v_lshlrev_b64 v[214:215], 11, v[212:213]
	v_lshl_add_u64 v[214:215], v[214:215], 0, v[144:145]
	v_lshl_add_u64 v[152:153], v[214:215], 2, s[28:29]
	global_load_dwordx4 v[180:183], v[152:153], off
	global_load_dwordx4 v[184:187], v[152:153], off offset:64
	global_load_dwordx4 v[188:191], v[152:153], off offset:512
	global_load_dwordx4 v[192:195], v[152:153], off offset:576
	v_add_u32_e32 v212, 0x20, v146
	v_mov_b32_e32 v213, v147
	v_lshlrev_b64 v[214:215], 11, v[212:213]
	v_lshl_add_u64 v[214:215], v[214:215], 0, v[144:145]
	v_lshl_add_u64 v[152:153], v[214:215], 2, s[28:29]
	global_load_dwordx4 v[196:199], v[152:153], off
	global_load_dwordx4 v[200:203], v[152:153], off offset:64
	global_load_dwordx4 v[204:207], v[152:153], off offset:512
	global_load_dwordx4 v[208:211], v[152:153], off offset:576
	s_waitcnt vmcnt(8)
	v_mov_b32_e32 v212, v146
	v_mov_b32_e32 v213, v147
	v_lshlrev_b64 v[214:215], 11, v[212:213]
	v_lshl_add_u64 v[214:215], v[214:215], 0, v[144:145]
	v_lshl_add_u64 v[154:155], v[214:215], 2, s[28:29]
	v_lshl_add_u64 v[156:157], v[214:215], 1, s[40:41]
	v_pk_add_f32 v[126:127], v[126:127], v[166:167]
	v_pk_add_f32 v[124:125], v[124:125], v[164:165]
	v_cvt_pk_bf16_f32 v159, v126, v127
	v_cvt_pk_bf16_f32 v158, v124, v125
	global_store_dwordx4 v[154:155], v[124:127], off
	global_store_dwordx2 v[156:157], v[158:159], off
	s_nop 0
	v_mul_f32_e32 v125, v125, v125
	v_mul_f32_e32 v127, v127, v127
	v_fmac_f32_e32 v125, v124, v124
	v_fmac_f32_e32 v127, v126, v126
	v_add_f32_e32 v160, v125, v127
	v_pk_add_f32 v[122:123], v[122:123], v[170:171]
	v_pk_add_f32 v[120:121], v[120:121], v[168:169]
	v_cvt_pk_bf16_f32 v159, v122, v123
	v_cvt_pk_bf16_f32 v158, v120, v121
	global_store_dwordx4 v[154:155], v[120:123], off offset:64
	global_store_dwordx2 v[156:157], v[158:159], off offset:32
	s_nop 0
	v_mul_f32_e32 v121, v121, v121
	v_mul_f32_e32 v123, v123, v123
	v_fmac_f32_e32 v121, v120, v120
	v_fmac_f32_e32 v123, v122, v122
	v_add_f32_e32 v120, v121, v123
	v_add_f32_e32 v160, v160, v120
	v_pk_add_f32 v[118:119], v[118:119], v[174:175]
	v_pk_add_f32 v[116:117], v[116:117], v[172:173]
	v_cvt_pk_bf16_f32 v159, v118, v119
	v_cvt_pk_bf16_f32 v158, v116, v117
	global_store_dwordx4 v[154:155], v[116:119], off offset:512
	global_store_dwordx2 v[156:157], v[158:159], off offset:256
	s_nop 0
	v_mul_f32_e32 v117, v117, v117
	v_mul_f32_e32 v119, v119, v119
	v_fmac_f32_e32 v117, v116, v116
	v_fmac_f32_e32 v119, v118, v118
	v_add_f32_e32 v116, v117, v119
	v_add_f32_e32 v160, v160, v116
	v_pk_add_f32 v[114:115], v[114:115], v[178:179]
	v_pk_add_f32 v[112:113], v[112:113], v[176:177]
	v_cvt_pk_bf16_f32 v159, v114, v115
	v_cvt_pk_bf16_f32 v158, v112, v113
	global_store_dwordx4 v[154:155], v[112:115], off offset:576
	global_store_dwordx2 v[156:157], v[158:159], off offset:288
	s_nop 0
	v_mul_f32_e32 v113, v113, v113
	v_mul_f32_e32 v115, v115, v115
	v_fmac_f32_e32 v113, v112, v112
	v_fmac_f32_e32 v115, v114, v114
	v_add_f32_e32 v112, v113, v115
	v_add_f32_e32 v160, v160, v112
	v_mov_b32_e32 v161, v160
	s_nop 1
	v_permlane16_swap_b32_e32 v160, v161
	v_add_f32_e32 v160, v160, v161
	v_mov_b32_e32 v161, v160
	s_nop 1
	v_permlane32_swap_b32_e32 v160, v161
	s_and_saveexec_b64 s[22:23], s[8:9]
	v_lshl_add_u64 v[162:163], v[212:213], 2, s[52:53]
	v_add_f32_e32 v160, v160, v161
	global_atomic_add_f32 v[162:163], v160, off
	s_or_b64 exec, exec, s[22:23]
	v_add_u32_e32 v212, 0x30, v146
	v_mov_b32_e32 v213, v147
	v_lshlrev_b64 v[214:215], 11, v[212:213]
	v_lshl_add_u64 v[214:215], v[214:215], 0, v[144:145]
	v_lshl_add_u64 v[152:153], v[214:215], 2, s[28:29]
	global_load_dwordx4 v[164:167], v[152:153], off
	global_load_dwordx4 v[168:171], v[152:153], off offset:64
	global_load_dwordx4 v[172:175], v[152:153], off offset:512
	global_load_dwordx4 v[176:179], v[152:153], off offset:576
	s_waitcnt vmcnt(17)
	v_add_u32_e32 v212, 0x10, v146
	v_mov_b32_e32 v213, v147
	v_lshlrev_b64 v[214:215], 11, v[212:213]
	v_lshl_add_u64 v[214:215], v[214:215], 0, v[144:145]
	v_lshl_add_u64 v[154:155], v[214:215], 2, s[28:29]
	v_lshl_add_u64 v[156:157], v[214:215], 1, s[40:41]
	v_pk_add_f32 v[110:111], v[110:111], v[182:183]
	v_pk_add_f32 v[108:109], v[108:109], v[180:181]
	v_cvt_pk_bf16_f32 v159, v110, v111
	v_cvt_pk_bf16_f32 v158, v108, v109
	global_store_dwordx4 v[154:155], v[108:111], off
	global_store_dwordx2 v[156:157], v[158:159], off
	s_nop 0
	v_mul_f32_e32 v109, v109, v109
	v_mul_f32_e32 v111, v111, v111
	v_fmac_f32_e32 v109, v108, v108
	v_fmac_f32_e32 v111, v110, v110
	v_add_f32_e32 v160, v109, v111
	v_pk_add_f32 v[106:107], v[106:107], v[186:187]
	v_pk_add_f32 v[104:105], v[104:105], v[184:185]
	v_cvt_pk_bf16_f32 v159, v106, v107
	v_cvt_pk_bf16_f32 v158, v104, v105
	global_store_dwordx4 v[154:155], v[104:107], off offset:64
	global_store_dwordx2 v[156:157], v[158:159], off offset:32
	s_nop 0
	v_mul_f32_e32 v105, v105, v105
	v_mul_f32_e32 v107, v107, v107
	v_fmac_f32_e32 v105, v104, v104
	v_fmac_f32_e32 v107, v106, v106
	v_add_f32_e32 v104, v105, v107
	v_add_f32_e32 v160, v160, v104
	v_pk_add_f32 v[102:103], v[102:103], v[190:191]
	v_pk_add_f32 v[100:101], v[100:101], v[188:189]
	v_cvt_pk_bf16_f32 v159, v102, v103
	v_cvt_pk_bf16_f32 v158, v100, v101
	global_store_dwordx4 v[154:155], v[100:103], off offset:512
	global_store_dwordx2 v[156:157], v[158:159], off offset:256
	s_nop 0
	v_mul_f32_e32 v101, v101, v101
	v_mul_f32_e32 v103, v103, v103
	v_fmac_f32_e32 v101, v100, v100
	v_fmac_f32_e32 v103, v102, v102
	v_add_f32_e32 v100, v101, v103
	v_add_f32_e32 v160, v160, v100
	v_pk_add_f32 v[98:99], v[98:99], v[194:195]
	v_pk_add_f32 v[96:97], v[96:97], v[192:193]
	v_cvt_pk_bf16_f32 v159, v98, v99
	v_cvt_pk_bf16_f32 v158, v96, v97
	global_store_dwordx4 v[154:155], v[96:99], off offset:576
	global_store_dwordx2 v[156:157], v[158:159], off offset:288
	s_nop 0
	v_mul_f32_e32 v97, v97, v97
	v_mul_f32_e32 v99, v99, v99
	v_fmac_f32_e32 v97, v96, v96
	v_fmac_f32_e32 v99, v98, v98
	v_add_f32_e32 v96, v97, v99
	v_add_f32_e32 v160, v160, v96
	v_mov_b32_e32 v161, v160
	s_nop 1
	v_permlane16_swap_b32_e32 v160, v161
	v_add_f32_e32 v160, v160, v161
	v_mov_b32_e32 v161, v160
	s_nop 1
	v_permlane32_swap_b32_e32 v160, v161
	s_and_saveexec_b64 s[22:23], s[8:9]
	v_lshl_add_u64 v[162:163], v[212:213], 2, s[52:53]
	v_add_f32_e32 v160, v160, v161
	global_atomic_add_f32 v[162:163], v160, off
	s_or_b64 exec, exec, s[22:23]
	v_add_u32_e32 v212, 0x80, v146
	v_mov_b32_e32 v213, v147
	v_lshlrev_b64 v[214:215], 11, v[212:213]
	v_lshl_add_u64 v[214:215], v[214:215], 0, v[144:145]
	v_lshl_add_u64 v[152:153], v[214:215], 2, s[28:29]
	global_load_dwordx4 v[180:183], v[152:153], off
	global_load_dwordx4 v[184:187], v[152:153], off offset:64
	global_load_dwordx4 v[188:191], v[152:153], off offset:512
	global_load_dwordx4 v[192:195], v[152:153], off offset:576
	s_waitcnt vmcnt(26)
	v_add_u32_e32 v212, 0x20, v146
	v_mov_b32_e32 v213, v147
	v_lshlrev_b64 v[214:215], 11, v[212:213]
	v_lshl_add_u64 v[214:215], v[214:215], 0, v[144:145]
	v_lshl_add_u64 v[154:155], v[214:215], 2, s[28:29]
	v_lshl_add_u64 v[156:157], v[214:215], 1, s[40:41]
	v_pk_add_f32 v[94:95], v[94:95], v[198:199]
	v_pk_add_f32 v[92:93], v[92:93], v[196:197]
	v_cvt_pk_bf16_f32 v159, v94, v95
	v_cvt_pk_bf16_f32 v158, v92, v93
	global_store_dwordx4 v[154:155], v[92:95], off
	global_store_dwordx2 v[156:157], v[158:159], off
	s_nop 0
	v_mul_f32_e32 v93, v93, v93
	v_mul_f32_e32 v95, v95, v95
	v_fmac_f32_e32 v93, v92, v92
	v_fmac_f32_e32 v95, v94, v94
	v_add_f32_e32 v160, v93, v95
	v_pk_add_f32 v[90:91], v[90:91], v[202:203]
	v_pk_add_f32 v[88:89], v[88:89], v[200:201]
	v_cvt_pk_bf16_f32 v159, v90, v91
	v_cvt_pk_bf16_f32 v158, v88, v89
	global_store_dwordx4 v[154:155], v[88:91], off offset:64
	global_store_dwordx2 v[156:157], v[158:159], off offset:32
	s_nop 0
	v_mul_f32_e32 v89, v89, v89
	v_mul_f32_e32 v91, v91, v91
	v_fmac_f32_e32 v89, v88, v88
	v_fmac_f32_e32 v91, v90, v90
	v_add_f32_e32 v88, v89, v91
	v_add_f32_e32 v160, v160, v88
	v_pk_add_f32 v[86:87], v[86:87], v[206:207]
	v_pk_add_f32 v[84:85], v[84:85], v[204:205]
	v_cvt_pk_bf16_f32 v159, v86, v87
	v_cvt_pk_bf16_f32 v158, v84, v85
	global_store_dwordx4 v[154:155], v[84:87], off offset:512
	global_store_dwordx2 v[156:157], v[158:159], off offset:256
	s_nop 0
	v_mul_f32_e32 v85, v85, v85
	v_mul_f32_e32 v87, v87, v87
	v_fmac_f32_e32 v85, v84, v84
	v_fmac_f32_e32 v87, v86, v86
	v_add_f32_e32 v84, v85, v87
	v_add_f32_e32 v160, v160, v84
	v_pk_add_f32 v[82:83], v[82:83], v[210:211]
	v_pk_add_f32 v[80:81], v[80:81], v[208:209]
	v_cvt_pk_bf16_f32 v159, v82, v83
	v_cvt_pk_bf16_f32 v158, v80, v81
	global_store_dwordx4 v[154:155], v[80:83], off offset:576
	global_store_dwordx2 v[156:157], v[158:159], off offset:288
	s_nop 0
	v_mul_f32_e32 v81, v81, v81
	v_mul_f32_e32 v83, v83, v83
	v_fmac_f32_e32 v81, v80, v80
	v_fmac_f32_e32 v83, v82, v82
	v_add_f32_e32 v80, v81, v83
	v_add_f32_e32 v160, v160, v80
	v_mov_b32_e32 v161, v160
	s_nop 1
	v_permlane16_swap_b32_e32 v160, v161
	v_add_f32_e32 v160, v160, v161
	v_mov_b32_e32 v161, v160
	s_nop 1
	v_permlane32_swap_b32_e32 v160, v161
	s_and_saveexec_b64 s[22:23], s[8:9]
	v_lshl_add_u64 v[162:163], v[212:213], 2, s[52:53]
	v_add_f32_e32 v160, v160, v161
	global_atomic_add_f32 v[162:163], v160, off
	s_or_b64 exec, exec, s[22:23]
	v_add_u32_e32 v212, 0x90, v146
	v_mov_b32_e32 v213, v147
	v_lshlrev_b64 v[214:215], 11, v[212:213]
	v_lshl_add_u64 v[214:215], v[214:215], 0, v[144:145]
	v_lshl_add_u64 v[152:153], v[214:215], 2, s[28:29]
	global_load_dwordx4 v[196:199], v[152:153], off
	global_load_dwordx4 v[200:203], v[152:153], off offset:64
	global_load_dwordx4 v[204:207], v[152:153], off offset:512
	global_load_dwordx4 v[208:211], v[152:153], off offset:576
	s_waitcnt vmcnt(26)
	v_add_u32_e32 v212, 0x30, v146
	v_mov_b32_e32 v213, v147
	v_lshlrev_b64 v[214:215], 11, v[212:213]
	v_lshl_add_u64 v[214:215], v[214:215], 0, v[144:145]
	v_lshl_add_u64 v[154:155], v[214:215], 2, s[28:29]
	v_lshl_add_u64 v[156:157], v[214:215], 1, s[40:41]
	v_pk_add_f32 v[78:79], v[78:79], v[166:167]
	v_pk_add_f32 v[76:77], v[76:77], v[164:165]
	v_cvt_pk_bf16_f32 v159, v78, v79
	v_cvt_pk_bf16_f32 v158, v76, v77
	global_store_dwordx4 v[154:155], v[76:79], off
	global_store_dwordx2 v[156:157], v[158:159], off
	s_nop 0
	v_mul_f32_e32 v77, v77, v77
	v_mul_f32_e32 v79, v79, v79
	v_fmac_f32_e32 v77, v76, v76
	v_fmac_f32_e32 v79, v78, v78
	v_add_f32_e32 v160, v77, v79
	v_pk_add_f32 v[74:75], v[74:75], v[170:171]
	v_pk_add_f32 v[72:73], v[72:73], v[168:169]
	v_cvt_pk_bf16_f32 v159, v74, v75
	v_cvt_pk_bf16_f32 v158, v72, v73
	global_store_dwordx4 v[154:155], v[72:75], off offset:64
	global_store_dwordx2 v[156:157], v[158:159], off offset:32
	s_nop 0
	v_mul_f32_e32 v73, v73, v73
	v_mul_f32_e32 v75, v75, v75
	v_fmac_f32_e32 v73, v72, v72
	v_fmac_f32_e32 v75, v74, v74
	v_add_f32_e32 v72, v73, v75
	v_add_f32_e32 v160, v160, v72
	v_pk_add_f32 v[70:71], v[70:71], v[174:175]
	v_pk_add_f32 v[68:69], v[68:69], v[172:173]
	v_cvt_pk_bf16_f32 v159, v70, v71
	v_cvt_pk_bf16_f32 v158, v68, v69
	global_store_dwordx4 v[154:155], v[68:71], off offset:512
	global_store_dwordx2 v[156:157], v[158:159], off offset:256
	s_nop 0
	v_mul_f32_e32 v69, v69, v69
	v_mul_f32_e32 v71, v71, v71
	v_fmac_f32_e32 v69, v68, v68
	v_fmac_f32_e32 v71, v70, v70
	v_add_f32_e32 v68, v69, v71
	v_add_f32_e32 v160, v160, v68
	v_pk_add_f32 v[66:67], v[66:67], v[178:179]
	v_pk_add_f32 v[64:65], v[64:65], v[176:177]
	v_cvt_pk_bf16_f32 v159, v66, v67
	v_cvt_pk_bf16_f32 v158, v64, v65
	global_store_dwordx4 v[154:155], v[64:67], off offset:576
	global_store_dwordx2 v[156:157], v[158:159], off offset:288
	s_nop 0
	v_mul_f32_e32 v65, v65, v65
	v_mul_f32_e32 v67, v67, v67
	v_fmac_f32_e32 v65, v64, v64
	v_fmac_f32_e32 v67, v66, v66
	v_add_f32_e32 v64, v65, v67
	v_add_f32_e32 v160, v160, v64
	v_mov_b32_e32 v161, v160
	s_nop 1
	v_permlane16_swap_b32_e32 v160, v161
	v_add_f32_e32 v160, v160, v161
	v_mov_b32_e32 v161, v160
	s_nop 1
	v_permlane32_swap_b32_e32 v160, v161
	s_and_saveexec_b64 s[22:23], s[8:9]
	v_lshl_add_u64 v[162:163], v[212:213], 2, s[52:53]
	v_add_f32_e32 v160, v160, v161
	global_atomic_add_f32 v[162:163], v160, off
	s_or_b64 exec, exec, s[22:23]
	v_add_u32_e32 v212, 0xa0, v146
	v_mov_b32_e32 v213, v147
	v_lshlrev_b64 v[214:215], 11, v[212:213]
	v_lshl_add_u64 v[214:215], v[214:215], 0, v[144:145]
	v_lshl_add_u64 v[152:153], v[214:215], 2, s[28:29]
	global_load_dwordx4 v[164:167], v[152:153], off
	global_load_dwordx4 v[168:171], v[152:153], off offset:64
	global_load_dwordx4 v[172:175], v[152:153], off offset:512
	global_load_dwordx4 v[176:179], v[152:153], off offset:576
	s_waitcnt vmcnt(26)
	v_add_u32_e32 v212, 0x80, v146
	v_mov_b32_e32 v213, v147
	v_lshlrev_b64 v[214:215], 11, v[212:213]
	v_lshl_add_u64 v[214:215], v[214:215], 0, v[144:145]
	v_lshl_add_u64 v[154:155], v[214:215], 2, s[28:29]
	v_lshl_add_u64 v[156:157], v[214:215], 1, s[40:41]
	v_pk_add_f32 v[62:63], v[62:63], v[182:183]
	v_pk_add_f32 v[60:61], v[60:61], v[180:181]
	v_cvt_pk_bf16_f32 v159, v62, v63
	v_cvt_pk_bf16_f32 v158, v60, v61
	global_store_dwordx4 v[154:155], v[60:63], off
	global_store_dwordx2 v[156:157], v[158:159], off
	s_nop 0
	v_mul_f32_e32 v61, v61, v61
	v_mul_f32_e32 v63, v63, v63
	v_fmac_f32_e32 v61, v60, v60
	v_fmac_f32_e32 v63, v62, v62
	v_add_f32_e32 v160, v61, v63
	v_pk_add_f32 v[58:59], v[58:59], v[186:187]
	v_pk_add_f32 v[56:57], v[56:57], v[184:185]
	v_cvt_pk_bf16_f32 v159, v58, v59
	v_cvt_pk_bf16_f32 v158, v56, v57
	global_store_dwordx4 v[154:155], v[56:59], off offset:64
	global_store_dwordx2 v[156:157], v[158:159], off offset:32
	s_nop 0
	v_mul_f32_e32 v57, v57, v57
	v_mul_f32_e32 v59, v59, v59
	v_fmac_f32_e32 v57, v56, v56
	v_fmac_f32_e32 v59, v58, v58
	v_add_f32_e32 v56, v57, v59
	v_add_f32_e32 v160, v160, v56
	v_pk_add_f32 v[54:55], v[54:55], v[190:191]
	v_pk_add_f32 v[52:53], v[52:53], v[188:189]
	v_cvt_pk_bf16_f32 v159, v54, v55
	v_cvt_pk_bf16_f32 v158, v52, v53
	global_store_dwordx4 v[154:155], v[52:55], off offset:512
	global_store_dwordx2 v[156:157], v[158:159], off offset:256
	s_nop 0
	v_mul_f32_e32 v53, v53, v53
	v_mul_f32_e32 v55, v55, v55
	v_fmac_f32_e32 v53, v52, v52
	v_fmac_f32_e32 v55, v54, v54
	v_add_f32_e32 v52, v53, v55
	v_add_f32_e32 v160, v160, v52
	v_pk_add_f32 v[50:51], v[50:51], v[194:195]
	v_pk_add_f32 v[48:49], v[48:49], v[192:193]
	v_cvt_pk_bf16_f32 v159, v50, v51
	v_cvt_pk_bf16_f32 v158, v48, v49
	global_store_dwordx4 v[154:155], v[48:51], off offset:576
	global_store_dwordx2 v[156:157], v[158:159], off offset:288
	s_nop 0
	v_mul_f32_e32 v49, v49, v49
	v_mul_f32_e32 v51, v51, v51
	v_fmac_f32_e32 v49, v48, v48
	v_fmac_f32_e32 v51, v50, v50
	v_add_f32_e32 v48, v49, v51
	v_add_f32_e32 v160, v160, v48
	v_mov_b32_e32 v161, v160
	s_nop 1
	v_permlane16_swap_b32_e32 v160, v161
	v_add_f32_e32 v160, v160, v161
	v_mov_b32_e32 v161, v160
	s_nop 1
	v_permlane32_swap_b32_e32 v160, v161
	s_and_saveexec_b64 s[22:23], s[8:9]
	v_lshl_add_u64 v[162:163], v[212:213], 2, s[52:53]
	v_add_f32_e32 v160, v160, v161
	global_atomic_add_f32 v[162:163], v160, off
	s_or_b64 exec, exec, s[22:23]
	v_add_u32_e32 v212, 0xb0, v146
	v_mov_b32_e32 v213, v147
	v_lshlrev_b64 v[214:215], 11, v[212:213]
	v_lshl_add_u64 v[214:215], v[214:215], 0, v[144:145]
	v_lshl_add_u64 v[152:153], v[214:215], 2, s[28:29]
	global_load_dwordx4 v[180:183], v[152:153], off
	global_load_dwordx4 v[184:187], v[152:153], off offset:64
	global_load_dwordx4 v[188:191], v[152:153], off offset:512
	global_load_dwordx4 v[192:195], v[152:153], off offset:576
	s_waitcnt vmcnt(26)
	v_add_u32_e32 v212, 0x90, v146
	v_mov_b32_e32 v213, v147
	v_lshlrev_b64 v[214:215], 11, v[212:213]
	v_lshl_add_u64 v[214:215], v[214:215], 0, v[144:145]
	v_lshl_add_u64 v[154:155], v[214:215], 2, s[28:29]
	v_lshl_add_u64 v[156:157], v[214:215], 1, s[40:41]
	v_pk_add_f32 v[46:47], v[46:47], v[198:199]
	v_pk_add_f32 v[44:45], v[44:45], v[196:197]
	v_cvt_pk_bf16_f32 v159, v46, v47
	v_cvt_pk_bf16_f32 v158, v44, v45
	global_store_dwordx4 v[154:155], v[44:47], off
	global_store_dwordx2 v[156:157], v[158:159], off
	s_nop 0
	v_mul_f32_e32 v45, v45, v45
	v_mul_f32_e32 v47, v47, v47
	v_fmac_f32_e32 v45, v44, v44
	v_fmac_f32_e32 v47, v46, v46
	v_add_f32_e32 v160, v45, v47
	v_pk_add_f32 v[42:43], v[42:43], v[202:203]
	v_pk_add_f32 v[40:41], v[40:41], v[200:201]
	v_cvt_pk_bf16_f32 v159, v42, v43
	v_cvt_pk_bf16_f32 v158, v40, v41
	global_store_dwordx4 v[154:155], v[40:43], off offset:64
	global_store_dwordx2 v[156:157], v[158:159], off offset:32
	s_nop 0
	v_mul_f32_e32 v41, v41, v41
	v_mul_f32_e32 v43, v43, v43
	v_fmac_f32_e32 v41, v40, v40
	v_fmac_f32_e32 v43, v42, v42
	v_add_f32_e32 v40, v41, v43
	v_add_f32_e32 v160, v160, v40
	v_pk_add_f32 v[38:39], v[38:39], v[206:207]
	v_pk_add_f32 v[36:37], v[36:37], v[204:205]
	v_cvt_pk_bf16_f32 v159, v38, v39
	v_cvt_pk_bf16_f32 v158, v36, v37
	global_store_dwordx4 v[154:155], v[36:39], off offset:512
	global_store_dwordx2 v[156:157], v[158:159], off offset:256
	s_nop 0
	v_mul_f32_e32 v37, v37, v37
	v_mul_f32_e32 v39, v39, v39
	v_fmac_f32_e32 v37, v36, v36
	v_fmac_f32_e32 v39, v38, v38
	v_add_f32_e32 v36, v37, v39
	v_add_f32_e32 v160, v160, v36
	v_pk_add_f32 v[34:35], v[34:35], v[210:211]
	v_pk_add_f32 v[32:33], v[32:33], v[208:209]
	v_cvt_pk_bf16_f32 v159, v34, v35
	v_cvt_pk_bf16_f32 v158, v32, v33
	global_store_dwordx4 v[154:155], v[32:35], off offset:576
	global_store_dwordx2 v[156:157], v[158:159], off offset:288
	s_nop 0
	v_mul_f32_e32 v33, v33, v33
	v_mul_f32_e32 v35, v35, v35
	v_fmac_f32_e32 v33, v32, v32
	v_fmac_f32_e32 v35, v34, v34
	v_add_f32_e32 v32, v33, v35
	v_add_f32_e32 v160, v160, v32
	v_mov_b32_e32 v161, v160
	s_nop 1
	v_permlane16_swap_b32_e32 v160, v161
	v_add_f32_e32 v160, v160, v161
	v_mov_b32_e32 v161, v160
	s_nop 1
	v_permlane32_swap_b32_e32 v160, v161
	s_and_saveexec_b64 s[22:23], s[8:9]
	v_lshl_add_u64 v[162:163], v[212:213], 2, s[52:53]
	v_add_f32_e32 v160, v160, v161
	global_atomic_add_f32 v[162:163], v160, off
	s_or_b64 exec, exec, s[22:23]
	s_waitcnt vmcnt(22)
	v_add_u32_e32 v212, 0xa0, v146
	v_mov_b32_e32 v213, v147
	v_lshlrev_b64 v[214:215], 11, v[212:213]
	v_lshl_add_u64 v[214:215], v[214:215], 0, v[144:145]
	v_lshl_add_u64 v[154:155], v[214:215], 2, s[28:29]
	v_lshl_add_u64 v[156:157], v[214:215], 1, s[40:41]
	v_pk_add_f32 v[30:31], v[30:31], v[166:167]
	v_pk_add_f32 v[28:29], v[28:29], v[164:165]
	v_cvt_pk_bf16_f32 v159, v30, v31
	v_cvt_pk_bf16_f32 v158, v28, v29
	global_store_dwordx4 v[154:155], v[28:31], off
	global_store_dwordx2 v[156:157], v[158:159], off
	s_nop 0
	v_mul_f32_e32 v29, v29, v29
	v_mul_f32_e32 v31, v31, v31
	v_fmac_f32_e32 v29, v28, v28
	v_fmac_f32_e32 v31, v30, v30
	v_add_f32_e32 v160, v29, v31
	v_pk_add_f32 v[26:27], v[26:27], v[170:171]
	v_pk_add_f32 v[24:25], v[24:25], v[168:169]
	v_cvt_pk_bf16_f32 v159, v26, v27
	v_cvt_pk_bf16_f32 v158, v24, v25
	global_store_dwordx4 v[154:155], v[24:27], off offset:64
	global_store_dwordx2 v[156:157], v[158:159], off offset:32
	s_nop 0
	v_mul_f32_e32 v25, v25, v25
	v_mul_f32_e32 v27, v27, v27
	v_fmac_f32_e32 v25, v24, v24
	v_fmac_f32_e32 v27, v26, v26
	v_add_f32_e32 v24, v25, v27
	v_add_f32_e32 v160, v160, v24
	v_pk_add_f32 v[22:23], v[22:23], v[174:175]
	v_pk_add_f32 v[20:21], v[20:21], v[172:173]
	v_cvt_pk_bf16_f32 v159, v22, v23
	v_cvt_pk_bf16_f32 v158, v20, v21
	global_store_dwordx4 v[154:155], v[20:23], off offset:512
	global_store_dwordx2 v[156:157], v[158:159], off offset:256
	s_nop 0
	v_mul_f32_e32 v21, v21, v21
	v_mul_f32_e32 v23, v23, v23
	v_fmac_f32_e32 v21, v20, v20
	v_fmac_f32_e32 v23, v22, v22
	v_add_f32_e32 v20, v21, v23
	v_add_f32_e32 v160, v160, v20
	v_pk_add_f32 v[18:19], v[18:19], v[178:179]
	v_pk_add_f32 v[16:17], v[16:17], v[176:177]
	v_cvt_pk_bf16_f32 v159, v18, v19
	v_cvt_pk_bf16_f32 v158, v16, v17
	global_store_dwordx4 v[154:155], v[16:19], off offset:576
	global_store_dwordx2 v[156:157], v[158:159], off offset:288
	s_nop 0
	v_mul_f32_e32 v17, v17, v17
	v_mul_f32_e32 v19, v19, v19
	v_fmac_f32_e32 v17, v16, v16
	v_fmac_f32_e32 v19, v18, v18
	v_add_f32_e32 v16, v17, v19
	v_add_f32_e32 v160, v160, v16
	v_mov_b32_e32 v161, v160
	s_nop 1
	v_permlane16_swap_b32_e32 v160, v161
	v_add_f32_e32 v160, v160, v161
	v_mov_b32_e32 v161, v160
	s_nop 1
	v_permlane32_swap_b32_e32 v160, v161
	s_and_saveexec_b64 s[22:23], s[8:9]
	v_lshl_add_u64 v[162:163], v[212:213], 2, s[52:53]
	v_add_f32_e32 v160, v160, v161
	global_atomic_add_f32 v[162:163], v160, off
	s_or_b64 exec, exec, s[22:23]
	s_waitcnt vmcnt(18)
	v_add_u32_e32 v212, 0xb0, v146
	v_mov_b32_e32 v213, v147
	v_lshlrev_b64 v[214:215], 11, v[212:213]
	v_lshl_add_u64 v[214:215], v[214:215], 0, v[144:145]
	v_lshl_add_u64 v[154:155], v[214:215], 2, s[28:29]
	v_lshl_add_u64 v[156:157], v[214:215], 1, s[40:41]
	v_pk_add_f32 v[14:15], v[14:15], v[182:183]
	v_pk_add_f32 v[12:13], v[12:13], v[180:181]
	v_cvt_pk_bf16_f32 v159, v14, v15
	v_cvt_pk_bf16_f32 v158, v12, v13
	global_store_dwordx4 v[154:155], v[12:15], off
	global_store_dwordx2 v[156:157], v[158:159], off
	s_nop 0
	v_mul_f32_e32 v13, v13, v13
	v_mul_f32_e32 v15, v15, v15
	v_fmac_f32_e32 v13, v12, v12
	v_fmac_f32_e32 v15, v14, v14
	v_add_f32_e32 v160, v13, v15
	v_pk_add_f32 v[10:11], v[10:11], v[186:187]
	v_pk_add_f32 v[8:9], v[8:9], v[184:185]
	v_cvt_pk_bf16_f32 v159, v10, v11
	v_cvt_pk_bf16_f32 v158, v8, v9
	global_store_dwordx4 v[154:155], v[8:11], off offset:64
	global_store_dwordx2 v[156:157], v[158:159], off offset:32
	s_nop 0
	v_mul_f32_e32 v9, v9, v9
	v_mul_f32_e32 v11, v11, v11
	v_fmac_f32_e32 v9, v8, v8
	v_fmac_f32_e32 v11, v10, v10
	v_add_f32_e32 v8, v9, v11
	v_add_f32_e32 v160, v160, v8
	v_pk_add_f32 v[6:7], v[6:7], v[190:191]
	v_pk_add_f32 v[4:5], v[4:5], v[188:189]
	v_cvt_pk_bf16_f32 v159, v6, v7
	v_cvt_pk_bf16_f32 v158, v4, v5
	global_store_dwordx4 v[154:155], v[4:7], off offset:512
	global_store_dwordx2 v[156:157], v[158:159], off offset:256
	s_nop 0
	v_mul_f32_e32 v5, v5, v5
	v_mul_f32_e32 v7, v7, v7
	v_fmac_f32_e32 v5, v4, v4
	v_fmac_f32_e32 v7, v6, v6
	v_add_f32_e32 v4, v5, v7
	v_add_f32_e32 v160, v160, v4
	v_pk_add_f32 v[2:3], v[2:3], v[194:195]
	v_pk_add_f32 v[0:1], v[0:1], v[192:193]
	v_cvt_pk_bf16_f32 v159, v2, v3
	v_cvt_pk_bf16_f32 v158, v0, v1
	global_store_dwordx4 v[154:155], v[0:3], off offset:576
	global_store_dwordx2 v[156:157], v[158:159], off offset:288
	s_nop 0
	v_mul_f32_e32 v1, v1, v1
	v_mul_f32_e32 v3, v3, v3
	v_fmac_f32_e32 v1, v0, v0
	v_fmac_f32_e32 v3, v2, v2
	v_add_f32_e32 v0, v1, v3
	v_add_f32_e32 v160, v160, v0
	v_mov_b32_e32 v161, v160
	s_nop 1
	v_permlane16_swap_b32_e32 v160, v161
	v_add_f32_e32 v160, v160, v161
	v_mov_b32_e32 v161, v160
	s_nop 1
	v_permlane32_swap_b32_e32 v160, v161
	s_and_saveexec_b64 s[22:23], s[8:9]
	v_lshl_add_u64 v[162:163], v[212:213], 2, s[52:53]
	v_add_f32_e32 v160, v160, v161
	global_atomic_add_f32 v[162:163], v160, off
	s_or_b64 exec, exec, s[22:23]
	s_branch .LBB0_1615

.LBB0_1785:
	ds_read_b128 v[144:147], v148
	ds_read_b128 v[152:155], v148 offset:1024
	ds_read_b128 v[156:159], v148 offset:2048
	ds_read_b128 v[160:163], v148 offset:3072
	s_add_u32 s58, s56, 0x100
	s_addc_u32 s59, s57, 0
	s_cmpk_eq_i32 s67, 0x7c
	s_cselect_b32 s63, s19, s59
	s_cselect_b32 s62, s53, s58
	s_cselect_b32 s61, s15, s66
	s_cselect_b32 s60, s64, s65
	v_lshl_add_u64 v[196:197], s[56:57], 0, v[134:135]
	s_add_i32 m0, s6, 0xc000
	ds_read_b128 v[164:167], v149
	ds_read_b128 v[168:171], v149 offset:1024
	ds_read_b128 v[172:175], v149 offset:2048
	ds_read_b128 v[176:179], v149 offset:3072
	ds_read_b128 v[180:183], v149 offset:4096
	ds_read_b128 v[184:187], v149 offset:5120
	ds_read_b128 v[188:191], v149 offset:6144
	ds_read_b128 v[192:195], v149 offset:7168
	global_load_lds_dwordx4 v[196:197], off
	v_lshl_add_u64 v[196:197], s[56:57], 0, v[138:139]
	s_add_i32 m0, s6, 0xe000
	s_nop 0
	global_load_lds_dwordx4 v[196:197], off
	s_waitcnt lgkmcnt(8)
	s_barrier
	s_waitcnt lgkmcnt(0)
	s_setprio 1
	s_waitcnt lgkmcnt(0)
	v_mfma_f32_16x16x32_bf16 v[124:127], v[144:147], v[164:167], v[124:127]
	v_mfma_f32_16x16x32_bf16 v[120:123], v[156:159], v[164:167], v[120:123]
	v_mfma_f32_16x16x32_bf16 v[108:111], v[144:147], v[172:175], v[108:111]
	v_mfma_f32_16x16x32_bf16 v[104:107], v[156:159], v[172:175], v[104:107]
	v_mfma_f32_16x16x32_bf16 v[92:95], v[144:147], v[180:183], v[92:95]
	v_mfma_f32_16x16x32_bf16 v[88:91], v[156:159], v[180:183], v[88:91]
	v_mfma_f32_16x16x32_bf16 v[76:79], v[144:147], v[188:191], v[76:79]
	v_mfma_f32_16x16x32_bf16 v[72:75], v[156:159], v[188:191], v[72:75]
	v_mfma_f32_16x16x32_bf16 v[124:127], v[152:155], v[168:171], v[124:127]
	v_mfma_f32_16x16x32_bf16 v[120:123], v[160:163], v[168:171], v[120:123]
	v_mfma_f32_16x16x32_bf16 v[108:111], v[152:155], v[176:179], v[108:111]
	v_mfma_f32_16x16x32_bf16 v[104:107], v[160:163], v[176:179], v[104:107]
	v_mfma_f32_16x16x32_bf16 v[92:95], v[152:155], v[184:187], v[92:95]
	v_mfma_f32_16x16x32_bf16 v[88:91], v[160:163], v[184:187], v[88:91]
	v_mfma_f32_16x16x32_bf16 v[76:79], v[152:155], v[192:195], v[76:79]
	v_mfma_f32_16x16x32_bf16 v[72:75], v[160:163], v[192:195], v[72:75]
	s_setprio 0
	s_barrier
	s_add_i32 s56, s47, s5
	v_lshl_add_u64 v[212:213], s[60:61], 0, v[128:129]
	s_mov_b32 m0, s56
	ds_read_b128 v[196:199], v150
	ds_read_b128 v[200:203], v150 offset:1024
	ds_read_b128 v[204:207], v150 offset:2048
	ds_read_b128 v[208:211], v150 offset:3072
	global_load_lds_dwordx4 v[212:213], off
	v_lshl_add_u64 v[214:215], s[60:61], 0, v[130:131]
	s_add_i32 m0, s56, 0x2000
	s_nop 0
	global_load_lds_dwordx4 v[214:215], off
	s_barrier
	s_waitcnt lgkmcnt(0)
	s_setprio 1
	s_waitcnt lgkmcnt(0)
	v_mfma_f32_16x16x32_bf16 v[116:119], v[196:199], v[164:167], v[116:119]
	v_mfma_f32_16x16x32_bf16 v[112:115], v[204:207], v[164:167], v[112:115]
	v_mfma_f32_16x16x32_bf16 v[100:103], v[196:199], v[172:175], v[100:103]
	v_mfma_f32_16x16x32_bf16 v[96:99], v[204:207], v[172:175], v[96:99]
	v_mfma_f32_16x16x32_bf16 v[84:87], v[196:199], v[180:183], v[84:87]
	v_mfma_f32_16x16x32_bf16 v[80:83], v[204:207], v[180:183], v[80:83]
	v_mfma_f32_16x16x32_bf16 v[68:71], v[196:199], v[188:191], v[68:71]
	v_mfma_f32_16x16x32_bf16 v[64:67], v[204:207], v[188:191], v[64:67]
	v_mfma_f32_16x16x32_bf16 v[116:119], v[200:203], v[168:171], v[116:119]
	v_mfma_f32_16x16x32_bf16 v[112:115], v[208:211], v[168:171], v[112:115]
	v_mfma_f32_16x16x32_bf16 v[100:103], v[200:203], v[176:179], v[100:103]
	v_mfma_f32_16x16x32_bf16 v[96:99], v[208:211], v[176:179], v[96:99]
	v_mfma_f32_16x16x32_bf16 v[84:87], v[200:203], v[184:187], v[84:87]
	v_mfma_f32_16x16x32_bf16 v[80:83], v[208:211], v[184:187], v[80:83]
	v_mfma_f32_16x16x32_bf16 v[68:71], v[200:203], v[192:195], v[68:71]
	v_mfma_f32_16x16x32_bf16 v[64:67], v[208:211], v[192:195], v[64:67]
	s_setprio 0
	s_mov_b32 m0, s6
	v_lshl_add_u64 v[216:217], s[62:63], 0, v[128:129]
	s_barrier
	ds_read_b128 v[164:167], v149 offset:16384
	ds_read_b128 v[168:171], v149 offset:17408
	ds_read_b128 v[172:175], v149 offset:18432
	ds_read_b128 v[176:179], v149 offset:19456
	ds_read_b128 v[180:183], v149 offset:20480
	ds_read_b128 v[184:187], v149 offset:21504
	ds_read_b128 v[188:191], v149 offset:22528
	ds_read_b128 v[192:195], v149 offset:23552
	global_load_lds_dwordx4 v[216:217], off
	v_lshl_add_u64 v[218:219], s[62:63], 0, v[130:131]
	s_mov_b32 m0, s7
	s_nop 0
	global_load_lds_dwordx4 v[218:219], off
	s_barrier
	s_waitcnt lgkmcnt(0)
	s_setprio 1
	s_waitcnt lgkmcnt(0)
	v_mfma_f32_16x16x32_bf16 v[60:63], v[144:147], v[164:167], v[60:63]
	v_mfma_f32_16x16x32_bf16 v[56:59], v[156:159], v[164:167], v[56:59]
	v_mfma_f32_16x16x32_bf16 v[44:47], v[144:147], v[172:175], v[44:47]
	v_mfma_f32_16x16x32_bf16 v[40:43], v[156:159], v[172:175], v[40:43]
	v_mfma_f32_16x16x32_bf16 v[28:31], v[144:147], v[180:183], v[28:31]
	v_mfma_f32_16x16x32_bf16 v[24:27], v[156:159], v[180:183], v[24:27]
	v_mfma_f32_16x16x32_bf16 v[12:15], v[144:147], v[188:191], v[12:15]
	v_mfma_f32_16x16x32_bf16 v[8:11], v[156:159], v[188:191], v[8:11]
	v_mfma_f32_16x16x32_bf16 v[60:63], v[152:155], v[168:171], v[60:63]
	v_mfma_f32_16x16x32_bf16 v[56:59], v[160:163], v[168:171], v[56:59]
	v_mfma_f32_16x16x32_bf16 v[44:47], v[152:155], v[176:179], v[44:47]
	v_mfma_f32_16x16x32_bf16 v[40:43], v[160:163], v[176:179], v[40:43]
	v_mfma_f32_16x16x32_bf16 v[28:31], v[152:155], v[184:187], v[28:31]
	v_mfma_f32_16x16x32_bf16 v[24:27], v[160:163], v[184:187], v[24:27]
	v_mfma_f32_16x16x32_bf16 v[12:15], v[152:155], v[192:195], v[12:15]
	v_mfma_f32_16x16x32_bf16 v[8:11], v[160:163], v[192:195], v[8:11]
	s_setprio 0
	s_barrier
	s_add_u32 s56, s60, 0x200000
	s_addc_u32 s57, s61, 0
	s_add_i32 s68, s55, s5
	v_lshl_add_u64 v[144:145], s[56:57], 0, v[128:129]
	s_mov_b32 m0, s68
	s_nop 0
	global_load_lds_dwordx4 v[144:145], off
	v_lshl_add_u64 v[144:145], s[56:57], 0, v[130:131]
	s_add_i32 m0, s68, 0x2000
	s_nop 0
	global_load_lds_dwordx4 v[144:145], off
	s_waitcnt vmcnt(6)
	s_barrier
	s_setprio 1
	v_mfma_f32_16x16x32_bf16 v[52:55], v[196:199], v[164:167], v[52:55]
	v_mfma_f32_16x16x32_bf16 v[48:51], v[204:207], v[164:167], v[48:51]
	v_mfma_f32_16x16x32_bf16 v[36:39], v[196:199], v[172:175], v[36:39]
	v_mfma_f32_16x16x32_bf16 v[32:35], v[204:207], v[172:175], v[32:35]
	v_mfma_f32_16x16x32_bf16 v[20:23], v[196:199], v[180:183], v[20:23]
	v_mfma_f32_16x16x32_bf16 v[16:19], v[204:207], v[180:183], v[16:19]
	v_mfma_f32_16x16x32_bf16 v[4:7], v[196:199], v[188:191], v[4:7]
	v_mfma_f32_16x16x32_bf16 v[0:3], v[204:207], v[188:191], v[0:3]
	v_mfma_f32_16x16x32_bf16 v[52:55], v[200:203], v[168:171], v[52:55]
	v_mfma_f32_16x16x32_bf16 v[48:51], v[208:211], v[168:171], v[48:51]
	v_mfma_f32_16x16x32_bf16 v[36:39], v[200:203], v[176:179], v[36:39]
	v_mfma_f32_16x16x32_bf16 v[32:35], v[208:211], v[176:179], v[32:35]
	v_mfma_f32_16x16x32_bf16 v[20:23], v[200:203], v[184:187], v[20:23]
	v_mfma_f32_16x16x32_bf16 v[16:19], v[208:211], v[184:187], v[16:19]
	v_mfma_f32_16x16x32_bf16 v[4:7], v[200:203], v[192:195], v[4:7]
	v_mfma_f32_16x16x32_bf16 v[0:3], v[208:211], v[192:195], v[0:3]
	s_setprio 0
	s_add_i32 s68, 16, 0x18000
	v_add_u32_e32 v151, s68, v137
	s_barrier
	ds_read_b128 v[144:147], v151
	ds_read_b128 v[152:155], v151 offset:1024
	ds_read_b128 v[156:159], v151 offset:2048
	ds_read_b128 v[160:163], v151 offset:3072
	s_add_u32 s56, s62, 0x200000
	s_addc_u32 s57, s63, 0
	s_mov_b32 m0, s26
	v_lshl_add_u64 v[196:197], s[56:57], 0, v[128:129]
	ds_read_b128 v[164:167], v149 offset:32768
	ds_read_b128 v[168:171], v149 offset:33792
	ds_read_b128 v[172:175], v149 offset:34816
	ds_read_b128 v[176:179], v149 offset:35840
	ds_read_b128 v[180:183], v149 offset:36864
	ds_read_b128 v[184:187], v149 offset:37888
	ds_read_b128 v[188:191], v149 offset:38912
	ds_read_b128 v[192:195], v149 offset:39936
	global_load_lds_dwordx4 v[196:197], off
	v_lshl_add_u64 v[196:197], s[56:57], 0, v[130:131]
	s_mov_b32 m0, s27
	s_nop 0
	global_load_lds_dwordx4 v[196:197], off
	s_waitcnt lgkmcnt(8)
	s_barrier
	s_waitcnt lgkmcnt(0)
	s_setprio 1
	s_waitcnt lgkmcnt(0)
	v_mfma_f32_16x16x32_bf16 v[124:127], v[144:147], v[164:167], v[124:127]
	v_mfma_f32_16x16x32_bf16 v[120:123], v[156:159], v[164:167], v[120:123]
	v_mfma_f32_16x16x32_bf16 v[108:111], v[144:147], v[172:175], v[108:111]
	v_mfma_f32_16x16x32_bf16 v[104:107], v[156:159], v[172:175], v[104:107]
	v_mfma_f32_16x16x32_bf16 v[92:95], v[144:147], v[180:183], v[92:95]
	v_mfma_f32_16x16x32_bf16 v[88:91], v[156:159], v[180:183], v[88:91]
	v_mfma_f32_16x16x32_bf16 v[76:79], v[144:147], v[188:191], v[76:79]
	v_mfma_f32_16x16x32_bf16 v[72:75], v[156:159], v[188:191], v[72:75]
	v_mfma_f32_16x16x32_bf16 v[124:127], v[152:155], v[168:171], v[124:127]
	v_mfma_f32_16x16x32_bf16 v[120:123], v[160:163], v[168:171], v[120:123]
	v_mfma_f32_16x16x32_bf16 v[108:111], v[152:155], v[176:179], v[108:111]
	v_mfma_f32_16x16x32_bf16 v[104:107], v[160:163], v[176:179], v[104:107]
	v_mfma_f32_16x16x32_bf16 v[92:95], v[152:155], v[184:187], v[92:95]
	v_mfma_f32_16x16x32_bf16 v[88:91], v[160:163], v[184:187], v[88:91]
	v_mfma_f32_16x16x32_bf16 v[76:79], v[152:155], v[192:195], v[76:79]
	v_mfma_f32_16x16x32_bf16 v[72:75], v[160:163], v[192:195], v[72:75]
	s_setprio 0
	s_barrier
	s_add_i32 s62, 16, 0x1c000
	s_add_i32 s56, s68, s5
	v_add_u32_e32 v151, s62, v137
	v_lshl_add_u64 v[212:213], v[212:213], 0, s[12:13]
	s_mov_b32 m0, s56
	ds_read_b128 v[196:199], v151
	ds_read_b128 v[200:203], v151 offset:1024
	ds_read_b128 v[204:207], v151 offset:2048
	ds_read_b128 v[208:211], v151 offset:3072
	global_load_lds_dwordx4 v[212:213], off
	v_lshl_add_u64 v[212:213], v[214:215], 0, s[12:13]
	s_add_i32 m0, s56, 0x2000
	s_nop 0
	global_load_lds_dwordx4 v[212:213], off
	s_barrier
	s_waitcnt lgkmcnt(0)
	s_setprio 1
	s_waitcnt lgkmcnt(0)
	v_mfma_f32_16x16x32_bf16 v[116:119], v[196:199], v[164:167], v[116:119]
	v_mfma_f32_16x16x32_bf16 v[112:115], v[204:207], v[164:167], v[112:115]
	v_mfma_f32_16x16x32_bf16 v[100:103], v[196:199], v[172:175], v[100:103]
	v_mfma_f32_16x16x32_bf16 v[96:99], v[204:207], v[172:175], v[96:99]
	v_mfma_f32_16x16x32_bf16 v[84:87], v[196:199], v[180:183], v[84:87]
	v_mfma_f32_16x16x32_bf16 v[80:83], v[204:207], v[180:183], v[80:83]
	v_mfma_f32_16x16x32_bf16 v[68:71], v[196:199], v[188:191], v[68:71]
	v_mfma_f32_16x16x32_bf16 v[64:67], v[204:207], v[188:191], v[64:67]
	v_mfma_f32_16x16x32_bf16 v[116:119], v[200:203], v[168:171], v[116:119]
	v_mfma_f32_16x16x32_bf16 v[112:115], v[208:211], v[168:171], v[112:115]
	v_mfma_f32_16x16x32_bf16 v[100:103], v[200:203], v[176:179], v[100:103]
	v_mfma_f32_16x16x32_bf16 v[96:99], v[208:211], v[176:179], v[96:99]
	v_mfma_f32_16x16x32_bf16 v[84:87], v[200:203], v[184:187], v[84:87]
	v_mfma_f32_16x16x32_bf16 v[80:83], v[208:211], v[184:187], v[80:83]
	v_mfma_f32_16x16x32_bf16 v[68:71], v[200:203], v[192:195], v[68:71]
	v_mfma_f32_16x16x32_bf16 v[64:67], v[208:211], v[192:195], v[64:67]
	s_setprio 0
	s_mov_b32 m0, s39
	v_lshl_add_u64 v[212:213], v[216:217], 0, s[12:13]
	s_barrier
	ds_read_b128 v[164:167], v149 offset:49152
	ds_read_b128 v[168:171], v149 offset:50176
	ds_read_b128 v[172:175], v149 offset:51200
	ds_read_b128 v[176:179], v149 offset:52224
	ds_read_b128 v[180:183], v149 offset:53248
	ds_read_b128 v[184:187], v149 offset:54272
	ds_read_b128 v[188:191], v149 offset:55296
	ds_read_b128 v[192:195], v149 offset:56320
	global_load_lds_dwordx4 v[212:213], off
	v_lshl_add_u64 v[212:213], v[218:219], 0, s[12:13]
	s_mov_b32 m0, s44
	s_nop 0
	global_load_lds_dwordx4 v[212:213], off
	s_barrier
	s_waitcnt lgkmcnt(0)
	s_setprio 1
	s_waitcnt lgkmcnt(0)
	v_mfma_f32_16x16x32_bf16 v[60:63], v[144:147], v[164:167], v[60:63]
	v_mfma_f32_16x16x32_bf16 v[56:59], v[156:159], v[164:167], v[56:59]
	v_mfma_f32_16x16x32_bf16 v[44:47], v[144:147], v[172:175], v[44:47]
	v_mfma_f32_16x16x32_bf16 v[40:43], v[156:159], v[172:175], v[40:43]
	v_mfma_f32_16x16x32_bf16 v[28:31], v[144:147], v[180:183], v[28:31]
	v_mfma_f32_16x16x32_bf16 v[24:27], v[156:159], v[180:183], v[24:27]
	v_mfma_f32_16x16x32_bf16 v[12:15], v[144:147], v[188:191], v[12:15]
	v_mfma_f32_16x16x32_bf16 v[8:11], v[156:159], v[188:191], v[8:11]
	v_mfma_f32_16x16x32_bf16 v[60:63], v[152:155], v[168:171], v[60:63]
	v_mfma_f32_16x16x32_bf16 v[56:59], v[160:163], v[168:171], v[56:59]
	v_mfma_f32_16x16x32_bf16 v[44:47], v[152:155], v[176:179], v[44:47]
	v_mfma_f32_16x16x32_bf16 v[40:43], v[160:163], v[176:179], v[40:43]
	v_mfma_f32_16x16x32_bf16 v[28:31], v[152:155], v[184:187], v[28:31]
	v_mfma_f32_16x16x32_bf16 v[24:27], v[160:163], v[184:187], v[24:27]
	v_mfma_f32_16x16x32_bf16 v[12:15], v[152:155], v[192:195], v[12:15]
	v_mfma_f32_16x16x32_bf16 v[8:11], v[160:163], v[192:195], v[8:11]
	s_setprio 0
	s_barrier
	s_add_u32 s56, s60, 0x200080
	s_addc_u32 s57, s61, 0
	s_add_i32 s60, s62, s5
	v_lshl_add_u64 v[144:145], s[56:57], 0, v[128:129]
	s_mov_b32 m0, s60
	s_nop 0
	global_load_lds_dwordx4 v[144:145], off
	v_lshl_add_u64 v[144:145], s[56:57], 0, v[130:131]
	s_add_i32 m0, s60, 0x2000
	s_nop 0
	global_load_lds_dwordx4 v[144:145], off
	s_waitcnt vmcnt(6)
	s_barrier
	s_setprio 1
	v_mfma_f32_16x16x32_bf16 v[52:55], v[196:199], v[164:167], v[52:55]
	v_mfma_f32_16x16x32_bf16 v[48:51], v[204:207], v[164:167], v[48:51]
	v_mfma_f32_16x16x32_bf16 v[36:39], v[196:199], v[172:175], v[36:39]
	v_mfma_f32_16x16x32_bf16 v[32:35], v[204:207], v[172:175], v[32:35]
	v_mfma_f32_16x16x32_bf16 v[20:23], v[196:199], v[180:183], v[20:23]
	v_mfma_f32_16x16x32_bf16 v[16:19], v[204:207], v[180:183], v[16:19]
	v_mfma_f32_16x16x32_bf16 v[4:7], v[196:199], v[188:191], v[4:7]
	v_mfma_f32_16x16x32_bf16 v[0:3], v[204:207], v[188:191], v[0:3]
	v_mfma_f32_16x16x32_bf16 v[52:55], v[200:203], v[168:171], v[52:55]
	v_mfma_f32_16x16x32_bf16 v[48:51], v[208:211], v[168:171], v[48:51]
	v_mfma_f32_16x16x32_bf16 v[36:39], v[200:203], v[176:179], v[36:39]
	v_mfma_f32_16x16x32_bf16 v[32:35], v[208:211], v[176:179], v[32:35]
	v_mfma_f32_16x16x32_bf16 v[20:23], v[200:203], v[184:187], v[20:23]
	v_mfma_f32_16x16x32_bf16 v[16:19], v[208:211], v[184:187], v[16:19]
	v_mfma_f32_16x16x32_bf16 v[4:7], v[200:203], v[192:195], v[4:7]
	v_mfma_f32_16x16x32_bf16 v[0:3], v[208:211], v[192:195], v[0:3]
	s_setprio 0
	s_add_i32 s67, s67, 2
	s_add_u32 s65, s65, 0x100
	s_addc_u32 s66, s66, 0
	s_cmpk_gt_u32 s67, 0x7d
	s_mov_b64 s[56:57], s[58:59]
	s_barrier
	s_cbranch_scc0 .LBB0_1785
	v_lshl_add_u32 v146, s52, 8, v133
	s_lshl_b32 s15, s54, 8
	s_ashr_i32 s19, s15, 31
	v_ashrrev_i32_e32 v147, 31, v146
	v_mov_b32_e32 v145, s19
	v_or_b32_e32 v144, s15, v132
	v_mov_b32_e32 v212, v146
	v_mov_b32_e32 v213, v147
	v_lshlrev_b64 v[214:215], 11, v[212:213]
	v_lshl_add_u64 v[214:215], v[214:215], 0, v[144:145]
	v_lshl_add_u64 v[152:153], v[214:215], 2, s[28:29]
	global_load_dwordx4 v[164:167], v[152:153], off
	global_load_dwordx4 v[168:171], v[152:153], off offset:64
	global_load_dwordx4 v[172:175], v[152:153], off offset:512
	global_load_dwordx4 v[176:179], v[152:153], off offset:576
	v_add_u32_e32 v212, 0x10, v146
	v_mov_b32_e32 v213, v147
	v_lshlrev_b64 v[214:215], 11, v[212:213]
	v_lshl_add_u64 v[214:215], v[214:215], 0, v[144:145]
	v_lshl_add_u64 v[152:153], v[214:215], 2, s[28:29]
	global_load_dwordx4 v[180:183], v[152:153], off
	global_load_dwordx4 v[184:187], v[152:153], off offset:64
	global_load_dwordx4 v[188:191], v[152:153], off offset:512
	global_load_dwordx4 v[192:195], v[152:153], off offset:576
	v_add_u32_e32 v212, 0x20, v146
	v_mov_b32_e32 v213, v147
	v_lshlrev_b64 v[214:215], 11, v[212:213]
	v_lshl_add_u64 v[214:215], v[214:215], 0, v[144:145]
	v_lshl_add_u64 v[152:153], v[214:215], 2, s[28:29]
	global_load_dwordx4 v[196:199], v[152:153], off
	global_load_dwordx4 v[200:203], v[152:153], off offset:64
	global_load_dwordx4 v[204:207], v[152:153], off offset:512
	global_load_dwordx4 v[208:211], v[152:153], off offset:576
	s_waitcnt vmcnt(8)
	v_mov_b32_e32 v212, v146
	v_mov_b32_e32 v213, v147
	v_lshlrev_b64 v[214:215], 11, v[212:213]
	v_lshl_add_u64 v[214:215], v[214:215], 0, v[144:145]
	v_lshl_add_u64 v[154:155], v[214:215], 2, s[28:29]
	v_lshl_add_u64 v[156:157], v[214:215], 1, s[40:41]
	v_pk_add_f32 v[126:127], v[126:127], v[166:167]
	v_pk_add_f32 v[124:125], v[124:125], v[164:165]
	v_cvt_pk_bf16_f32 v159, v126, v127
	v_cvt_pk_bf16_f32 v158, v124, v125
	global_store_dwordx4 v[154:155], v[124:127], off
	global_store_dwordx2 v[156:157], v[158:159], off
	s_nop 0
	v_mul_f32_e32 v125, v125, v125
	v_mul_f32_e32 v127, v127, v127
	v_fmac_f32_e32 v125, v124, v124
	v_fmac_f32_e32 v127, v126, v126
	v_add_f32_e32 v160, v125, v127
	v_pk_add_f32 v[122:123], v[122:123], v[170:171]
	v_pk_add_f32 v[120:121], v[120:121], v[168:169]
	v_cvt_pk_bf16_f32 v159, v122, v123
	v_cvt_pk_bf16_f32 v158, v120, v121
	global_store_dwordx4 v[154:155], v[120:123], off offset:64
	global_store_dwordx2 v[156:157], v[158:159], off offset:32
	s_nop 0
	v_mul_f32_e32 v121, v121, v121
	v_mul_f32_e32 v123, v123, v123
	v_fmac_f32_e32 v121, v120, v120
	v_fmac_f32_e32 v123, v122, v122
	v_add_f32_e32 v120, v121, v123
	v_add_f32_e32 v160, v160, v120
	v_pk_add_f32 v[118:119], v[118:119], v[174:175]
	v_pk_add_f32 v[116:117], v[116:117], v[172:173]
	v_cvt_pk_bf16_f32 v159, v118, v119
	v_cvt_pk_bf16_f32 v158, v116, v117
	global_store_dwordx4 v[154:155], v[116:119], off offset:512
	global_store_dwordx2 v[156:157], v[158:159], off offset:256
	s_nop 0
	v_mul_f32_e32 v117, v117, v117
	v_mul_f32_e32 v119, v119, v119
	v_fmac_f32_e32 v117, v116, v116
	v_fmac_f32_e32 v119, v118, v118
	v_add_f32_e32 v116, v117, v119
	v_add_f32_e32 v160, v160, v116
	v_pk_add_f32 v[114:115], v[114:115], v[178:179]
	v_pk_add_f32 v[112:113], v[112:113], v[176:177]
	v_cvt_pk_bf16_f32 v159, v114, v115
	v_cvt_pk_bf16_f32 v158, v112, v113
	global_store_dwordx4 v[154:155], v[112:115], off offset:576
	global_store_dwordx2 v[156:157], v[158:159], off offset:288
	s_nop 0
	v_mul_f32_e32 v113, v113, v113
	v_mul_f32_e32 v115, v115, v115
	v_fmac_f32_e32 v113, v112, v112
	v_fmac_f32_e32 v115, v114, v114
	v_add_f32_e32 v112, v113, v115
	v_add_f32_e32 v160, v160, v112
	v_mov_b32_e32 v161, v160
	s_nop 1
	v_permlane16_swap_b32_e32 v160, v161
	v_add_f32_e32 v160, v160, v161
	v_mov_b32_e32 v161, v160
	s_nop 1
	v_permlane32_swap_b32_e32 v160, v161
	s_and_saveexec_b64 s[52:53], s[8:9]
	v_lshl_add_u64 v[162:163], v[212:213], 2, s[16:17]
	v_add_f32_e32 v160, v160, v161
	global_atomic_add_f32 v[162:163], v160, off
	s_or_b64 exec, exec, s[52:53]
	v_add_u32_e32 v212, 0x30, v146
	v_mov_b32_e32 v213, v147
	v_lshlrev_b64 v[214:215], 11, v[212:213]
	v_lshl_add_u64 v[214:215], v[214:215], 0, v[144:145]
	v_lshl_add_u64 v[152:153], v[214:215], 2, s[28:29]
	global_load_dwordx4 v[164:167], v[152:153], off
	global_load_dwordx4 v[168:171], v[152:153], off offset:64
	global_load_dwordx4 v[172:175], v[152:153], off offset:512
	global_load_dwordx4 v[176:179], v[152:153], off offset:576
	s_waitcnt vmcnt(17)
	v_add_u32_e32 v212, 0x10, v146
	v_mov_b32_e32 v213, v147
	v_lshlrev_b64 v[214:215], 11, v[212:213]
	v_lshl_add_u64 v[214:215], v[214:215], 0, v[144:145]
	v_lshl_add_u64 v[154:155], v[214:215], 2, s[28:29]
	v_lshl_add_u64 v[156:157], v[214:215], 1, s[40:41]
	v_pk_add_f32 v[110:111], v[110:111], v[182:183]
	v_pk_add_f32 v[108:109], v[108:109], v[180:181]
	v_cvt_pk_bf16_f32 v159, v110, v111
	v_cvt_pk_bf16_f32 v158, v108, v109
	global_store_dwordx4 v[154:155], v[108:111], off
	global_store_dwordx2 v[156:157], v[158:159], off
	s_nop 0
	v_mul_f32_e32 v109, v109, v109
	v_mul_f32_e32 v111, v111, v111
	v_fmac_f32_e32 v109, v108, v108
	v_fmac_f32_e32 v111, v110, v110
	v_add_f32_e32 v160, v109, v111
	v_pk_add_f32 v[106:107], v[106:107], v[186:187]
	v_pk_add_f32 v[104:105], v[104:105], v[184:185]
	v_cvt_pk_bf16_f32 v159, v106, v107
	v_cvt_pk_bf16_f32 v158, v104, v105
	global_store_dwordx4 v[154:155], v[104:107], off offset:64
	global_store_dwordx2 v[156:157], v[158:159], off offset:32
	s_nop 0
	v_mul_f32_e32 v105, v105, v105
	v_mul_f32_e32 v107, v107, v107
	v_fmac_f32_e32 v105, v104, v104
	v_fmac_f32_e32 v107, v106, v106
	v_add_f32_e32 v104, v105, v107
	v_add_f32_e32 v160, v160, v104
	v_pk_add_f32 v[102:103], v[102:103], v[190:191]
	v_pk_add_f32 v[100:101], v[100:101], v[188:189]
	v_cvt_pk_bf16_f32 v159, v102, v103
	v_cvt_pk_bf16_f32 v158, v100, v101
	global_store_dwordx4 v[154:155], v[100:103], off offset:512
	global_store_dwordx2 v[156:157], v[158:159], off offset:256
	s_nop 0
	v_mul_f32_e32 v101, v101, v101
	v_mul_f32_e32 v103, v103, v103
	v_fmac_f32_e32 v101, v100, v100
	v_fmac_f32_e32 v103, v102, v102
	v_add_f32_e32 v100, v101, v103
	v_add_f32_e32 v160, v160, v100
	v_pk_add_f32 v[98:99], v[98:99], v[194:195]
	v_pk_add_f32 v[96:97], v[96:97], v[192:193]
	v_cvt_pk_bf16_f32 v159, v98, v99
	v_cvt_pk_bf16_f32 v158, v96, v97
	global_store_dwordx4 v[154:155], v[96:99], off offset:576
	global_store_dwordx2 v[156:157], v[158:159], off offset:288
	s_nop 0
	v_mul_f32_e32 v97, v97, v97
	v_mul_f32_e32 v99, v99, v99
	v_fmac_f32_e32 v97, v96, v96
	v_fmac_f32_e32 v99, v98, v98
	v_add_f32_e32 v96, v97, v99
	v_add_f32_e32 v160, v160, v96
	v_mov_b32_e32 v161, v160
	s_nop 1
	v_permlane16_swap_b32_e32 v160, v161
	v_add_f32_e32 v160, v160, v161
	v_mov_b32_e32 v161, v160
	s_nop 1
	v_permlane32_swap_b32_e32 v160, v161
	s_and_saveexec_b64 s[52:53], s[8:9]
	v_lshl_add_u64 v[162:163], v[212:213], 2, s[16:17]
	v_add_f32_e32 v160, v160, v161
	global_atomic_add_f32 v[162:163], v160, off
	s_or_b64 exec, exec, s[52:53]
	v_add_u32_e32 v212, 0x80, v146
	v_mov_b32_e32 v213, v147
	v_lshlrev_b64 v[214:215], 11, v[212:213]
	v_lshl_add_u64 v[214:215], v[214:215], 0, v[144:145]
	v_lshl_add_u64 v[152:153], v[214:215], 2, s[28:29]
	global_load_dwordx4 v[180:183], v[152:153], off
	global_load_dwordx4 v[184:187], v[152:153], off offset:64
	global_load_dwordx4 v[188:191], v[152:153], off offset:512
	global_load_dwordx4 v[192:195], v[152:153], off offset:576
	s_waitcnt vmcnt(26)
	v_add_u32_e32 v212, 0x20, v146
	v_mov_b32_e32 v213, v147
	v_lshlrev_b64 v[214:215], 11, v[212:213]
	v_lshl_add_u64 v[214:215], v[214:215], 0, v[144:145]
	v_lshl_add_u64 v[154:155], v[214:215], 2, s[28:29]
	v_lshl_add_u64 v[156:157], v[214:215], 1, s[40:41]
	v_pk_add_f32 v[94:95], v[94:95], v[198:199]
	v_pk_add_f32 v[92:93], v[92:93], v[196:197]
	v_cvt_pk_bf16_f32 v159, v94, v95
	v_cvt_pk_bf16_f32 v158, v92, v93
	global_store_dwordx4 v[154:155], v[92:95], off
	global_store_dwordx2 v[156:157], v[158:159], off
	s_nop 0
	v_mul_f32_e32 v93, v93, v93
	v_mul_f32_e32 v95, v95, v95
	v_fmac_f32_e32 v93, v92, v92
	v_fmac_f32_e32 v95, v94, v94
	v_add_f32_e32 v160, v93, v95
	v_pk_add_f32 v[90:91], v[90:91], v[202:203]
	v_pk_add_f32 v[88:89], v[88:89], v[200:201]
	v_cvt_pk_bf16_f32 v159, v90, v91
	v_cvt_pk_bf16_f32 v158, v88, v89
	global_store_dwordx4 v[154:155], v[88:91], off offset:64
	global_store_dwordx2 v[156:157], v[158:159], off offset:32
	s_nop 0
	v_mul_f32_e32 v89, v89, v89
	v_mul_f32_e32 v91, v91, v91
	v_fmac_f32_e32 v89, v88, v88
	v_fmac_f32_e32 v91, v90, v90
	v_add_f32_e32 v88, v89, v91
	v_add_f32_e32 v160, v160, v88
	v_pk_add_f32 v[86:87], v[86:87], v[206:207]
	v_pk_add_f32 v[84:85], v[84:85], v[204:205]
	v_cvt_pk_bf16_f32 v159, v86, v87
	v_cvt_pk_bf16_f32 v158, v84, v85
	global_store_dwordx4 v[154:155], v[84:87], off offset:512
	global_store_dwordx2 v[156:157], v[158:159], off offset:256
	s_nop 0
	v_mul_f32_e32 v85, v85, v85
	v_mul_f32_e32 v87, v87, v87
	v_fmac_f32_e32 v85, v84, v84
	v_fmac_f32_e32 v87, v86, v86
	v_add_f32_e32 v84, v85, v87
	v_add_f32_e32 v160, v160, v84
	v_pk_add_f32 v[82:83], v[82:83], v[210:211]
	v_pk_add_f32 v[80:81], v[80:81], v[208:209]
	v_cvt_pk_bf16_f32 v159, v82, v83
	v_cvt_pk_bf16_f32 v158, v80, v81
	global_store_dwordx4 v[154:155], v[80:83], off offset:576
	global_store_dwordx2 v[156:157], v[158:159], off offset:288
	s_nop 0
	v_mul_f32_e32 v81, v81, v81
	v_mul_f32_e32 v83, v83, v83
	v_fmac_f32_e32 v81, v80, v80
	v_fmac_f32_e32 v83, v82, v82
	v_add_f32_e32 v80, v81, v83
	v_add_f32_e32 v160, v160, v80
	v_mov_b32_e32 v161, v160
	s_nop 1
	v_permlane16_swap_b32_e32 v160, v161
	v_add_f32_e32 v160, v160, v161
	v_mov_b32_e32 v161, v160
	s_nop 1
	v_permlane32_swap_b32_e32 v160, v161
	s_and_saveexec_b64 s[52:53], s[8:9]
	v_lshl_add_u64 v[162:163], v[212:213], 2, s[16:17]
	v_add_f32_e32 v160, v160, v161
	global_atomic_add_f32 v[162:163], v160, off
	s_or_b64 exec, exec, s[52:53]
	v_add_u32_e32 v212, 0x90, v146
	v_mov_b32_e32 v213, v147
	v_lshlrev_b64 v[214:215], 11, v[212:213]
	v_lshl_add_u64 v[214:215], v[214:215], 0, v[144:145]
	v_lshl_add_u64 v[152:153], v[214:215], 2, s[28:29]
	global_load_dwordx4 v[196:199], v[152:153], off
	global_load_dwordx4 v[200:203], v[152:153], off offset:64
	global_load_dwordx4 v[204:207], v[152:153], off offset:512
	global_load_dwordx4 v[208:211], v[152:153], off offset:576
	s_waitcnt vmcnt(26)
	v_add_u32_e32 v212, 0x30, v146
	v_mov_b32_e32 v213, v147
	v_lshlrev_b64 v[214:215], 11, v[212:213]
	v_lshl_add_u64 v[214:215], v[214:215], 0, v[144:145]
	v_lshl_add_u64 v[154:155], v[214:215], 2, s[28:29]
	v_lshl_add_u64 v[156:157], v[214:215], 1, s[40:41]
	v_pk_add_f32 v[78:79], v[78:79], v[166:167]
	v_pk_add_f32 v[76:77], v[76:77], v[164:165]
	v_cvt_pk_bf16_f32 v159, v78, v79
	v_cvt_pk_bf16_f32 v158, v76, v77
	global_store_dwordx4 v[154:155], v[76:79], off
	global_store_dwordx2 v[156:157], v[158:159], off
	s_nop 0
	v_mul_f32_e32 v77, v77, v77
	v_mul_f32_e32 v79, v79, v79
	v_fmac_f32_e32 v77, v76, v76
	v_fmac_f32_e32 v79, v78, v78
	v_add_f32_e32 v160, v77, v79
	v_pk_add_f32 v[74:75], v[74:75], v[170:171]
	v_pk_add_f32 v[72:73], v[72:73], v[168:169]
	v_cvt_pk_bf16_f32 v159, v74, v75
	v_cvt_pk_bf16_f32 v158, v72, v73
	global_store_dwordx4 v[154:155], v[72:75], off offset:64
	global_store_dwordx2 v[156:157], v[158:159], off offset:32
	s_nop 0
	v_mul_f32_e32 v73, v73, v73
	v_mul_f32_e32 v75, v75, v75
	v_fmac_f32_e32 v73, v72, v72
	v_fmac_f32_e32 v75, v74, v74
	v_add_f32_e32 v72, v73, v75
	v_add_f32_e32 v160, v160, v72
	v_pk_add_f32 v[70:71], v[70:71], v[174:175]
	v_pk_add_f32 v[68:69], v[68:69], v[172:173]
	v_cvt_pk_bf16_f32 v159, v70, v71
	v_cvt_pk_bf16_f32 v158, v68, v69
	global_store_dwordx4 v[154:155], v[68:71], off offset:512
	global_store_dwordx2 v[156:157], v[158:159], off offset:256
	s_nop 0
	v_mul_f32_e32 v69, v69, v69
	v_mul_f32_e32 v71, v71, v71
	v_fmac_f32_e32 v69, v68, v68
	v_fmac_f32_e32 v71, v70, v70
	v_add_f32_e32 v68, v69, v71
	v_add_f32_e32 v160, v160, v68
	v_pk_add_f32 v[66:67], v[66:67], v[178:179]
	v_pk_add_f32 v[64:65], v[64:65], v[176:177]
	v_cvt_pk_bf16_f32 v159, v66, v67
	v_cvt_pk_bf16_f32 v158, v64, v65
	global_store_dwordx4 v[154:155], v[64:67], off offset:576
	global_store_dwordx2 v[156:157], v[158:159], off offset:288
	s_nop 0
	v_mul_f32_e32 v65, v65, v65
	v_mul_f32_e32 v67, v67, v67
	v_fmac_f32_e32 v65, v64, v64
	v_fmac_f32_e32 v67, v66, v66
	v_add_f32_e32 v64, v65, v67
	v_add_f32_e32 v160, v160, v64
	v_mov_b32_e32 v161, v160
	s_nop 1
	v_permlane16_swap_b32_e32 v160, v161
	v_add_f32_e32 v160, v160, v161
	v_mov_b32_e32 v161, v160
	s_nop 1
	v_permlane32_swap_b32_e32 v160, v161
	s_and_saveexec_b64 s[52:53], s[8:9]
	v_lshl_add_u64 v[162:163], v[212:213], 2, s[16:17]
	v_add_f32_e32 v160, v160, v161
	global_atomic_add_f32 v[162:163], v160, off
	s_or_b64 exec, exec, s[52:53]
	v_add_u32_e32 v212, 0xa0, v146
	v_mov_b32_e32 v213, v147
	v_lshlrev_b64 v[214:215], 11, v[212:213]
	v_lshl_add_u64 v[214:215], v[214:215], 0, v[144:145]
	v_lshl_add_u64 v[152:153], v[214:215], 2, s[28:29]
	global_load_dwordx4 v[164:167], v[152:153], off
	global_load_dwordx4 v[168:171], v[152:153], off offset:64
	global_load_dwordx4 v[172:175], v[152:153], off offset:512
	global_load_dwordx4 v[176:179], v[152:153], off offset:576
	s_waitcnt vmcnt(26)
	v_add_u32_e32 v212, 0x80, v146
	v_mov_b32_e32 v213, v147
	v_lshlrev_b64 v[214:215], 11, v[212:213]
	v_lshl_add_u64 v[214:215], v[214:215], 0, v[144:145]
	v_lshl_add_u64 v[154:155], v[214:215], 2, s[28:29]
	v_lshl_add_u64 v[156:157], v[214:215], 1, s[40:41]
	v_pk_add_f32 v[62:63], v[62:63], v[182:183]
	v_pk_add_f32 v[60:61], v[60:61], v[180:181]
	v_cvt_pk_bf16_f32 v159, v62, v63
	v_cvt_pk_bf16_f32 v158, v60, v61
	global_store_dwordx4 v[154:155], v[60:63], off
	global_store_dwordx2 v[156:157], v[158:159], off
	s_nop 0
	v_mul_f32_e32 v61, v61, v61
	v_mul_f32_e32 v63, v63, v63
	v_fmac_f32_e32 v61, v60, v60
	v_fmac_f32_e32 v63, v62, v62
	v_add_f32_e32 v160, v61, v63
	v_pk_add_f32 v[58:59], v[58:59], v[186:187]
	v_pk_add_f32 v[56:57], v[56:57], v[184:185]
	v_cvt_pk_bf16_f32 v159, v58, v59
	v_cvt_pk_bf16_f32 v158, v56, v57
	global_store_dwordx4 v[154:155], v[56:59], off offset:64
	global_store_dwordx2 v[156:157], v[158:159], off offset:32
	s_nop 0
	v_mul_f32_e32 v57, v57, v57
	v_mul_f32_e32 v59, v59, v59
	v_fmac_f32_e32 v57, v56, v56
	v_fmac_f32_e32 v59, v58, v58
	v_add_f32_e32 v56, v57, v59
	v_add_f32_e32 v160, v160, v56
	v_pk_add_f32 v[54:55], v[54:55], v[190:191]
	v_pk_add_f32 v[52:53], v[52:53], v[188:189]
	v_cvt_pk_bf16_f32 v159, v54, v55
	v_cvt_pk_bf16_f32 v158, v52, v53
	global_store_dwordx4 v[154:155], v[52:55], off offset:512
	global_store_dwordx2 v[156:157], v[158:159], off offset:256
	s_nop 0
	v_mul_f32_e32 v53, v53, v53
	v_mul_f32_e32 v55, v55, v55
	v_fmac_f32_e32 v53, v52, v52
	v_fmac_f32_e32 v55, v54, v54
	v_add_f32_e32 v52, v53, v55
	v_add_f32_e32 v160, v160, v52
	v_pk_add_f32 v[50:51], v[50:51], v[194:195]
	v_pk_add_f32 v[48:49], v[48:49], v[192:193]
	v_cvt_pk_bf16_f32 v159, v50, v51
	v_cvt_pk_bf16_f32 v158, v48, v49
	global_store_dwordx4 v[154:155], v[48:51], off offset:576
	global_store_dwordx2 v[156:157], v[158:159], off offset:288
	s_nop 0
	v_mul_f32_e32 v49, v49, v49
	v_mul_f32_e32 v51, v51, v51
	v_fmac_f32_e32 v49, v48, v48
	v_fmac_f32_e32 v51, v50, v50
	v_add_f32_e32 v48, v49, v51
	v_add_f32_e32 v160, v160, v48
	v_mov_b32_e32 v161, v160
	s_nop 1
	v_permlane16_swap_b32_e32 v160, v161
	v_add_f32_e32 v160, v160, v161
	v_mov_b32_e32 v161, v160
	s_nop 1
	v_permlane32_swap_b32_e32 v160, v161
	s_and_saveexec_b64 s[52:53], s[8:9]
	v_lshl_add_u64 v[162:163], v[212:213], 2, s[16:17]
	v_add_f32_e32 v160, v160, v161
	global_atomic_add_f32 v[162:163], v160, off
	s_or_b64 exec, exec, s[52:53]
	v_add_u32_e32 v212, 0xb0, v146
	v_mov_b32_e32 v213, v147
	v_lshlrev_b64 v[214:215], 11, v[212:213]
	v_lshl_add_u64 v[214:215], v[214:215], 0, v[144:145]
	v_lshl_add_u64 v[152:153], v[214:215], 2, s[28:29]
	global_load_dwordx4 v[180:183], v[152:153], off
	global_load_dwordx4 v[184:187], v[152:153], off offset:64
	global_load_dwordx4 v[188:191], v[152:153], off offset:512
	global_load_dwordx4 v[192:195], v[152:153], off offset:576
	s_waitcnt vmcnt(26)
	v_add_u32_e32 v212, 0x90, v146
	v_mov_b32_e32 v213, v147
	v_lshlrev_b64 v[214:215], 11, v[212:213]
	v_lshl_add_u64 v[214:215], v[214:215], 0, v[144:145]
	v_lshl_add_u64 v[154:155], v[214:215], 2, s[28:29]
	v_lshl_add_u64 v[156:157], v[214:215], 1, s[40:41]
	v_pk_add_f32 v[46:47], v[46:47], v[198:199]
	v_pk_add_f32 v[44:45], v[44:45], v[196:197]
	v_cvt_pk_bf16_f32 v159, v46, v47
	v_cvt_pk_bf16_f32 v158, v44, v45
	global_store_dwordx4 v[154:155], v[44:47], off
	global_store_dwordx2 v[156:157], v[158:159], off
	s_nop 0
	v_mul_f32_e32 v45, v45, v45
	v_mul_f32_e32 v47, v47, v47
	v_fmac_f32_e32 v45, v44, v44
	v_fmac_f32_e32 v47, v46, v46
	v_add_f32_e32 v160, v45, v47
	v_pk_add_f32 v[42:43], v[42:43], v[202:203]
	v_pk_add_f32 v[40:41], v[40:41], v[200:201]
	v_cvt_pk_bf16_f32 v159, v42, v43
	v_cvt_pk_bf16_f32 v158, v40, v41
	global_store_dwordx4 v[154:155], v[40:43], off offset:64
	global_store_dwordx2 v[156:157], v[158:159], off offset:32
	s_nop 0
	v_mul_f32_e32 v41, v41, v41
	v_mul_f32_e32 v43, v43, v43
	v_fmac_f32_e32 v41, v40, v40
	v_fmac_f32_e32 v43, v42, v42
	v_add_f32_e32 v40, v41, v43
	v_add_f32_e32 v160, v160, v40
	v_pk_add_f32 v[38:39], v[38:39], v[206:207]
	v_pk_add_f32 v[36:37], v[36:37], v[204:205]
	v_cvt_pk_bf16_f32 v159, v38, v39
	v_cvt_pk_bf16_f32 v158, v36, v37
	global_store_dwordx4 v[154:155], v[36:39], off offset:512
	global_store_dwordx2 v[156:157], v[158:159], off offset:256
	s_nop 0
	v_mul_f32_e32 v37, v37, v37
	v_mul_f32_e32 v39, v39, v39
	v_fmac_f32_e32 v37, v36, v36
	v_fmac_f32_e32 v39, v38, v38
	v_add_f32_e32 v36, v37, v39
	v_add_f32_e32 v160, v160, v36
	v_pk_add_f32 v[34:35], v[34:35], v[210:211]
	v_pk_add_f32 v[32:33], v[32:33], v[208:209]
	v_cvt_pk_bf16_f32 v159, v34, v35
	v_cvt_pk_bf16_f32 v158, v32, v33
	global_store_dwordx4 v[154:155], v[32:35], off offset:576
	global_store_dwordx2 v[156:157], v[158:159], off offset:288
	s_nop 0
	v_mul_f32_e32 v33, v33, v33
	v_mul_f32_e32 v35, v35, v35
	v_fmac_f32_e32 v33, v32, v32
	v_fmac_f32_e32 v35, v34, v34
	v_add_f32_e32 v32, v33, v35
	v_add_f32_e32 v160, v160, v32
	v_mov_b32_e32 v161, v160
	s_nop 1
	v_permlane16_swap_b32_e32 v160, v161
	v_add_f32_e32 v160, v160, v161
	v_mov_b32_e32 v161, v160
	s_nop 1
	v_permlane32_swap_b32_e32 v160, v161
	s_and_saveexec_b64 s[52:53], s[8:9]
	v_lshl_add_u64 v[162:163], v[212:213], 2, s[16:17]
	v_add_f32_e32 v160, v160, v161
	global_atomic_add_f32 v[162:163], v160, off
	s_or_b64 exec, exec, s[52:53]
	s_waitcnt vmcnt(22)
	v_add_u32_e32 v212, 0xa0, v146
	v_mov_b32_e32 v213, v147
	v_lshlrev_b64 v[214:215], 11, v[212:213]
	v_lshl_add_u64 v[214:215], v[214:215], 0, v[144:145]
	v_lshl_add_u64 v[154:155], v[214:215], 2, s[28:29]
	v_lshl_add_u64 v[156:157], v[214:215], 1, s[40:41]
	v_pk_add_f32 v[30:31], v[30:31], v[166:167]
	v_pk_add_f32 v[28:29], v[28:29], v[164:165]
	v_cvt_pk_bf16_f32 v159, v30, v31
	v_cvt_pk_bf16_f32 v158, v28, v29
	global_store_dwordx4 v[154:155], v[28:31], off
	global_store_dwordx2 v[156:157], v[158:159], off
	s_nop 0
	v_mul_f32_e32 v29, v29, v29
	v_mul_f32_e32 v31, v31, v31
	v_fmac_f32_e32 v29, v28, v28
	v_fmac_f32_e32 v31, v30, v30
	v_add_f32_e32 v160, v29, v31
	v_pk_add_f32 v[26:27], v[26:27], v[170:171]
	v_pk_add_f32 v[24:25], v[24:25], v[168:169]
	v_cvt_pk_bf16_f32 v159, v26, v27
	v_cvt_pk_bf16_f32 v158, v24, v25
	global_store_dwordx4 v[154:155], v[24:27], off offset:64
	global_store_dwordx2 v[156:157], v[158:159], off offset:32
	s_nop 0
	v_mul_f32_e32 v25, v25, v25
	v_mul_f32_e32 v27, v27, v27
	v_fmac_f32_e32 v25, v24, v24
	v_fmac_f32_e32 v27, v26, v26
	v_add_f32_e32 v24, v25, v27
	v_add_f32_e32 v160, v160, v24
	v_pk_add_f32 v[22:23], v[22:23], v[174:175]
	v_pk_add_f32 v[20:21], v[20:21], v[172:173]
	v_cvt_pk_bf16_f32 v159, v22, v23
	v_cvt_pk_bf16_f32 v158, v20, v21
	global_store_dwordx4 v[154:155], v[20:23], off offset:512
	global_store_dwordx2 v[156:157], v[158:159], off offset:256
	s_nop 0
	v_mul_f32_e32 v21, v21, v21
	v_mul_f32_e32 v23, v23, v23
	v_fmac_f32_e32 v21, v20, v20
	v_fmac_f32_e32 v23, v22, v22
	v_add_f32_e32 v20, v21, v23
	v_add_f32_e32 v160, v160, v20
	v_pk_add_f32 v[18:19], v[18:19], v[178:179]
	v_pk_add_f32 v[16:17], v[16:17], v[176:177]
	v_cvt_pk_bf16_f32 v159, v18, v19
	v_cvt_pk_bf16_f32 v158, v16, v17
	global_store_dwordx4 v[154:155], v[16:19], off offset:576
	global_store_dwordx2 v[156:157], v[158:159], off offset:288
	s_nop 0
	v_mul_f32_e32 v17, v17, v17
	v_mul_f32_e32 v19, v19, v19
	v_fmac_f32_e32 v17, v16, v16
	v_fmac_f32_e32 v19, v18, v18
	v_add_f32_e32 v16, v17, v19
	v_add_f32_e32 v160, v160, v16
	v_mov_b32_e32 v161, v160
	s_nop 1
	v_permlane16_swap_b32_e32 v160, v161
	v_add_f32_e32 v160, v160, v161
	v_mov_b32_e32 v161, v160
	s_nop 1
	v_permlane32_swap_b32_e32 v160, v161
	s_and_saveexec_b64 s[52:53], s[8:9]
	v_lshl_add_u64 v[162:163], v[212:213], 2, s[16:17]
	v_add_f32_e32 v160, v160, v161
	global_atomic_add_f32 v[162:163], v160, off
	s_or_b64 exec, exec, s[52:53]
	s_waitcnt vmcnt(18)
	v_add_u32_e32 v212, 0xb0, v146
	v_mov_b32_e32 v213, v147
	v_lshlrev_b64 v[214:215], 11, v[212:213]
	v_lshl_add_u64 v[214:215], v[214:215], 0, v[144:145]
	v_lshl_add_u64 v[154:155], v[214:215], 2, s[28:29]
	v_lshl_add_u64 v[156:157], v[214:215], 1, s[40:41]
	v_pk_add_f32 v[14:15], v[14:15], v[182:183]
	v_pk_add_f32 v[12:13], v[12:13], v[180:181]
	v_cvt_pk_bf16_f32 v159, v14, v15
	v_cvt_pk_bf16_f32 v158, v12, v13
	global_store_dwordx4 v[154:155], v[12:15], off
	global_store_dwordx2 v[156:157], v[158:159], off
	s_nop 0
	v_mul_f32_e32 v13, v13, v13
	v_mul_f32_e32 v15, v15, v15
	v_fmac_f32_e32 v13, v12, v12
	v_fmac_f32_e32 v15, v14, v14
	v_add_f32_e32 v160, v13, v15
	v_pk_add_f32 v[10:11], v[10:11], v[186:187]
	v_pk_add_f32 v[8:9], v[8:9], v[184:185]
	v_cvt_pk_bf16_f32 v159, v10, v11
	v_cvt_pk_bf16_f32 v158, v8, v9
	global_store_dwordx4 v[154:155], v[8:11], off offset:64
	global_store_dwordx2 v[156:157], v[158:159], off offset:32
	s_nop 0
	v_mul_f32_e32 v9, v9, v9
	v_mul_f32_e32 v11, v11, v11
	v_fmac_f32_e32 v9, v8, v8
	v_fmac_f32_e32 v11, v10, v10
	v_add_f32_e32 v8, v9, v11
	v_add_f32_e32 v160, v160, v8
	v_pk_add_f32 v[6:7], v[6:7], v[190:191]
	v_pk_add_f32 v[4:5], v[4:5], v[188:189]
	v_cvt_pk_bf16_f32 v159, v6, v7
	v_cvt_pk_bf16_f32 v158, v4, v5
	global_store_dwordx4 v[154:155], v[4:7], off offset:512
	global_store_dwordx2 v[156:157], v[158:159], off offset:256
	s_nop 0
	v_mul_f32_e32 v5, v5, v5
	v_mul_f32_e32 v7, v7, v7
	v_fmac_f32_e32 v5, v4, v4
	v_fmac_f32_e32 v7, v6, v6
	v_add_f32_e32 v4, v5, v7
	v_add_f32_e32 v160, v160, v4
	v_pk_add_f32 v[2:3], v[2:3], v[194:195]
	v_pk_add_f32 v[0:1], v[0:1], v[192:193]
	v_cvt_pk_bf16_f32 v159, v2, v3
	v_cvt_pk_bf16_f32 v158, v0, v1
	global_store_dwordx4 v[154:155], v[0:3], off offset:576
	global_store_dwordx2 v[156:157], v[158:159], off offset:288
	s_nop 0
	v_mul_f32_e32 v1, v1, v1
	v_mul_f32_e32 v3, v3, v3
	v_fmac_f32_e32 v1, v0, v0
	v_fmac_f32_e32 v3, v2, v2
	v_add_f32_e32 v0, v1, v3
	v_add_f32_e32 v160, v160, v0
	v_mov_b32_e32 v161, v160
	s_nop 1
	v_permlane16_swap_b32_e32 v160, v161
	v_add_f32_e32 v160, v160, v161
	v_mov_b32_e32 v161, v160
	s_nop 1
	v_permlane32_swap_b32_e32 v160, v161
	s_and_saveexec_b64 s[52:53], s[8:9]
	v_lshl_add_u64 v[162:163], v[212:213], 2, s[16:17]
	v_add_f32_e32 v160, v160, v161
	global_atomic_add_f32 v[162:163], v160, off
	s_or_b64 exec, exec, s[52:53]
	s_branch .LBB0_1777

	.amdhsa_kernel _Z8yoco_fwd4Args
		.amdhsa_group_segment_fixed_size 16
		.amdhsa_private_segment_fixed_size 0
		.amdhsa_kernarg_size 512
		.amdhsa_user_sgpr_count 2
		.amdhsa_user_sgpr_dispatch_ptr 0
		.amdhsa_user_sgpr_queue_ptr 0
		.amdhsa_user_sgpr_kernarg_segment_ptr 1
		.amdhsa_user_sgpr_dispatch_id 0
		.amdhsa_user_sgpr_kernarg_preload_length 0
		.amdhsa_user_sgpr_kernarg_preload_offset 0
		.amdhsa_user_sgpr_private_segment_size 0
		.amdhsa_uses_dynamic_stack 0
		.amdhsa_enable_private_segment 0
		.amdhsa_system_sgpr_workgroup_id_x 1
		.amdhsa_system_sgpr_workgroup_id_y 0
		.amdhsa_system_sgpr_workgroup_id_z 0
		.amdhsa_system_sgpr_workgroup_info 0
		.amdhsa_system_vgpr_workitem_id 2
		.amdhsa_next_free_vgpr 240
		.amdhsa_next_free_sgpr 100
		.amdhsa_accum_offset 240
		.amdhsa_reserve_vcc 1
		.amdhsa_float_round_mode_32 0
		.amdhsa_float_round_mode_16_64 0
		.amdhsa_float_denorm_mode_32 3
		.amdhsa_float_denorm_mode_16_64 3
		.amdhsa_dx10_clamp 1
		.amdhsa_ieee_mode 1
		.amdhsa_fp16_overflow 0
		.amdhsa_tg_split 0
		.amdhsa_exception_fp_ieee_invalid_op 0
		.amdhsa_exception_fp_denorm_src 0
		.amdhsa_exception_fp_ieee_div_zero 0
		.amdhsa_exception_fp_ieee_overflow 0
		.amdhsa_exception_fp_ieee_underflow 0
		.amdhsa_exception_fp_ieee_inexact 0
		.amdhsa_exception_int_div_zero 0
	.end_amdhsa_kernel

amdhsa.kernels:
  - .agpr_count:     0
    .args:
      - .offset:         0
        .size:           256
        .value_kind:     by_value
      - .offset:         256
        .size:           4
        .value_kind:     hidden_block_count_x
      - .offset:         260
        .size:           4
        .value_kind:     hidden_block_count_y
      - .offset:         264
        .size:           4
        .value_kind:     hidden_block_count_z
      - .offset:         268
        .size:           2
        .value_kind:     hidden_group_size_x
      - .offset:         270
        .size:           2
        .value_kind:     hidden_group_size_y
      - .offset:         272
        .size:           2
        .value_kind:     hidden_group_size_z
      - .offset:         274
        .size:           2
        .value_kind:     hidden_remainder_x
      - .offset:         276
        .size:           2
        .value_kind:     hidden_remainder_y
      - .offset:         278
        .size:           2
        .value_kind:     hidden_remainder_z
      - .offset:         296
        .size:           8
        .value_kind:     hidden_global_offset_x
      - .offset:         304
        .size:           8
        .value_kind:     hidden_global_offset_y
      - .offset:         312
        .size:           8
        .value_kind:     hidden_global_offset_z
      - .offset:         320
        .size:           2
        .value_kind:     hidden_grid_dims
      - .offset:         344
        .size:           8
        .value_kind:     hidden_multigrid_sync_arg
      - .offset:         376
        .size:           4
        .value_kind:     hidden_dynamic_lds_size
    .group_segment_fixed_size: 16
    .kernarg_segment_align: 8
    .kernarg_segment_size: 512
    .language:       OpenCL C
    .language_version:
      - 2
      - 0
    .max_flat_workgroup_size: 512
    .name:           _Z8yoco_fwd4Args
    .private_segment_fixed_size: 0
    .sgpr_count:     106
    .sgpr_spill_count: 21
    .symbol:         _Z8yoco_fwd4Args.kd
    .uniform_work_group_size: 1
    .uses_dynamic_stack: false
    .vgpr_count:     240
    .vgpr_spill_count: 0
    .wavefront_size: 64
